# one static s_setprio 1 for waves 0-3 (the leading half of the GEMM barrier pairing), per-segment setprio toggles removed
# baseline (speedup 1.0000x reference)
_Z9hymba_fwd6Params:
	s_load_dwordx2 s[42:43], s[0:1], 0x100
	v_and_b32_e32 v160, 0x3ff, v0
	v_readfirstlane_b32 s100, v160
	s_nop 3
	s_cmpk_ge_u32 s100, 0x100
	s_cbranch_scc1 .Lprio_skip
	s_setprio 1
.Lprio_skip:
	v_mov_b32_e32 v1, v160
	v_writelane_b32 v253, s2, 0
	s_mov_b64 s[40:41], s[0:1]
	s_nop 0
	v_cmp_gt_i32_e32 vcc, 4, v1
	s_and_saveexec_b64 s[0:1], vcc
	s_cbranch_execz .LBB0_2
	v_mov_b32_e32 v1, v160
	v_mov_b32_e32 v2, 0x100
	v_lshl_add_u32 v1, v1, 2, v2
	v_add_u32_e32 v1, 0x20000, v1
	v_mov_b32_e32 v2, 0
	ds_write_b32 v1, v2

.LBB0_175:
	s_cmp_eq_u32 s11, 12
	s_cselect_b64 vcc, -1, 0
	s_add_i32 s13, s33, 0x100
	s_add_i32 s14, s92, 0x100
	v_add_u32_e32 v166, s13, v157
	v_add_u32_e32 v186, s14, v157
	ds_read_b128 v[170:173], v166
	ds_read_b128 v[174:177], v166 offset:1024
	ds_read_b128 v[178:181], v166 offset:2048
	ds_read_b128 v[182:185], v166 offset:3072
	ds_read_b128 v[198:201], v186
	ds_read_b128 v[202:205], v186 offset:1024
	ds_read_b128 v[206:209], v186 offset:2048
	ds_read_b128 v[210:213], v186 offset:3072
	v_lshl_add_u64 v[164:165], v[154:155], 0, s[44:45]
	v_cndmask_b32_e32 v165, v165, v149, vcc
	v_cndmask_b32_e32 v164, v164, v148, vcc
	v_cndmask_b32_e32 v167, v153, v151, vcc
	v_cndmask_b32_e32 v166, v152, v150, vcc
	v_lshl_add_u64 v[186:187], v[154:155], 0, v[142:143]
	s_add_i32 m0, s20, 0xc000
	ds_read_b128 v[214:217], v159
	ds_read_b128 v[218:221], v159 offset:1024
	ds_read_b128 v[222:225], v159 offset:2048
	ds_read_b128 v[226:229], v159 offset:3072
	ds_read_b128 v[230:233], v159 offset:4096
	ds_read_b128 v[234:237], v159 offset:5120
	ds_read_b128 v[238:241], v159 offset:6144
	ds_read_b128 v[242:245], v159 offset:7168
	global_load_lds_dwordx4 v[186:187], off
	v_lshl_add_u64 v[186:187], v[154:155], 0, v[140:141]
	s_add_i32 m0, s20, 0xe000
	s_nop 0
	global_load_lds_dwordx4 v[186:187], off
	s_waitcnt vmcnt(8)
	s_waitcnt lgkmcnt(0)
	s_barrier
	s_waitcnt lgkmcnt(0)
	v_mfma_f32_16x16x32_bf16 v[124:127], v[170:173], v[214:217], v[124:127]
	v_mfma_f32_16x16x32_bf16 v[116:119], v[178:181], v[214:217], v[116:119]
	v_mfma_f32_16x16x32_bf16 v[108:111], v[170:173], v[222:225], v[108:111]
	v_mfma_f32_16x16x32_bf16 v[100:103], v[178:181], v[222:225], v[100:103]
	v_mfma_f32_16x16x32_bf16 v[92:95], v[170:173], v[230:233], v[92:95]
	v_mfma_f32_16x16x32_bf16 v[84:87], v[178:181], v[230:233], v[84:87]
	v_mfma_f32_16x16x32_bf16 v[76:79], v[170:173], v[238:241], v[76:79]
	v_mfma_f32_16x16x32_bf16 v[68:71], v[178:181], v[238:241], v[68:71]
	v_mfma_f32_16x16x32_bf16 v[124:127], v[174:177], v[218:221], v[124:127]
	v_mfma_f32_16x16x32_bf16 v[116:119], v[182:185], v[218:221], v[116:119]
	v_mfma_f32_16x16x32_bf16 v[108:111], v[174:177], v[226:229], v[108:111]
	v_mfma_f32_16x16x32_bf16 v[100:103], v[182:185], v[226:229], v[100:103]
	v_mfma_f32_16x16x32_bf16 v[92:95], v[174:177], v[234:237], v[92:95]
	v_mfma_f32_16x16x32_bf16 v[84:87], v[182:185], v[234:237], v[84:87]
	v_mfma_f32_16x16x32_bf16 v[76:79], v[174:177], v[242:245], v[76:79]
	v_mfma_f32_16x16x32_bf16 v[68:71], v[182:185], v[242:245], v[68:71]
	v_mfma_f32_16x16x32_bf16 v[120:123], v[198:201], v[214:217], v[120:123]
	v_mfma_f32_16x16x32_bf16 v[112:115], v[206:209], v[214:217], v[112:115]
	v_mfma_f32_16x16x32_bf16 v[104:107], v[198:201], v[222:225], v[104:107]
	v_mfma_f32_16x16x32_bf16 v[96:99], v[206:209], v[222:225], v[96:99]
	v_mfma_f32_16x16x32_bf16 v[88:91], v[198:201], v[230:233], v[88:91]
	v_mfma_f32_16x16x32_bf16 v[80:83], v[206:209], v[230:233], v[80:83]
	v_mfma_f32_16x16x32_bf16 v[72:75], v[198:201], v[238:241], v[72:75]
	v_mfma_f32_16x16x32_bf16 v[64:67], v[206:209], v[238:241], v[64:67]
	v_mfma_f32_16x16x32_bf16 v[120:123], v[202:205], v[218:221], v[120:123]
	v_mfma_f32_16x16x32_bf16 v[112:115], v[210:213], v[218:221], v[112:115]
	v_mfma_f32_16x16x32_bf16 v[104:107], v[202:205], v[226:229], v[104:107]
	v_mfma_f32_16x16x32_bf16 v[96:99], v[210:213], v[226:229], v[96:99]
	v_mfma_f32_16x16x32_bf16 v[88:91], v[202:205], v[234:237], v[88:91]
	v_mfma_f32_16x16x32_bf16 v[80:83], v[210:213], v[234:237], v[80:83]
	v_mfma_f32_16x16x32_bf16 v[72:75], v[202:205], v[242:245], v[72:75]
	v_mfma_f32_16x16x32_bf16 v[64:67], v[210:213], v[242:245], v[64:67]
	s_barrier
	s_add_i32 s13, s13, s19
	v_lshl_add_u64 v[186:187], v[166:167], 0, v[162:163]
	s_mov_b32 m0, s13
	ds_read_b128 v[214:217], v159 offset:16384
	ds_read_b128 v[218:221], v159 offset:17408
	ds_read_b128 v[222:225], v159 offset:18432
	ds_read_b128 v[226:229], v159 offset:19456
	ds_read_b128 v[230:233], v159 offset:20480
	ds_read_b128 v[234:237], v159 offset:21504
	ds_read_b128 v[238:241], v159 offset:22528
	ds_read_b128 v[242:245], v159 offset:23552
	global_load_lds_dwordx4 v[186:187], off
	v_lshl_add_u64 v[190:191], v[166:167], 0, v[136:137]
	s_add_i32 m0, s13, 0x2000
	v_lshl_add_u64 v[192:193], v[166:167], 0, s[78:79]
	s_add_i32 s13, s14, s19
	global_load_lds_dwordx4 v[190:191], off
	v_lshl_add_u64 v[246:247], v[192:193], 0, v[162:163]
	s_mov_b32 m0, s13
	v_lshl_add_u64 v[192:193], v[192:193], 0, v[136:137]
	global_load_lds_dwordx4 v[246:247], off
	s_add_i32 m0, s13, 0x2000
	v_lshl_add_u64 v[246:247], v[164:165], 0, v[134:135]
	global_load_lds_dwordx4 v[192:193], off
	v_lshl_add_u64 v[192:193], v[164:165], 0, v[132:133]
	s_mov_b32 m0, s20
	s_nop 0
	global_load_lds_dwordx4 v[192:193], off
	s_mov_b32 m0, s21
	s_nop 0
	global_load_lds_dwordx4 v[246:247], off
	s_waitcnt vmcnt(8)
	s_waitcnt lgkmcnt(0)
	s_barrier
	s_waitcnt lgkmcnt(0)
	v_mfma_f32_16x16x32_bf16 v[60:63], v[170:173], v[214:217], v[60:63]
	v_mfma_f32_16x16x32_bf16 v[52:55], v[178:181], v[214:217], v[52:55]
	v_mfma_f32_16x16x32_bf16 v[44:47], v[170:173], v[222:225], v[44:47]
	v_mfma_f32_16x16x32_bf16 v[36:39], v[178:181], v[222:225], v[36:39]
	v_mfma_f32_16x16x32_bf16 v[28:31], v[170:173], v[230:233], v[28:31]
	v_mfma_f32_16x16x32_bf16 v[20:23], v[178:181], v[230:233], v[20:23]
	v_mfma_f32_16x16x32_bf16 v[12:15], v[170:173], v[238:241], v[12:15]
	v_mfma_f32_16x16x32_bf16 v[4:7], v[178:181], v[238:241], v[4:7]
	v_mfma_f32_16x16x32_bf16 v[60:63], v[174:177], v[218:221], v[60:63]
	v_mfma_f32_16x16x32_bf16 v[52:55], v[182:185], v[218:221], v[52:55]
	v_mfma_f32_16x16x32_bf16 v[44:47], v[174:177], v[226:229], v[44:47]
	v_mfma_f32_16x16x32_bf16 v[36:39], v[182:185], v[226:229], v[36:39]
	v_mfma_f32_16x16x32_bf16 v[28:31], v[174:177], v[234:237], v[28:31]
	v_mfma_f32_16x16x32_bf16 v[20:23], v[182:185], v[234:237], v[20:23]
	v_mfma_f32_16x16x32_bf16 v[12:15], v[174:177], v[242:245], v[12:15]
	v_mfma_f32_16x16x32_bf16 v[4:7], v[182:185], v[242:245], v[4:7]
	v_mfma_f32_16x16x32_bf16 v[56:59], v[198:201], v[214:217], v[56:59]
	v_mfma_f32_16x16x32_bf16 v[48:51], v[206:209], v[214:217], v[48:51]
	v_mfma_f32_16x16x32_bf16 v[40:43], v[198:201], v[222:225], v[40:43]
	v_mfma_f32_16x16x32_bf16 v[32:35], v[206:209], v[222:225], v[32:35]
	v_mfma_f32_16x16x32_bf16 v[24:27], v[198:201], v[230:233], v[24:27]
	v_mfma_f32_16x16x32_bf16 v[16:19], v[206:209], v[230:233], v[16:19]
	v_mfma_f32_16x16x32_bf16 v[8:11], v[198:201], v[238:241], v[8:11]
	v_mfma_f32_16x16x32_bf16 v[0:3], v[206:209], v[238:241], v[0:3]
	v_mfma_f32_16x16x32_bf16 v[56:59], v[202:205], v[218:221], v[56:59]
	v_mfma_f32_16x16x32_bf16 v[48:51], v[210:213], v[218:221], v[48:51]
	v_mfma_f32_16x16x32_bf16 v[40:43], v[202:205], v[226:229], v[40:43]
	v_mfma_f32_16x16x32_bf16 v[32:35], v[210:213], v[226:229], v[32:35]
	v_mfma_f32_16x16x32_bf16 v[24:27], v[202:205], v[234:237], v[24:27]
	v_mfma_f32_16x16x32_bf16 v[16:19], v[210:213], v[234:237], v[16:19]
	v_mfma_f32_16x16x32_bf16 v[8:11], v[202:205], v[242:245], v[8:11]
	v_mfma_f32_16x16x32_bf16 v[0:3], v[210:213], v[242:245], v[0:3]
	s_barrier
	s_add_i32 s13, s93, 0x100
	s_add_i32 s14, s82, 0x100
	v_add_u32_e32 v182, s13, v157
	v_add_u32_e32 v210, s14, v157
	ds_read_b128 v[170:173], v182
	ds_read_b128 v[174:177], v182 offset:1024
	ds_read_b128 v[178:181], v182 offset:2048
	ds_read_b128 v[182:185], v182 offset:3072
	ds_read_b128 v[198:201], v210
	ds_read_b128 v[202:205], v210 offset:1024
	ds_read_b128 v[206:209], v210 offset:2048
	ds_read_b128 v[210:213], v210 offset:3072
	v_lshl_add_u64 v[164:165], v[164:165], 0, s[78:79]
	s_mov_b32 m0, s22
	v_lshl_add_u64 v[248:249], v[164:165], 0, v[132:133]
	ds_read_b128 v[214:217], v159 offset:32768
	ds_read_b128 v[218:221], v159 offset:33792
	ds_read_b128 v[222:225], v159 offset:34816
	ds_read_b128 v[226:229], v159 offset:35840
	ds_read_b128 v[230:233], v159 offset:36864
	ds_read_b128 v[234:237], v159 offset:37888
	ds_read_b128 v[238:241], v159 offset:38912
	ds_read_b128 v[242:245], v159 offset:39936
	global_load_lds_dwordx4 v[248:249], off
	v_lshl_add_u64 v[164:165], v[164:165], 0, v[134:135]
	s_mov_b32 m0, s23
	s_nop 0
	global_load_lds_dwordx4 v[164:165], off
	s_waitcnt vmcnt(8)
	s_waitcnt lgkmcnt(0)
	s_barrier
	s_waitcnt lgkmcnt(0)
	v_mfma_f32_16x16x32_bf16 v[124:127], v[170:173], v[214:217], v[124:127]
	v_mfma_f32_16x16x32_bf16 v[116:119], v[178:181], v[214:217], v[116:119]
	v_mfma_f32_16x16x32_bf16 v[108:111], v[170:173], v[222:225], v[108:111]
	v_mfma_f32_16x16x32_bf16 v[100:103], v[178:181], v[222:225], v[100:103]
	v_mfma_f32_16x16x32_bf16 v[92:95], v[170:173], v[230:233], v[92:95]
	v_mfma_f32_16x16x32_bf16 v[84:87], v[178:181], v[230:233], v[84:87]
	v_mfma_f32_16x16x32_bf16 v[76:79], v[170:173], v[238:241], v[76:79]
	v_mfma_f32_16x16x32_bf16 v[68:71], v[178:181], v[238:241], v[68:71]
	v_mfma_f32_16x16x32_bf16 v[124:127], v[174:177], v[218:221], v[124:127]
	v_mfma_f32_16x16x32_bf16 v[116:119], v[182:185], v[218:221], v[116:119]
	v_mfma_f32_16x16x32_bf16 v[108:111], v[174:177], v[226:229], v[108:111]
	v_mfma_f32_16x16x32_bf16 v[100:103], v[182:185], v[226:229], v[100:103]
	v_mfma_f32_16x16x32_bf16 v[92:95], v[174:177], v[234:237], v[92:95]
	v_mfma_f32_16x16x32_bf16 v[84:87], v[182:185], v[234:237], v[84:87]
	v_mfma_f32_16x16x32_bf16 v[76:79], v[174:177], v[242:245], v[76:79]
	v_mfma_f32_16x16x32_bf16 v[68:71], v[182:185], v[242:245], v[68:71]
	v_mfma_f32_16x16x32_bf16 v[120:123], v[198:201], v[214:217], v[120:123]
	v_mfma_f32_16x16x32_bf16 v[112:115], v[206:209], v[214:217], v[112:115]
	v_mfma_f32_16x16x32_bf16 v[104:107], v[198:201], v[222:225], v[104:107]
	v_mfma_f32_16x16x32_bf16 v[96:99], v[206:209], v[222:225], v[96:99]
	v_mfma_f32_16x16x32_bf16 v[88:91], v[198:201], v[230:233], v[88:91]
	v_mfma_f32_16x16x32_bf16 v[80:83], v[206:209], v[230:233], v[80:83]
	v_mfma_f32_16x16x32_bf16 v[72:75], v[198:201], v[238:241], v[72:75]
	v_mfma_f32_16x16x32_bf16 v[64:67], v[206:209], v[238:241], v[64:67]
	v_mfma_f32_16x16x32_bf16 v[120:123], v[202:205], v[218:221], v[120:123]
	v_mfma_f32_16x16x32_bf16 v[112:115], v[210:213], v[218:221], v[112:115]
	v_mfma_f32_16x16x32_bf16 v[104:107], v[202:205], v[226:229], v[104:107]
	v_mfma_f32_16x16x32_bf16 v[96:99], v[210:213], v[226:229], v[96:99]
	v_mfma_f32_16x16x32_bf16 v[88:91], v[202:205], v[234:237], v[88:91]
	v_mfma_f32_16x16x32_bf16 v[80:83], v[210:213], v[234:237], v[80:83]
	v_mfma_f32_16x16x32_bf16 v[72:75], v[202:205], v[242:245], v[72:75]
	v_mfma_f32_16x16x32_bf16 v[64:67], v[210:213], v[242:245], v[64:67]
	s_barrier
	s_add_i32 s13, s13, s19
	v_lshl_add_u64 v[164:165], v[186:187], 0, s[84:85]
	s_mov_b32 m0, s13
	ds_read_b128 v[214:217], v159 offset:49152
	ds_read_b128 v[218:221], v159 offset:50176
	ds_read_b128 v[222:225], v159 offset:51200
	ds_read_b128 v[226:229], v159 offset:52224
	ds_read_b128 v[230:233], v159 offset:53248
	ds_read_b128 v[234:237], v159 offset:54272
	ds_read_b128 v[238:241], v159 offset:55296
	ds_read_b128 v[242:245], v159 offset:56320
	global_load_lds_dwordx4 v[164:165], off
	v_lshl_add_u64 v[164:165], v[190:191], 0, s[84:85]
	s_add_i32 m0, s13, 0x2000
	s_add_i32 s13, s14, s19
	global_load_lds_dwordx4 v[164:165], off
	v_lshl_add_u64 v[164:165], v[166:167], 0, s[86:87]
	v_lshl_add_u64 v[166:167], v[164:165], 0, v[162:163]
	s_mov_b32 m0, s13
	v_lshl_add_u64 v[164:165], v[164:165], 0, v[136:137]
	global_load_lds_dwordx4 v[166:167], off
	s_add_i32 m0, s13, 0x2000
	s_nop 0
	global_load_lds_dwordx4 v[164:165], off
	v_lshl_add_u64 v[164:165], v[192:193], 0, s[84:85]
	s_mov_b32 m0, s24
	s_nop 0
	global_load_lds_dwordx4 v[164:165], off
	v_lshl_add_u64 v[164:165], v[246:247], 0, s[84:85]
	s_mov_b32 m0, s25
	s_nop 0
	global_load_lds_dwordx4 v[164:165], off
	s_waitcnt vmcnt(8)
	s_waitcnt lgkmcnt(0)
	s_barrier
	s_waitcnt lgkmcnt(0)
	v_mfma_f32_16x16x32_bf16 v[60:63], v[170:173], v[214:217], v[60:63]
	v_mfma_f32_16x16x32_bf16 v[52:55], v[178:181], v[214:217], v[52:55]
	v_mfma_f32_16x16x32_bf16 v[44:47], v[170:173], v[222:225], v[44:47]
	v_mfma_f32_16x16x32_bf16 v[36:39], v[178:181], v[222:225], v[36:39]
	v_mfma_f32_16x16x32_bf16 v[28:31], v[170:173], v[230:233], v[28:31]
	v_mfma_f32_16x16x32_bf16 v[20:23], v[178:181], v[230:233], v[20:23]
	v_mfma_f32_16x16x32_bf16 v[12:15], v[170:173], v[238:241], v[12:15]
	v_mfma_f32_16x16x32_bf16 v[4:7], v[178:181], v[238:241], v[4:7]
	v_mfma_f32_16x16x32_bf16 v[60:63], v[174:177], v[218:221], v[60:63]
	v_mfma_f32_16x16x32_bf16 v[52:55], v[182:185], v[218:221], v[52:55]
	v_mfma_f32_16x16x32_bf16 v[44:47], v[174:177], v[226:229], v[44:47]
	v_mfma_f32_16x16x32_bf16 v[36:39], v[182:185], v[226:229], v[36:39]
	v_mfma_f32_16x16x32_bf16 v[28:31], v[174:177], v[234:237], v[28:31]
	v_mfma_f32_16x16x32_bf16 v[20:23], v[182:185], v[234:237], v[20:23]
	v_mfma_f32_16x16x32_bf16 v[12:15], v[174:177], v[242:245], v[12:15]
	v_mfma_f32_16x16x32_bf16 v[4:7], v[182:185], v[242:245], v[4:7]
	v_mfma_f32_16x16x32_bf16 v[56:59], v[198:201], v[214:217], v[56:59]
	v_mfma_f32_16x16x32_bf16 v[48:51], v[206:209], v[214:217], v[48:51]
	v_mfma_f32_16x16x32_bf16 v[40:43], v[198:201], v[222:225], v[40:43]
	v_mfma_f32_16x16x32_bf16 v[32:35], v[206:209], v[222:225], v[32:35]
	v_mfma_f32_16x16x32_bf16 v[24:27], v[198:201], v[230:233], v[24:27]
	v_mfma_f32_16x16x32_bf16 v[16:19], v[206:209], v[230:233], v[16:19]
	v_mfma_f32_16x16x32_bf16 v[8:11], v[198:201], v[238:241], v[8:11]
	v_mfma_f32_16x16x32_bf16 v[0:3], v[206:209], v[238:241], v[0:3]
	v_mfma_f32_16x16x32_bf16 v[56:59], v[202:205], v[218:221], v[56:59]
	v_mfma_f32_16x16x32_bf16 v[48:51], v[210:213], v[218:221], v[48:51]
	v_mfma_f32_16x16x32_bf16 v[40:43], v[202:205], v[226:229], v[40:43]
	v_mfma_f32_16x16x32_bf16 v[32:35], v[210:213], v[226:229], v[32:35]
	v_mfma_f32_16x16x32_bf16 v[24:27], v[202:205], v[234:237], v[24:27]
	v_mfma_f32_16x16x32_bf16 v[16:19], v[210:213], v[234:237], v[16:19]
	v_mfma_f32_16x16x32_bf16 v[8:11], v[202:205], v[242:245], v[8:11]
	v_mfma_f32_16x16x32_bf16 v[0:3], v[210:213], v[242:245], v[0:3]
	s_barrier
	s_add_i32 s11, s11, 2
	v_lshl_add_u64 v[152:153], v[152:153], 0, s[0:1]
	s_cmp_gt_u32 s11, 13
	v_lshl_add_u64 v[154:155], v[154:155], 0, s[0:1]
	s_cbranch_scc0 .LBB0_175
	s_and_b64 vcc, exec, s[8:9]
	s_cbranch_vccz .LBB0_178
	s_barrier

.LBB0_264:
	s_cmp_eq_u32 s2, 40
	s_cselect_b64 vcc, -1, 0
	s_add_i32 s3, s33, 0x100
	v_add_u32_e32 v155, s3, v152
	s_add_i32 s6, s92, 0x100
	ds_read_b128 v[156:159], v155
	ds_read_b128 v[170:173], v155 offset:1024
	ds_read_b128 v[174:177], v155 offset:2048
	ds_read_b128 v[178:181], v155 offset:3072
	v_add_u32_e32 v155, s6, v152
	ds_read_b128 v[182:185], v155
	ds_read_b128 v[198:201], v155 offset:1024
	ds_read_b128 v[202:205], v155 offset:2048
	ds_read_b128 v[206:209], v155 offset:3072
	v_lshl_add_u64 v[148:149], v[146:147], 0, s[0:1]
	v_cndmask_b32_e32 v165, v149, v141, vcc
	v_cndmask_b32_e32 v164, v148, v140, vcc
	v_cndmask_b32_e32 v167, v145, v143, vcc
	v_cndmask_b32_e32 v166, v144, v142, vcc
	v_lshl_add_u64 v[186:187], v[146:147], 0, v[138:139]
	s_add_i32 m0, s18, 0xc000
	ds_read_b128 v[210:213], v154
	ds_read_b128 v[214:217], v154 offset:1024
	ds_read_b128 v[218:221], v154 offset:2048
	ds_read_b128 v[222:225], v154 offset:3072
	ds_read_b128 v[226:229], v154 offset:4096
	ds_read_b128 v[230:233], v154 offset:5120
	ds_read_b128 v[234:237], v154 offset:6144
	ds_read_b128 v[238:241], v154 offset:7168
	global_load_lds_dwordx4 v[186:187], off
	v_lshl_add_u64 v[146:147], v[146:147], 0, v[136:137]
	s_add_i32 m0, s18, 0xe000
	s_nop 0
	global_load_lds_dwordx4 v[146:147], off
	s_waitcnt vmcnt(8)
	s_waitcnt lgkmcnt(0)
	s_barrier
	s_waitcnt lgkmcnt(0)
	v_mfma_f32_16x16x32_bf16 v[124:127], v[156:159], v[210:213], v[124:127]
	v_mfma_f32_16x16x32_bf16 v[120:123], v[174:177], v[210:213], v[120:123]
	v_mfma_f32_16x16x32_bf16 v[108:111], v[156:159], v[218:221], v[108:111]
	v_mfma_f32_16x16x32_bf16 v[104:107], v[174:177], v[218:221], v[104:107]
	v_mfma_f32_16x16x32_bf16 v[92:95], v[156:159], v[226:229], v[92:95]
	v_mfma_f32_16x16x32_bf16 v[88:91], v[174:177], v[226:229], v[88:91]
	v_mfma_f32_16x16x32_bf16 v[76:79], v[156:159], v[234:237], v[76:79]
	v_mfma_f32_16x16x32_bf16 v[72:75], v[174:177], v[234:237], v[72:75]
	v_mfma_f32_16x16x32_bf16 v[124:127], v[170:173], v[214:217], v[124:127]
	v_mfma_f32_16x16x32_bf16 v[120:123], v[178:181], v[214:217], v[120:123]
	v_mfma_f32_16x16x32_bf16 v[108:111], v[170:173], v[222:225], v[108:111]
	v_mfma_f32_16x16x32_bf16 v[104:107], v[178:181], v[222:225], v[104:107]
	v_mfma_f32_16x16x32_bf16 v[92:95], v[170:173], v[230:233], v[92:95]
	v_mfma_f32_16x16x32_bf16 v[88:91], v[178:181], v[230:233], v[88:91]
	v_mfma_f32_16x16x32_bf16 v[76:79], v[170:173], v[238:241], v[76:79]
	v_mfma_f32_16x16x32_bf16 v[72:75], v[178:181], v[238:241], v[72:75]
	v_mfma_f32_16x16x32_bf16 v[116:119], v[182:185], v[210:213], v[116:119]
	v_mfma_f32_16x16x32_bf16 v[112:115], v[202:205], v[210:213], v[112:115]
	v_mfma_f32_16x16x32_bf16 v[100:103], v[182:185], v[218:221], v[100:103]
	v_mfma_f32_16x16x32_bf16 v[96:99], v[202:205], v[218:221], v[96:99]
	v_mfma_f32_16x16x32_bf16 v[84:87], v[182:185], v[226:229], v[84:87]
	v_mfma_f32_16x16x32_bf16 v[80:83], v[202:205], v[226:229], v[80:83]
	v_mfma_f32_16x16x32_bf16 v[68:71], v[182:185], v[234:237], v[68:71]
	v_mfma_f32_16x16x32_bf16 v[64:67], v[202:205], v[234:237], v[64:67]
	v_mfma_f32_16x16x32_bf16 v[116:119], v[198:201], v[214:217], v[116:119]
	v_mfma_f32_16x16x32_bf16 v[112:115], v[206:209], v[214:217], v[112:115]
	v_mfma_f32_16x16x32_bf16 v[100:103], v[198:201], v[222:225], v[100:103]
	v_mfma_f32_16x16x32_bf16 v[96:99], v[206:209], v[222:225], v[96:99]
	v_mfma_f32_16x16x32_bf16 v[84:87], v[198:201], v[230:233], v[84:87]
	v_mfma_f32_16x16x32_bf16 v[80:83], v[206:209], v[230:233], v[80:83]
	v_mfma_f32_16x16x32_bf16 v[68:71], v[198:201], v[238:241], v[68:71]
	v_mfma_f32_16x16x32_bf16 v[64:67], v[206:209], v[238:241], v[64:67]
	s_barrier
	s_add_i32 s3, s3, s17
	v_lshl_add_u64 v[146:147], v[166:167], 0, v[162:163]
	s_mov_b32 m0, s3
	ds_read_b128 v[210:213], v154 offset:16384
	ds_read_b128 v[214:217], v154 offset:17408
	ds_read_b128 v[218:221], v154 offset:18432
	ds_read_b128 v[222:225], v154 offset:19456
	ds_read_b128 v[226:229], v154 offset:20480
	ds_read_b128 v[230:233], v154 offset:21504
	ds_read_b128 v[234:237], v154 offset:22528
	ds_read_b128 v[238:241], v154 offset:23552
	global_load_lds_dwordx4 v[146:147], off
	v_lshl_add_u64 v[186:187], v[166:167], 0, v[134:135]
	s_add_i32 m0, s3, 0x2000
	v_lshl_add_u64 v[190:191], v[166:167], 0, s[44:45]
	s_add_i32 s3, s6, s17
	global_load_lds_dwordx4 v[186:187], off
	v_lshl_add_u64 v[192:193], v[190:191], 0, v[162:163]
	s_mov_b32 m0, s3
	v_lshl_add_u64 v[190:191], v[190:191], 0, v[134:135]
	global_load_lds_dwordx4 v[192:193], off
	s_add_i32 m0, s3, 0x2000
	v_lshl_add_u64 v[192:193], v[164:165], 0, v[134:135]
	global_load_lds_dwordx4 v[190:191], off
	v_lshl_add_u64 v[190:191], v[164:165], 0, v[162:163]
	s_mov_b32 m0, s18
	s_nop 0
	global_load_lds_dwordx4 v[190:191], off
	s_mov_b32 m0, s19
	s_nop 0
	global_load_lds_dwordx4 v[192:193], off
	s_waitcnt vmcnt(8)
	s_waitcnt lgkmcnt(0)
	s_barrier
	s_waitcnt lgkmcnt(0)
	v_mfma_f32_16x16x32_bf16 v[60:63], v[156:159], v[210:213], v[60:63]
	v_mfma_f32_16x16x32_bf16 v[56:59], v[174:177], v[210:213], v[56:59]
	v_mfma_f32_16x16x32_bf16 v[44:47], v[156:159], v[218:221], v[44:47]
	v_mfma_f32_16x16x32_bf16 v[40:43], v[174:177], v[218:221], v[40:43]
	v_mfma_f32_16x16x32_bf16 v[28:31], v[156:159], v[226:229], v[28:31]
	v_mfma_f32_16x16x32_bf16 v[24:27], v[174:177], v[226:229], v[24:27]
	v_mfma_f32_16x16x32_bf16 v[12:15], v[156:159], v[234:237], v[12:15]
	v_mfma_f32_16x16x32_bf16 v[8:11], v[174:177], v[234:237], v[8:11]
	v_mfma_f32_16x16x32_bf16 v[60:63], v[170:173], v[214:217], v[60:63]
	v_mfma_f32_16x16x32_bf16 v[56:59], v[178:181], v[214:217], v[56:59]
	v_mfma_f32_16x16x32_bf16 v[44:47], v[170:173], v[222:225], v[44:47]
	v_mfma_f32_16x16x32_bf16 v[40:43], v[178:181], v[222:225], v[40:43]
	v_mfma_f32_16x16x32_bf16 v[28:31], v[170:173], v[230:233], v[28:31]
	v_mfma_f32_16x16x32_bf16 v[24:27], v[178:181], v[230:233], v[24:27]
	v_mfma_f32_16x16x32_bf16 v[12:15], v[170:173], v[238:241], v[12:15]
	v_mfma_f32_16x16x32_bf16 v[8:11], v[178:181], v[238:241], v[8:11]
	v_mfma_f32_16x16x32_bf16 v[52:55], v[182:185], v[210:213], v[52:55]
	v_mfma_f32_16x16x32_bf16 v[48:51], v[202:205], v[210:213], v[48:51]
	v_mfma_f32_16x16x32_bf16 v[36:39], v[182:185], v[218:221], v[36:39]
	v_mfma_f32_16x16x32_bf16 v[32:35], v[202:205], v[218:221], v[32:35]
	v_mfma_f32_16x16x32_bf16 v[20:23], v[182:185], v[226:229], v[20:23]
	v_mfma_f32_16x16x32_bf16 v[16:19], v[202:205], v[226:229], v[16:19]
	v_mfma_f32_16x16x32_bf16 v[4:7], v[182:185], v[234:237], v[4:7]
	v_mfma_f32_16x16x32_bf16 v[0:3], v[202:205], v[234:237], v[0:3]
	v_mfma_f32_16x16x32_bf16 v[52:55], v[198:201], v[214:217], v[52:55]
	v_mfma_f32_16x16x32_bf16 v[48:51], v[206:209], v[214:217], v[48:51]
	v_mfma_f32_16x16x32_bf16 v[36:39], v[198:201], v[222:225], v[36:39]
	v_mfma_f32_16x16x32_bf16 v[32:35], v[206:209], v[222:225], v[32:35]
	v_mfma_f32_16x16x32_bf16 v[20:23], v[198:201], v[230:233], v[20:23]
	v_mfma_f32_16x16x32_bf16 v[16:19], v[206:209], v[230:233], v[16:19]
	v_mfma_f32_16x16x32_bf16 v[4:7], v[198:201], v[238:241], v[4:7]
	v_mfma_f32_16x16x32_bf16 v[0:3], v[206:209], v[238:241], v[0:3]
	s_barrier
	s_add_i32 s3, s93, 0x100
	v_add_u32_e32 v155, s3, v152
	s_add_i32 s6, s82, 0x100
	ds_read_b128 v[156:159], v155
	ds_read_b128 v[170:173], v155 offset:1024
	ds_read_b128 v[174:177], v155 offset:2048
	ds_read_b128 v[178:181], v155 offset:3072
	v_add_u32_e32 v155, s6, v152
	ds_read_b128 v[182:185], v155
	ds_read_b128 v[198:201], v155 offset:1024
	ds_read_b128 v[202:205], v155 offset:2048
	ds_read_b128 v[206:209], v155 offset:3072
	v_lshl_add_u64 v[164:165], v[164:165], 0, s[44:45]
	s_mov_b32 m0, s20
	v_lshl_add_u64 v[242:243], v[164:165], 0, v[162:163]
	ds_read_b128 v[210:213], v154 offset:32768
	ds_read_b128 v[214:217], v154 offset:33792
	ds_read_b128 v[218:221], v154 offset:34816
	ds_read_b128 v[222:225], v154 offset:35840
	ds_read_b128 v[226:229], v154 offset:36864
	ds_read_b128 v[230:233], v154 offset:37888
	ds_read_b128 v[234:237], v154 offset:38912
	ds_read_b128 v[238:241], v154 offset:39936
	global_load_lds_dwordx4 v[242:243], off
	v_lshl_add_u64 v[164:165], v[164:165], 0, v[134:135]
	s_mov_b32 m0, s21
	s_nop 0
	global_load_lds_dwordx4 v[164:165], off
	s_waitcnt vmcnt(8)
	s_waitcnt lgkmcnt(0)
	s_barrier
	s_waitcnt lgkmcnt(0)
	v_mfma_f32_16x16x32_bf16 v[124:127], v[156:159], v[210:213], v[124:127]
	v_mfma_f32_16x16x32_bf16 v[120:123], v[174:177], v[210:213], v[120:123]
	v_mfma_f32_16x16x32_bf16 v[108:111], v[156:159], v[218:221], v[108:111]
	v_mfma_f32_16x16x32_bf16 v[104:107], v[174:177], v[218:221], v[104:107]
	v_mfma_f32_16x16x32_bf16 v[92:95], v[156:159], v[226:229], v[92:95]
	v_mfma_f32_16x16x32_bf16 v[88:91], v[174:177], v[226:229], v[88:91]
	v_mfma_f32_16x16x32_bf16 v[76:79], v[156:159], v[234:237], v[76:79]
	v_mfma_f32_16x16x32_bf16 v[72:75], v[174:177], v[234:237], v[72:75]
	v_mfma_f32_16x16x32_bf16 v[124:127], v[170:173], v[214:217], v[124:127]
	v_mfma_f32_16x16x32_bf16 v[120:123], v[178:181], v[214:217], v[120:123]
	v_mfma_f32_16x16x32_bf16 v[108:111], v[170:173], v[222:225], v[108:111]
	v_mfma_f32_16x16x32_bf16 v[104:107], v[178:181], v[222:225], v[104:107]
	v_mfma_f32_16x16x32_bf16 v[92:95], v[170:173], v[230:233], v[92:95]
	v_mfma_f32_16x16x32_bf16 v[88:91], v[178:181], v[230:233], v[88:91]
	v_mfma_f32_16x16x32_bf16 v[76:79], v[170:173], v[238:241], v[76:79]
	v_mfma_f32_16x16x32_bf16 v[72:75], v[178:181], v[238:241], v[72:75]
	v_mfma_f32_16x16x32_bf16 v[116:119], v[182:185], v[210:213], v[116:119]
	v_mfma_f32_16x16x32_bf16 v[112:115], v[202:205], v[210:213], v[112:115]
	v_mfma_f32_16x16x32_bf16 v[100:103], v[182:185], v[218:221], v[100:103]
	v_mfma_f32_16x16x32_bf16 v[96:99], v[202:205], v[218:221], v[96:99]
	v_mfma_f32_16x16x32_bf16 v[84:87], v[182:185], v[226:229], v[84:87]
	v_mfma_f32_16x16x32_bf16 v[80:83], v[202:205], v[226:229], v[80:83]
	v_mfma_f32_16x16x32_bf16 v[68:71], v[182:185], v[234:237], v[68:71]
	v_mfma_f32_16x16x32_bf16 v[64:67], v[202:205], v[234:237], v[64:67]
	v_mfma_f32_16x16x32_bf16 v[116:119], v[198:201], v[214:217], v[116:119]
	v_mfma_f32_16x16x32_bf16 v[112:115], v[206:209], v[214:217], v[112:115]
	v_mfma_f32_16x16x32_bf16 v[100:103], v[198:201], v[222:225], v[100:103]
	v_mfma_f32_16x16x32_bf16 v[96:99], v[206:209], v[222:225], v[96:99]
	v_mfma_f32_16x16x32_bf16 v[84:87], v[198:201], v[230:233], v[84:87]
	v_mfma_f32_16x16x32_bf16 v[80:83], v[206:209], v[230:233], v[80:83]
	v_mfma_f32_16x16x32_bf16 v[68:71], v[198:201], v[238:241], v[68:71]
	v_mfma_f32_16x16x32_bf16 v[64:67], v[206:209], v[238:241], v[64:67]
	s_barrier
	s_add_i32 s3, s3, s17
	v_lshl_add_u64 v[146:147], v[146:147], 0, s[84:85]
	s_mov_b32 m0, s3
	ds_read_b128 v[210:213], v154 offset:49152
	ds_read_b128 v[214:217], v154 offset:50176
	ds_read_b128 v[218:221], v154 offset:51200
	ds_read_b128 v[222:225], v154 offset:52224
	ds_read_b128 v[226:229], v154 offset:53248
	ds_read_b128 v[230:233], v154 offset:54272
	ds_read_b128 v[234:237], v154 offset:55296
	ds_read_b128 v[238:241], v154 offset:56320
	global_load_lds_dwordx4 v[146:147], off
	v_lshl_add_u64 v[146:147], v[186:187], 0, s[84:85]
	s_add_i32 m0, s3, 0x2000
	s_add_i32 s3, s6, s17
	global_load_lds_dwordx4 v[146:147], off
	v_lshl_add_u64 v[146:147], v[166:167], 0, s[30:31]
	v_lshl_add_u64 v[164:165], v[146:147], 0, v[162:163]
	s_mov_b32 m0, s3
	v_lshl_add_u64 v[146:147], v[146:147], 0, v[134:135]
	global_load_lds_dwordx4 v[164:165], off
	s_add_i32 m0, s3, 0x2000
	s_nop 0
	global_load_lds_dwordx4 v[146:147], off
	v_lshl_add_u64 v[146:147], v[190:191], 0, s[84:85]
	s_mov_b32 m0, s22
	s_nop 0
	global_load_lds_dwordx4 v[146:147], off
	v_lshl_add_u64 v[146:147], v[192:193], 0, s[84:85]
	s_mov_b32 m0, s23
	s_nop 0
	global_load_lds_dwordx4 v[146:147], off
	s_waitcnt vmcnt(8)
	s_waitcnt lgkmcnt(0)
	s_barrier
	s_waitcnt lgkmcnt(0)
	v_mfma_f32_16x16x32_bf16 v[60:63], v[156:159], v[210:213], v[60:63]
	v_mfma_f32_16x16x32_bf16 v[56:59], v[174:177], v[210:213], v[56:59]
	v_mfma_f32_16x16x32_bf16 v[44:47], v[156:159], v[218:221], v[44:47]
	v_mfma_f32_16x16x32_bf16 v[40:43], v[174:177], v[218:221], v[40:43]
	v_mfma_f32_16x16x32_bf16 v[28:31], v[156:159], v[226:229], v[28:31]
	v_mfma_f32_16x16x32_bf16 v[24:27], v[174:177], v[226:229], v[24:27]
	v_mfma_f32_16x16x32_bf16 v[12:15], v[156:159], v[234:237], v[12:15]
	v_mfma_f32_16x16x32_bf16 v[8:11], v[174:177], v[234:237], v[8:11]
	v_mfma_f32_16x16x32_bf16 v[60:63], v[170:173], v[214:217], v[60:63]
	v_mfma_f32_16x16x32_bf16 v[56:59], v[178:181], v[214:217], v[56:59]
	v_mfma_f32_16x16x32_bf16 v[44:47], v[170:173], v[222:225], v[44:47]
	v_mfma_f32_16x16x32_bf16 v[40:43], v[178:181], v[222:225], v[40:43]
	v_mfma_f32_16x16x32_bf16 v[28:31], v[170:173], v[230:233], v[28:31]
	v_mfma_f32_16x16x32_bf16 v[24:27], v[178:181], v[230:233], v[24:27]
	v_mfma_f32_16x16x32_bf16 v[12:15], v[170:173], v[238:241], v[12:15]
	v_mfma_f32_16x16x32_bf16 v[8:11], v[178:181], v[238:241], v[8:11]
	v_mfma_f32_16x16x32_bf16 v[52:55], v[182:185], v[210:213], v[52:55]
	v_mfma_f32_16x16x32_bf16 v[48:51], v[202:205], v[210:213], v[48:51]
	v_mfma_f32_16x16x32_bf16 v[36:39], v[182:185], v[218:221], v[36:39]
	v_mfma_f32_16x16x32_bf16 v[32:35], v[202:205], v[218:221], v[32:35]
	v_mfma_f32_16x16x32_bf16 v[20:23], v[182:185], v[226:229], v[20:23]
	v_mfma_f32_16x16x32_bf16 v[16:19], v[202:205], v[226:229], v[16:19]
	v_mfma_f32_16x16x32_bf16 v[4:7], v[182:185], v[234:237], v[4:7]
	v_mfma_f32_16x16x32_bf16 v[0:3], v[202:205], v[234:237], v[0:3]
	v_mfma_f32_16x16x32_bf16 v[52:55], v[198:201], v[214:217], v[52:55]
	v_mfma_f32_16x16x32_bf16 v[48:51], v[206:209], v[214:217], v[48:51]
	v_mfma_f32_16x16x32_bf16 v[36:39], v[198:201], v[222:225], v[36:39]
	v_mfma_f32_16x16x32_bf16 v[32:35], v[206:209], v[222:225], v[32:35]
	v_mfma_f32_16x16x32_bf16 v[20:23], v[198:201], v[230:233], v[20:23]
	v_mfma_f32_16x16x32_bf16 v[16:19], v[206:209], v[230:233], v[16:19]
	v_mfma_f32_16x16x32_bf16 v[4:7], v[198:201], v[238:241], v[4:7]
	v_mfma_f32_16x16x32_bf16 v[0:3], v[206:209], v[238:241], v[0:3]
	s_barrier
	s_add_i32 s2, s2, 2
	v_lshl_add_u64 v[144:145], v[144:145], 0, s[0:1]
	s_cmp_gt_u32 s2, 41
	v_mov_b64_e32 v[146:147], v[148:149]
	s_cbranch_scc0 .LBB0_264
	s_and_b64 vcc, exec, s[10:11]
	s_cbranch_vccz .LBB0_267
	s_barrier

.LBB0_279:
	v_bfe_u32 v35, v4, 4, 2
	v_and_b32_e32 v5, 15, v4
	v_lshlrev_b32_e32 v6, 4, v35
	v_lshlrev_b32_e32 v4, 2, v4
	v_lshl_or_b32 v34, s8, 6, v5
	v_lshl_or_b32 v5, v5, 6, v6
	s_lshl_b32 s5, s8, 13
	v_and_b32_e32 v4, 32, v4
	v_bitop3_b32 v36, v5, s5, v4 bitop3:0xde
	s_lshl_b32 s5, s9, 5
	s_and_b32 s5, s5, 0x60
	s_lshl_b32 s8, s5, 7
	s_add_i32 s18, s93, 0x100
	v_bitop3_b32 v37, v5, s8, v4 bitop3:0xde
	s_add_i32 s8, s18, s17
	v_lshl_add_u64 v[6:7], v[12:13], 0, s[84:85]
	s_mov_b32 m0, s8
	s_add_i32 s11, s8, 0x2000
	s_waitcnt vmcnt(2)
	s_barrier
	global_load_lds_dwordx4 v[6:7], off
	v_lshl_add_u64 v[8:9], v[18:19], 0, s[84:85]
	s_mov_b32 m0, s11
	s_add_i32 s9, s10, 0x8000
	global_load_lds_dwordx4 v[8:9], off
	v_lshl_add_u64 v[4:5], v[26:27], 0, s[84:85]
	s_mov_b32 m0, s9
	s_add_i32 s13, s10, 0xa000
	s_add_i32 s19, s82, 0x100
	global_load_lds_dwordx4 v[4:5], off
	v_lshl_add_u64 v[10:11], v[28:29], 0, s[84:85]
	s_mov_b32 m0, s13
	v_lshl_add_u64 v[16:17], v[32:33], 0, s[26:27]
	s_add_i32 s14, s19, s17
	global_load_lds_dwordx4 v[10:11], off
	v_lshl_add_u64 v[14:15], v[16:17], 0, v[162:163]
	s_mov_b32 m0, s14
	s_add_i32 s15, s14, 0x2000
	global_load_lds_dwordx4 v[14:15], off
	v_lshl_add_u64 v[16:17], v[16:17], 0, v[24:25]
	s_mov_b32 m0, s15
	s_add_i32 s20, s33, 0x100
	global_load_lds_dwordx4 v[16:17], off
	v_add_u32_e32 v186, s20, v37
	s_add_i32 s21, s92, 0x100
	s_waitcnt vmcnt(6)
	s_barrier
	v_add_u32_e32 v187, s21, v37
	ds_read_b128 v[38:41], v186
	ds_read_b128 v[42:45], v186 offset:1024
	ds_read_b128 v[46:49], v186 offset:2048
	ds_read_b128 v[50:53], v186 offset:3072
	ds_read_b128 v[54:57], v187
	ds_read_b128 v[58:61], v187 offset:1024
	ds_read_b128 v[62:65], v187 offset:2048
	ds_read_b128 v[66:69], v187 offset:3072
	v_add_u32_e32 v36, 0x100, v36
	v_add_u32_e32 v250, s18, v37
	v_add_u32_e32 v37, s19, v37
	v_lshlrev_b32_e32 v35, 2, v35
	v_lshl_add_u64 v[102:103], v[30:31], 0, s[26:27]
	s_add_i32 s22, s10, 0xc000
	v_lshl_add_u64 v[104:105], v[102:103], 0, v[162:163]
	s_mov_b32 m0, s22
	s_add_i32 s18, s10, 0xe000
	ds_read_b128 v[70:73], v36
	ds_read_b128 v[74:77], v36 offset:1024
	ds_read_b128 v[78:81], v36 offset:2048
	ds_read_b128 v[82:85], v36 offset:3072
	ds_read_b128 v[86:89], v36 offset:4096
	ds_read_b128 v[90:93], v36 offset:5120
	ds_read_b128 v[94:97], v36 offset:6144
	ds_read_b128 v[98:101], v36 offset:7168
	global_load_lds_dwordx4 v[104:105], off
	v_lshl_add_u64 v[102:103], v[102:103], 0, v[24:25]
	s_mov_b32 m0, s18
	s_nop 0
	global_load_lds_dwordx4 v[102:103], off
	s_waitcnt vmcnt(8)
	s_waitcnt lgkmcnt(0)
	s_barrier
	s_waitcnt lgkmcnt(0)
	v_mfma_f32_16x16x32_bf16 v[102:105], v[38:41], v[70:73], 0
	v_mfma_f32_16x16x32_bf16 v[106:109], v[46:49], v[70:73], 0
	v_mfma_f32_16x16x32_bf16 v[110:113], v[38:41], v[78:81], 0
	v_mfma_f32_16x16x32_bf16 v[114:117], v[46:49], v[78:81], 0
	v_mfma_f32_16x16x32_bf16 v[118:121], v[38:41], v[86:89], 0
	v_mfma_f32_16x16x32_bf16 v[122:125], v[46:49], v[86:89], 0
	v_mfma_f32_16x16x32_bf16 v[130:133], v[38:41], v[94:97], 0
	v_mfma_f32_16x16x32_bf16 v[134:137], v[46:49], v[94:97], 0
	v_mfma_f32_16x16x32_bf16 v[102:105], v[42:45], v[74:77], v[102:105]
	v_mfma_f32_16x16x32_bf16 v[106:109], v[50:53], v[74:77], v[106:109]
	v_mfma_f32_16x16x32_bf16 v[110:113], v[42:45], v[82:85], v[110:113]
	v_mfma_f32_16x16x32_bf16 v[114:117], v[50:53], v[82:85], v[114:117]
	v_mfma_f32_16x16x32_bf16 v[118:121], v[42:45], v[90:93], v[118:121]
	v_mfma_f32_16x16x32_bf16 v[122:125], v[50:53], v[90:93], v[122:125]
	v_mfma_f32_16x16x32_bf16 v[130:133], v[42:45], v[98:101], v[130:133]
	v_mfma_f32_16x16x32_bf16 v[134:137], v[50:53], v[98:101], v[134:137]
	v_mfma_f32_16x16x32_bf16 v[138:141], v[54:57], v[70:73], 0
	v_mfma_f32_16x16x32_bf16 v[70:73], v[62:65], v[70:73], 0
	v_mfma_f32_16x16x32_bf16 v[138:141], v[58:61], v[74:77], v[138:141]
	v_mfma_f32_16x16x32_bf16 v[70:73], v[66:69], v[74:77], v[70:73]
	v_mfma_f32_16x16x32_bf16 v[74:77], v[54:57], v[78:81], 0
	v_mfma_f32_16x16x32_bf16 v[78:81], v[62:65], v[78:81], 0
	v_mfma_f32_16x16x32_bf16 v[74:77], v[58:61], v[82:85], v[74:77]
	v_mfma_f32_16x16x32_bf16 v[78:81], v[66:69], v[82:85], v[78:81]
	v_mfma_f32_16x16x32_bf16 v[82:85], v[54:57], v[86:89], 0
	v_mfma_f32_16x16x32_bf16 v[86:89], v[62:65], v[86:89], 0
	v_mfma_f32_16x16x32_bf16 v[82:85], v[58:61], v[90:93], v[82:85]
	v_mfma_f32_16x16x32_bf16 v[86:89], v[66:69], v[90:93], v[86:89]
	v_mfma_f32_16x16x32_bf16 v[90:93], v[54:57], v[94:97], 0
	v_mfma_f32_16x16x32_bf16 v[94:97], v[62:65], v[94:97], 0
	v_mfma_f32_16x16x32_bf16 v[90:93], v[58:61], v[98:101], v[90:93]
	v_mfma_f32_16x16x32_bf16 v[94:97], v[66:69], v[98:101], v[94:97]
	s_barrier
	s_add_i32 s19, s20, s17
	v_lshl_add_u64 v[126:127], v[12:13], 0, s[0:1]
	s_mov_b32 m0, s19
	s_add_i32 s20, s19, 0x2000
	ds_read_b128 v[98:101], v36 offset:16384
	ds_read_b128 v[142:145], v36 offset:17408
	ds_read_b128 v[146:149], v36 offset:18432
	ds_read_b128 v[150:153], v36 offset:19456
	ds_read_b128 v[154:157], v36 offset:20480
	ds_read_b128 v[170:173], v36 offset:21504
	ds_read_b128 v[174:177], v36 offset:22528
	ds_read_b128 v[178:181], v36 offset:23552
	global_load_lds_dwordx4 v[126:127], off
	v_lshl_add_u64 v[126:127], v[18:19], 0, s[0:1]
	s_mov_b32 m0, s20
	s_mov_b64 s[26:27], 0xb0100
	global_load_lds_dwordx4 v[126:127], off
	v_lshl_add_u64 v[126:127], v[32:33], 0, s[26:27]
	s_add_i32 s17, s21, s17
	v_lshl_add_u64 v[158:159], v[126:127], 0, v[162:163]
	s_mov_b32 m0, s17
	s_add_i32 s21, s17, 0x2000
	global_load_lds_dwordx4 v[158:159], off
	v_lshl_add_u64 v[126:127], v[126:127], 0, v[24:25]
	s_mov_b32 m0, s21
	s_nop 0
	global_load_lds_dwordx4 v[126:127], off
	v_lshl_add_u64 v[126:127], v[26:27], 0, s[0:1]
	s_mov_b32 m0, s10
	s_nop 0
	global_load_lds_dwordx4 v[126:127], off
	v_lshl_add_u64 v[126:127], v[28:29], 0, s[0:1]
	s_mov_b32 m0, s16
	s_nop 0
	global_load_lds_dwordx4 v[126:127], off
	s_waitcnt vmcnt(8)
	s_waitcnt lgkmcnt(0)
	s_barrier
	s_waitcnt lgkmcnt(0)
	v_mfma_f32_16x16x32_bf16 v[182:185], v[38:41], v[98:101], 0
	v_mfma_f32_16x16x32_bf16 v[202:205], v[38:41], v[146:149], 0
	v_mfma_f32_16x16x32_bf16 v[210:213], v[38:41], v[154:157], 0
	v_mfma_f32_16x16x32_bf16 v[38:41], v[38:41], v[174:177], 0
	v_mfma_f32_16x16x32_bf16 v[182:185], v[42:45], v[142:145], v[182:185]
	v_mfma_f32_16x16x32_bf16 v[198:201], v[46:49], v[98:101], 0
	v_mfma_f32_16x16x32_bf16 v[202:205], v[42:45], v[150:153], v[202:205]
	v_mfma_f32_16x16x32_bf16 v[206:209], v[46:49], v[146:149], 0
	v_mfma_f32_16x16x32_bf16 v[210:213], v[42:45], v[170:173], v[210:213]
	v_mfma_f32_16x16x32_bf16 v[214:217], v[46:49], v[154:157], 0
	v_mfma_f32_16x16x32_bf16 v[38:41], v[42:45], v[178:181], v[38:41]
	v_mfma_f32_16x16x32_bf16 v[42:45], v[46:49], v[174:177], 0
	v_mfma_f32_16x16x32_bf16 v[198:201], v[50:53], v[142:145], v[198:201]
	v_mfma_f32_16x16x32_bf16 v[206:209], v[50:53], v[150:153], v[206:209]
	v_mfma_f32_16x16x32_bf16 v[214:217], v[50:53], v[170:173], v[214:217]
	v_mfma_f32_16x16x32_bf16 v[42:45], v[50:53], v[178:181], v[42:45]
	v_mfma_f32_16x16x32_bf16 v[46:49], v[54:57], v[98:101], 0
	v_mfma_f32_16x16x32_bf16 v[50:53], v[62:65], v[98:101], 0
	v_mfma_f32_16x16x32_bf16 v[46:49], v[58:61], v[142:145], v[46:49]
	v_mfma_f32_16x16x32_bf16 v[50:53], v[66:69], v[142:145], v[50:53]
	v_mfma_f32_16x16x32_bf16 v[98:101], v[54:57], v[146:149], 0
	v_mfma_f32_16x16x32_bf16 v[142:145], v[62:65], v[146:149], 0
	v_mfma_f32_16x16x32_bf16 v[146:149], v[54:57], v[154:157], 0
	v_mfma_f32_16x16x32_bf16 v[54:57], v[54:57], v[174:177], 0
	v_mfma_f32_16x16x32_bf16 v[98:101], v[58:61], v[150:153], v[98:101]
	v_mfma_f32_16x16x32_bf16 v[142:145], v[66:69], v[150:153], v[142:145]
	v_mfma_f32_16x16x32_bf16 v[146:149], v[58:61], v[170:173], v[146:149]
	v_mfma_f32_16x16x32_bf16 v[150:153], v[62:65], v[154:157], 0
	v_mfma_f32_16x16x32_bf16 v[54:57], v[58:61], v[178:181], v[54:57]
	v_mfma_f32_16x16x32_bf16 v[58:61], v[62:65], v[174:177], 0
	v_mfma_f32_16x16x32_bf16 v[150:153], v[66:69], v[170:173], v[150:153]
	v_mfma_f32_16x16x32_bf16 v[58:61], v[66:69], v[178:181], v[58:61]
	s_barrier
	ds_read_b128 v[62:65], v250
	ds_read_b128 v[66:69], v250 offset:1024
	ds_read_b128 v[154:157], v250 offset:2048
	ds_read_b128 v[170:173], v250 offset:3072
	ds_read_b128 v[174:177], v37
	ds_read_b128 v[178:181], v37 offset:1024
	ds_read_b128 v[218:221], v37 offset:2048
	ds_read_b128 v[222:225], v37 offset:3072
	v_lshl_add_u64 v[126:127], v[30:31], 0, s[26:27]
	s_mov_b32 m0, s6
	v_lshl_add_u64 v[158:159], v[126:127], 0, v[162:163]
	ds_read_b128 v[226:229], v36 offset:32768
	ds_read_b128 v[230:233], v36 offset:33792
	ds_read_b128 v[234:237], v36 offset:34816
	ds_read_b128 v[238:241], v36 offset:35840
	ds_read_b128 v[242:245], v36 offset:36864
	ds_read_b128 v[246:249], v36 offset:37888
	ds_read_b128 v[164:167], v36 offset:38912
	ds_read_b128 v[190:193], v36 offset:39936
	global_load_lds_dwordx4 v[158:159], off
	v_lshl_add_u64 v[126:127], v[126:127], 0, v[24:25]
	s_mov_b32 m0, s7
	s_nop 0
	global_load_lds_dwordx4 v[126:127], off
	s_waitcnt vmcnt(8)
	s_waitcnt lgkmcnt(0)
	s_barrier
	s_waitcnt lgkmcnt(0)
	v_mfma_f32_16x16x32_bf16 v[102:105], v[62:65], v[226:229], v[102:105]
	v_mfma_f32_16x16x32_bf16 v[106:109], v[154:157], v[226:229], v[106:109]
	v_mfma_f32_16x16x32_bf16 v[110:113], v[62:65], v[234:237], v[110:113]
	v_mfma_f32_16x16x32_bf16 v[114:117], v[154:157], v[234:237], v[114:117]
	v_mfma_f32_16x16x32_bf16 v[118:121], v[62:65], v[242:245], v[118:121]
	v_mfma_f32_16x16x32_bf16 v[122:125], v[154:157], v[242:245], v[122:125]
	v_mfma_f32_16x16x32_bf16 v[130:133], v[62:65], v[164:167], v[130:133]
	v_mfma_f32_16x16x32_bf16 v[134:137], v[154:157], v[164:167], v[134:137]
	v_mfma_f32_16x16x32_bf16 v[102:105], v[66:69], v[230:233], v[102:105]
	v_mfma_f32_16x16x32_bf16 v[106:109], v[170:173], v[230:233], v[106:109]
	v_mfma_f32_16x16x32_bf16 v[110:113], v[66:69], v[238:241], v[110:113]
	v_mfma_f32_16x16x32_bf16 v[114:117], v[170:173], v[238:241], v[114:117]
	v_mfma_f32_16x16x32_bf16 v[118:121], v[66:69], v[246:249], v[118:121]
	v_mfma_f32_16x16x32_bf16 v[122:125], v[170:173], v[246:249], v[122:125]
	v_mfma_f32_16x16x32_bf16 v[130:133], v[66:69], v[190:193], v[130:133]
	v_mfma_f32_16x16x32_bf16 v[134:137], v[170:173], v[190:193], v[134:137]
	v_mfma_f32_16x16x32_bf16 v[138:141], v[174:177], v[226:229], v[138:141]
	v_mfma_f32_16x16x32_bf16 v[70:73], v[218:221], v[226:229], v[70:73]
	v_mfma_f32_16x16x32_bf16 v[74:77], v[174:177], v[234:237], v[74:77]
	v_mfma_f32_16x16x32_bf16 v[78:81], v[218:221], v[234:237], v[78:81]
	v_mfma_f32_16x16x32_bf16 v[82:85], v[174:177], v[242:245], v[82:85]
	v_mfma_f32_16x16x32_bf16 v[86:89], v[218:221], v[242:245], v[86:89]
	v_mfma_f32_16x16x32_bf16 v[90:93], v[174:177], v[164:167], v[90:93]
	v_mfma_f32_16x16x32_bf16 v[94:97], v[218:221], v[164:167], v[94:97]
	v_mfma_f32_16x16x32_bf16 v[138:141], v[178:181], v[230:233], v[138:141]
	v_mfma_f32_16x16x32_bf16 v[70:73], v[222:225], v[230:233], v[70:73]
	v_mfma_f32_16x16x32_bf16 v[74:77], v[178:181], v[238:241], v[74:77]
	v_mfma_f32_16x16x32_bf16 v[78:81], v[222:225], v[238:241], v[78:81]
	v_mfma_f32_16x16x32_bf16 v[82:85], v[178:181], v[246:249], v[82:85]
	v_mfma_f32_16x16x32_bf16 v[86:89], v[222:225], v[246:249], v[86:89]
	v_mfma_f32_16x16x32_bf16 v[90:93], v[178:181], v[190:193], v[90:93]
	v_mfma_f32_16x16x32_bf16 v[94:97], v[222:225], v[190:193], v[94:97]
	s_barrier
	s_mov_b64 s[26:27], 0x180
	s_mov_b32 m0, s8
	v_lshl_add_u64 v[126:127], v[12:13], 0, s[26:27]
	s_mov_b64 s[30:31], 0xb0180
	ds_read_b128 v[164:167], v36 offset:49152
	ds_read_b128 v[190:193], v36 offset:50176
	ds_read_b128 v[226:229], v36 offset:51200
	ds_read_b128 v[230:233], v36 offset:52224
	ds_read_b128 v[234:237], v36 offset:53248
	ds_read_b128 v[238:241], v36 offset:54272
	ds_read_b128 v[242:245], v36 offset:55296
	ds_read_b128 v[246:249], v36 offset:56320
	global_load_lds_dwordx4 v[126:127], off
	v_lshl_add_u64 v[126:127], v[18:19], 0, s[26:27]
	s_mov_b32 m0, s11
	v_lshl_add_u64 v[32:33], v[32:33], 0, s[30:31]
	global_load_lds_dwordx4 v[126:127], off
	v_lshl_add_u64 v[126:127], v[32:33], 0, v[162:163]
	s_mov_b32 m0, s14
	v_lshl_add_u64 v[32:33], v[32:33], 0, v[24:25]
	global_load_lds_dwordx4 v[126:127], off
	s_mov_b32 m0, s15
	s_nop 0
	global_load_lds_dwordx4 v[32:33], off
	v_lshl_add_u64 v[32:33], v[26:27], 0, s[26:27]
	s_mov_b32 m0, s9
	s_nop 0
	global_load_lds_dwordx4 v[32:33], off
	v_lshl_add_u64 v[32:33], v[28:29], 0, s[26:27]
	s_mov_b32 m0, s13
	s_nop 0
	global_load_lds_dwordx4 v[32:33], off
	s_waitcnt vmcnt(8)
	s_waitcnt lgkmcnt(0)
	s_barrier
	s_waitcnt lgkmcnt(0)
	v_mfma_f32_16x16x32_bf16 v[182:185], v[62:65], v[164:167], v[182:185]
	v_mfma_f32_16x16x32_bf16 v[198:201], v[154:157], v[164:167], v[198:201]
	v_mfma_f32_16x16x32_bf16 v[202:205], v[62:65], v[226:229], v[202:205]
	v_mfma_f32_16x16x32_bf16 v[206:209], v[154:157], v[226:229], v[206:209]
	v_mfma_f32_16x16x32_bf16 v[210:213], v[62:65], v[234:237], v[210:213]
	v_mfma_f32_16x16x32_bf16 v[214:217], v[154:157], v[234:237], v[214:217]
	v_mfma_f32_16x16x32_bf16 v[38:41], v[62:65], v[242:245], v[38:41]
	v_mfma_f32_16x16x32_bf16 v[42:45], v[154:157], v[242:245], v[42:45]
	v_mfma_f32_16x16x32_bf16 v[182:185], v[66:69], v[190:193], v[182:185]
	v_mfma_f32_16x16x32_bf16 v[198:201], v[170:173], v[190:193], v[198:201]
	v_mfma_f32_16x16x32_bf16 v[202:205], v[66:69], v[230:233], v[202:205]
	v_mfma_f32_16x16x32_bf16 v[206:209], v[170:173], v[230:233], v[206:209]
	v_mfma_f32_16x16x32_bf16 v[210:213], v[66:69], v[238:241], v[210:213]
	v_mfma_f32_16x16x32_bf16 v[214:217], v[170:173], v[238:241], v[214:217]
	v_mfma_f32_16x16x32_bf16 v[38:41], v[66:69], v[246:249], v[38:41]
	v_mfma_f32_16x16x32_bf16 v[42:45], v[170:173], v[246:249], v[42:45]
	v_mfma_f32_16x16x32_bf16 v[46:49], v[174:177], v[164:167], v[46:49]
	v_mfma_f32_16x16x32_bf16 v[50:53], v[218:221], v[164:167], v[50:53]
	v_mfma_f32_16x16x32_bf16 v[62:65], v[174:177], v[226:229], v[98:101]
	v_mfma_f32_16x16x32_bf16 v[66:69], v[218:221], v[226:229], v[142:145]
	v_mfma_f32_16x16x32_bf16 v[98:101], v[174:177], v[234:237], v[146:149]
	v_mfma_f32_16x16x32_bf16 v[142:145], v[218:221], v[234:237], v[150:153]
	v_mfma_f32_16x16x32_bf16 v[54:57], v[174:177], v[242:245], v[54:57]
	v_mfma_f32_16x16x32_bf16 v[58:61], v[218:221], v[242:245], v[58:61]
	v_mfma_f32_16x16x32_bf16 v[46:49], v[178:181], v[190:193], v[46:49]
	v_mfma_f32_16x16x32_bf16 v[50:53], v[222:225], v[190:193], v[50:53]
	v_mfma_f32_16x16x32_bf16 v[62:65], v[178:181], v[230:233], v[62:65]
	v_mfma_f32_16x16x32_bf16 v[66:69], v[222:225], v[230:233], v[66:69]
	v_mfma_f32_16x16x32_bf16 v[98:101], v[178:181], v[238:241], v[98:101]
	v_mfma_f32_16x16x32_bf16 v[142:145], v[222:225], v[238:241], v[142:145]
	v_mfma_f32_16x16x32_bf16 v[54:57], v[178:181], v[246:249], v[54:57]
	v_mfma_f32_16x16x32_bf16 v[58:61], v[222:225], v[246:249], v[58:61]
	s_barrier
	ds_read_b128 v[146:149], v186
	ds_read_b128 v[150:153], v186 offset:1024
	ds_read_b128 v[154:157], v186 offset:2048
	ds_read_b128 v[164:167], v186 offset:3072
	ds_read_b128 v[170:173], v187
	ds_read_b128 v[174:177], v187 offset:1024
	ds_read_b128 v[178:181], v187 offset:2048
	ds_read_b128 v[190:193], v187 offset:3072
	v_lshl_add_u64 v[30:31], v[30:31], 0, s[30:31]
	s_mov_b32 m0, s22
	v_lshl_add_u64 v[32:33], v[30:31], 0, v[162:163]
	ds_read_b128 v[218:221], v36
	ds_read_b128 v[222:225], v36 offset:1024
	ds_read_b128 v[226:229], v36 offset:2048
	ds_read_b128 v[230:233], v36 offset:3072
	ds_read_b128 v[234:237], v36 offset:4096
	ds_read_b128 v[238:241], v36 offset:5120
	ds_read_b128 v[242:245], v36 offset:6144
	ds_read_b128 v[246:249], v36 offset:7168
	global_load_lds_dwordx4 v[32:33], off
	v_lshl_add_u64 v[24:25], v[30:31], 0, v[24:25]
	s_mov_b32 m0, s18
	s_nop 0
	global_load_lds_dwordx4 v[24:25], off
	s_waitcnt vmcnt(8)
	s_waitcnt lgkmcnt(0)
	s_barrier
	s_waitcnt lgkmcnt(0)
	v_mfma_f32_16x16x32_bf16 v[30:33], v[146:149], v[218:221], v[102:105]
	v_mfma_f32_16x16x32_bf16 v[102:105], v[154:157], v[218:221], v[106:109]
	v_mfma_f32_16x16x32_bf16 v[106:109], v[146:149], v[226:229], v[110:113]
	v_mfma_f32_16x16x32_bf16 v[110:113], v[154:157], v[226:229], v[114:117]
	v_mfma_f32_16x16x32_bf16 v[114:117], v[146:149], v[234:237], v[118:121]
	v_mfma_f32_16x16x32_bf16 v[118:121], v[154:157], v[234:237], v[122:125]
	v_mfma_f32_16x16x32_bf16 v[122:125], v[146:149], v[242:245], v[130:133]
	v_mfma_f32_16x16x32_bf16 v[130:133], v[154:157], v[242:245], v[134:137]
	v_mfma_f32_16x16x32_bf16 v[30:33], v[150:153], v[222:225], v[30:33]
	v_mfma_f32_16x16x32_bf16 v[102:105], v[164:167], v[222:225], v[102:105]
	v_mfma_f32_16x16x32_bf16 v[106:109], v[150:153], v[230:233], v[106:109]
	v_mfma_f32_16x16x32_bf16 v[110:113], v[164:167], v[230:233], v[110:113]
	v_mfma_f32_16x16x32_bf16 v[114:117], v[150:153], v[238:241], v[114:117]
	v_mfma_f32_16x16x32_bf16 v[118:121], v[164:167], v[238:241], v[118:121]
	v_mfma_f32_16x16x32_bf16 v[122:125], v[150:153], v[246:249], v[122:125]
	v_mfma_f32_16x16x32_bf16 v[130:133], v[164:167], v[246:249], v[130:133]
	v_mfma_f32_16x16x32_bf16 v[134:137], v[170:173], v[218:221], v[138:141]
	v_mfma_f32_16x16x32_bf16 v[70:73], v[178:181], v[218:221], v[70:73]
	v_mfma_f32_16x16x32_bf16 v[74:77], v[170:173], v[226:229], v[74:77]
	v_mfma_f32_16x16x32_bf16 v[78:81], v[178:181], v[226:229], v[78:81]
	v_mfma_f32_16x16x32_bf16 v[82:85], v[170:173], v[234:237], v[82:85]
	v_mfma_f32_16x16x32_bf16 v[86:89], v[178:181], v[234:237], v[86:89]
	v_mfma_f32_16x16x32_bf16 v[90:93], v[170:173], v[242:245], v[90:93]
	v_mfma_f32_16x16x32_bf16 v[94:97], v[178:181], v[242:245], v[94:97]
	v_mfma_f32_16x16x32_bf16 v[134:137], v[174:177], v[222:225], v[134:137]
	v_mfma_f32_16x16x32_bf16 v[70:73], v[190:193], v[222:225], v[70:73]
	v_mfma_f32_16x16x32_bf16 v[74:77], v[174:177], v[230:233], v[74:77]
	v_mfma_f32_16x16x32_bf16 v[78:81], v[190:193], v[230:233], v[78:81]
	v_mfma_f32_16x16x32_bf16 v[82:85], v[174:177], v[238:241], v[82:85]
	v_mfma_f32_16x16x32_bf16 v[86:89], v[190:193], v[238:241], v[86:89]
	v_mfma_f32_16x16x32_bf16 v[90:93], v[174:177], v[246:249], v[90:93]
	v_mfma_f32_16x16x32_bf16 v[94:97], v[190:193], v[246:249], v[94:97]
	s_barrier
	s_mov_b32 m0, s19
	ds_read_b128 v[138:141], v36 offset:16384
	ds_read_b128 v[218:221], v36 offset:17408
	ds_read_b128 v[222:225], v36 offset:18432
	ds_read_b128 v[226:229], v36 offset:19456
	ds_read_b128 v[230:233], v36 offset:20480
	ds_read_b128 v[234:237], v36 offset:21504
	ds_read_b128 v[238:241], v36 offset:22528
	ds_read_b128 v[242:245], v36 offset:23552
	global_load_lds_dwordx4 v[12:13], off
	s_mov_b32 m0, s20
	s_nop 0
	global_load_lds_dwordx4 v[18:19], off
	s_mov_b32 m0, s17
	s_nop 0
	global_load_lds_dwordx4 v[20:21], off
	s_mov_b32 m0, s21
	s_nop 0
	global_load_lds_dwordx4 v[22:23], off
	s_mov_b32 m0, s10
	s_nop 0
	global_load_lds_dwordx4 v[26:27], off
	s_mov_b32 m0, s16
	s_nop 0
	global_load_lds_dwordx4 v[28:29], off
	s_waitcnt vmcnt(8)
	s_waitcnt lgkmcnt(0)
	s_barrier
	s_waitcnt lgkmcnt(0)
	v_mfma_f32_16x16x32_bf16 v[18:21], v[146:149], v[138:141], v[182:185]
	v_mfma_f32_16x16x32_bf16 v[22:25], v[154:157], v[138:141], v[198:201]
	v_mfma_f32_16x16x32_bf16 v[26:29], v[146:149], v[222:225], v[202:205]
	v_mfma_f32_16x16x32_bf16 v[182:185], v[154:157], v[222:225], v[206:209]
	v_mfma_f32_16x16x32_bf16 v[198:201], v[146:149], v[230:233], v[210:213]
	v_mfma_f32_16x16x32_bf16 v[202:205], v[154:157], v[230:233], v[214:217]
	v_mfma_f32_16x16x32_bf16 v[38:41], v[146:149], v[238:241], v[38:41]
	v_mfma_f32_16x16x32_bf16 v[42:45], v[154:157], v[238:241], v[42:45]
	v_mfma_f32_16x16x32_bf16 v[18:21], v[150:153], v[218:221], v[18:21]
	v_mfma_f32_16x16x32_bf16 v[22:25], v[164:167], v[218:221], v[22:25]
	v_mfma_f32_16x16x32_bf16 v[26:29], v[150:153], v[226:229], v[26:29]
	v_mfma_f32_16x16x32_bf16 v[182:185], v[164:167], v[226:229], v[182:185]
	v_mfma_f32_16x16x32_bf16 v[198:201], v[150:153], v[234:237], v[198:201]
	v_mfma_f32_16x16x32_bf16 v[202:205], v[164:167], v[234:237], v[202:205]
	v_mfma_f32_16x16x32_bf16 v[38:41], v[150:153], v[242:245], v[38:41]
	v_mfma_f32_16x16x32_bf16 v[42:45], v[164:167], v[242:245], v[42:45]
	v_mfma_f32_16x16x32_bf16 v[46:49], v[170:173], v[138:141], v[46:49]
	v_mfma_f32_16x16x32_bf16 v[50:53], v[178:181], v[138:141], v[50:53]
	v_mfma_f32_16x16x32_bf16 v[62:65], v[170:173], v[222:225], v[62:65]
	v_mfma_f32_16x16x32_bf16 v[66:69], v[178:181], v[222:225], v[66:69]
	v_mfma_f32_16x16x32_bf16 v[98:101], v[170:173], v[230:233], v[98:101]
	v_mfma_f32_16x16x32_bf16 v[138:141], v[178:181], v[230:233], v[142:145]
	v_mfma_f32_16x16x32_bf16 v[54:57], v[170:173], v[238:241], v[54:57]
	v_mfma_f32_16x16x32_bf16 v[58:61], v[178:181], v[238:241], v[58:61]
	v_mfma_f32_16x16x32_bf16 v[46:49], v[174:177], v[218:221], v[46:49]
	v_mfma_f32_16x16x32_bf16 v[50:53], v[190:193], v[218:221], v[50:53]
	v_mfma_f32_16x16x32_bf16 v[62:65], v[174:177], v[226:229], v[62:65]
	v_mfma_f32_16x16x32_bf16 v[66:69], v[190:193], v[226:229], v[66:69]
	v_mfma_f32_16x16x32_bf16 v[98:101], v[174:177], v[234:237], v[98:101]
	v_mfma_f32_16x16x32_bf16 v[138:141], v[190:193], v[234:237], v[138:141]
	v_mfma_f32_16x16x32_bf16 v[54:57], v[174:177], v[242:245], v[54:57]
	v_mfma_f32_16x16x32_bf16 v[58:61], v[190:193], v[242:245], v[58:61]
	s_barrier
	ds_read_b128 v[142:145], v250
	ds_read_b128 v[146:149], v250 offset:1024
	ds_read_b128 v[150:153], v250 offset:2048
	ds_read_b128 v[154:157], v250 offset:3072
	ds_read_b128 v[164:167], v37
	ds_read_b128 v[170:173], v37 offset:1024
	ds_read_b128 v[174:177], v37 offset:2048
	ds_read_b128 v[178:181], v37 offset:3072
	s_mov_b32 m0, s6
	ds_read_b128 v[190:193], v36 offset:32768
	ds_read_b128 v[206:209], v36 offset:33792
	ds_read_b128 v[210:213], v36 offset:34816
	ds_read_b128 v[214:217], v36 offset:35840
	ds_read_b128 v[218:221], v36 offset:36864
	ds_read_b128 v[222:225], v36 offset:37888
	ds_read_b128 v[226:229], v36 offset:38912
	ds_read_b128 v[230:233], v36 offset:39936
	global_load_lds_dwordx4 v[0:1], off
	s_mov_b32 m0, s7
	s_nop 0
	global_load_lds_dwordx4 v[2:3], off
	s_waitcnt vmcnt(8)
	s_waitcnt lgkmcnt(0)
	s_barrier
	s_waitcnt lgkmcnt(0)
	v_mfma_f32_16x16x32_bf16 v[0:3], v[142:145], v[190:193], v[30:33]
	v_mfma_f32_16x16x32_bf16 v[234:237], v[146:149], v[206:209], v[0:3]
	v_mfma_f32_16x16x32_bf16 v[0:3], v[150:153], v[190:193], v[102:105]
	v_mfma_f32_16x16x32_bf16 v[102:105], v[154:157], v[206:209], v[0:3]
	v_mfma_f32_16x16x32_bf16 v[0:3], v[142:145], v[210:213], v[106:109]
	v_mfma_f32_16x16x32_bf16 v[106:109], v[146:149], v[214:217], v[0:3]
	v_mfma_f32_16x16x32_bf16 v[0:3], v[150:153], v[210:213], v[110:113]
	v_mfma_f32_16x16x32_bf16 v[110:113], v[154:157], v[214:217], v[0:3]
	v_mfma_f32_16x16x32_bf16 v[0:3], v[142:145], v[218:221], v[114:117]
	v_mfma_f32_16x16x32_bf16 v[114:117], v[146:149], v[222:225], v[0:3]
	v_mfma_f32_16x16x32_bf16 v[0:3], v[150:153], v[218:221], v[118:121]
	v_mfma_f32_16x16x32_bf16 v[118:121], v[154:157], v[222:225], v[0:3]
	v_mfma_f32_16x16x32_bf16 v[0:3], v[142:145], v[226:229], v[122:125]
	v_mfma_f32_16x16x32_bf16 v[122:125], v[146:149], v[230:233], v[0:3]
	v_mfma_f32_16x16x32_bf16 v[0:3], v[150:153], v[226:229], v[130:133]
	v_mfma_f32_16x16x32_bf16 v[130:133], v[154:157], v[230:233], v[0:3]
	v_mfma_f32_16x16x32_bf16 v[0:3], v[164:167], v[190:193], v[134:137]
	v_mfma_f32_16x16x32_bf16 v[134:137], v[170:173], v[206:209], v[0:3]
	v_mfma_f32_16x16x32_bf16 v[0:3], v[174:177], v[190:193], v[70:73]
	v_mfma_f32_16x16x32_bf16 v[70:73], v[178:181], v[206:209], v[0:3]
	v_mfma_f32_16x16x32_bf16 v[0:3], v[164:167], v[210:213], v[74:77]
	v_mfma_f32_16x16x32_bf16 v[74:77], v[170:173], v[214:217], v[0:3]
	v_mfma_f32_16x16x32_bf16 v[0:3], v[174:177], v[210:213], v[78:81]
	v_mfma_f32_16x16x32_bf16 v[78:81], v[178:181], v[214:217], v[0:3]
	v_mfma_f32_16x16x32_bf16 v[0:3], v[164:167], v[218:221], v[82:85]
	v_mfma_f32_16x16x32_bf16 v[82:85], v[170:173], v[222:225], v[0:3]
	v_mfma_f32_16x16x32_bf16 v[0:3], v[174:177], v[218:221], v[86:89]
	v_mfma_f32_16x16x32_bf16 v[86:89], v[178:181], v[222:225], v[0:3]
	v_mfma_f32_16x16x32_bf16 v[0:3], v[164:167], v[226:229], v[90:93]
	v_mfma_f32_16x16x32_bf16 v[90:93], v[170:173], v[230:233], v[0:3]
	v_mfma_f32_16x16x32_bf16 v[0:3], v[174:177], v[226:229], v[94:97]
	v_mfma_f32_16x16x32_bf16 v[94:97], v[178:181], v[230:233], v[0:3]
	s_barrier
	s_mov_b32 m0, s8
	ds_read_b128 v[190:193], v36 offset:49152
	ds_read_b128 v[206:209], v36 offset:50176
	ds_read_b128 v[210:213], v36 offset:51200
	ds_read_b128 v[214:217], v36 offset:52224
	ds_read_b128 v[218:221], v36 offset:53248
	ds_read_b128 v[222:225], v36 offset:54272
	ds_read_b128 v[226:229], v36 offset:55296
	ds_read_b128 v[230:233], v36 offset:56320
	global_load_lds_dwordx4 v[6:7], off
	s_mov_b32 m0, s11
	s_nop 0
	global_load_lds_dwordx4 v[8:9], off
	s_mov_b32 m0, s14
	s_nop 0
	global_load_lds_dwordx4 v[14:15], off
	s_mov_b32 m0, s15
	s_nop 0
	global_load_lds_dwordx4 v[16:17], off
	s_mov_b32 m0, s9
	s_nop 0
	global_load_lds_dwordx4 v[4:5], off
	s_mov_b32 m0, s13
	s_nop 0
	global_load_lds_dwordx4 v[10:11], off
	s_waitcnt vmcnt(8)
	s_waitcnt lgkmcnt(0)
	s_barrier
	s_waitcnt lgkmcnt(0)
	v_mfma_f32_16x16x32_bf16 v[0:3], v[142:145], v[190:193], v[18:21]
	v_mfma_f32_16x16x32_bf16 v[238:241], v[146:149], v[206:209], v[0:3]
	v_mfma_f32_16x16x32_bf16 v[0:3], v[150:153], v[190:193], v[22:25]
	v_mfma_f32_16x16x32_bf16 v[242:245], v[154:157], v[206:209], v[0:3]
	v_mfma_f32_16x16x32_bf16 v[0:3], v[142:145], v[210:213], v[26:29]
	v_mfma_f32_16x16x32_bf16 v[246:249], v[146:149], v[214:217], v[0:3]
	v_mfma_f32_16x16x32_bf16 v[0:3], v[150:153], v[210:213], v[182:185]
	v_mfma_f32_16x16x32_bf16 v[182:185], v[154:157], v[214:217], v[0:3]
	v_mfma_f32_16x16x32_bf16 v[0:3], v[142:145], v[218:221], v[198:201]
	v_mfma_f32_16x16x32_bf16 v[28:31], v[146:149], v[222:225], v[0:3]
	v_mfma_f32_16x16x32_bf16 v[0:3], v[150:153], v[218:221], v[202:205]
	v_mfma_f32_16x16x32_bf16 v[16:19], v[154:157], v[222:225], v[0:3]
	v_mfma_f32_16x16x32_bf16 v[0:3], v[142:145], v[226:229], v[38:41]
	v_mfma_f32_16x16x32_bf16 v[12:15], v[146:149], v[230:233], v[0:3]
	v_mfma_f32_16x16x32_bf16 v[0:3], v[150:153], v[226:229], v[42:45]
	v_mfma_f32_16x16x32_bf16 v[0:3], v[154:157], v[230:233], v[0:3]
	v_mfma_f32_16x16x32_bf16 v[4:7], v[164:167], v[190:193], v[46:49]
	v_mfma_f32_16x16x32_bf16 v[36:39], v[170:173], v[206:209], v[4:7]
	v_mfma_f32_16x16x32_bf16 v[4:7], v[174:177], v[190:193], v[50:53]
	v_mfma_f32_16x16x32_bf16 v[40:43], v[178:181], v[206:209], v[4:7]
	v_mfma_f32_16x16x32_bf16 v[4:7], v[164:167], v[210:213], v[62:65]
	v_mfma_f32_16x16x32_bf16 v[44:47], v[170:173], v[214:217], v[4:7]
	v_mfma_f32_16x16x32_bf16 v[4:7], v[174:177], v[210:213], v[66:69]
	v_mfma_f32_16x16x32_bf16 v[48:51], v[178:181], v[214:217], v[4:7]
	v_mfma_f32_16x16x32_bf16 v[4:7], v[164:167], v[218:221], v[98:101]
	v_mfma_f32_16x16x32_bf16 v[24:27], v[170:173], v[222:225], v[4:7]
	v_mfma_f32_16x16x32_bf16 v[4:7], v[174:177], v[218:221], v[138:141]
	v_mfma_f32_16x16x32_bf16 v[20:23], v[178:181], v[222:225], v[4:7]
	v_mfma_f32_16x16x32_bf16 v[4:7], v[164:167], v[226:229], v[54:57]
	v_mfma_f32_16x16x32_bf16 v[8:11], v[170:173], v[230:233], v[4:7]
	v_mfma_f32_16x16x32_bf16 v[4:7], v[174:177], v[226:229], v[58:61]
	v_mfma_f32_16x16x32_bf16 v[4:7], v[178:181], v[230:233], v[4:7]
	s_barrier
	v_readlane_b32 vcc_lo, v253, 0
	s_mul_i32 vcc_hi, vcc_lo, 0x1746
	s_lshr_b32 vcc_hi, vcc_hi, 16
	s_mul_i32 s100, vcc_hi, 11
	s_sub_u32 vcc_lo, vcc_lo, s100
	s_mul_i32 s100, vcc_hi, 0x300000
	s_lshr_b32 s101, vcc_lo, 2
	s_lshl_b32 s101, s101, 20
	s_add_u32 s100, s100, s101
	s_and_b32 s101, vcc_lo, 3
	s_lshl_b32 s101, s101, 10
	s_add_u32 s100, s100, s101
	s_lshl_b32 s101, s3, 20
	s_sub_u32 s100, s100, s101
	s_lshl_b32 s101, s2, 10
	s_sub_u32 s100, s100, s101
	s_add_u32 s100, s100, 0x70e2000
	s_load_dwordx2 vcc, s[40:41], 0xf0
	s_waitcnt lgkmcnt(0)
	s_add_u32 vcc_lo, vcc_lo, s100
	s_addc_u32 vcc_hi, vcc_hi, 0
	v_mov_b32_e32 v128, vcc_lo
	v_mov_b32_e32 v129, vcc_hi
	v_lshl_add_u32 v34, s3, 8, v34
	v_lshl_or_b32 v32, s2, 8, v35
	v_or_b32_e32 v32, s5, v32
	v_ashrrev_i32_e32 v35, 31, v34
	v_ashrrev_i32_e32 v33, 31, v32
	v_lshlrev_b64 v[52:53], 12, v[34:35]
	v_lshl_add_u64 v[52:53], v[128:129], 0, v[52:53]
	v_lshlrev_b64 v[54:55], 2, v[32:33]
	v_lshl_add_u64 v[32:33], v[52:53], 0, v[54:55]
	v_pk_mul_f32 v[62:63], v[236:237], 0.5 op_sel_hi:[1,0]
	v_pk_mul_f32 v[60:61], v[234:235], 0.5 op_sel_hi:[1,0]
	global_store_dwordx4 v[32:33], v[60:63], off sc0 sc1
	v_pk_mul_f32 v[66:67], v[104:105], 0.5 op_sel_hi:[1,0]
	v_pk_mul_f32 v[64:65], v[102:103], 0.5 op_sel_hi:[1,0]
	global_store_dwordx4 v[32:33], v[64:67], off offset:64 sc0 sc1
	v_pk_mul_f32 v[62:63], v[136:137], 0.5 op_sel_hi:[1,0]
	v_pk_mul_f32 v[60:61], v[134:135], 0.5 op_sel_hi:[1,0]
	global_store_dwordx4 v[32:33], v[60:63], off offset:512 sc0 sc1
	v_pk_mul_f32 v[66:67], v[72:73], 0.5 op_sel_hi:[1,0]
	v_pk_mul_f32 v[64:65], v[70:71], 0.5 op_sel_hi:[1,0]
	global_store_dwordx4 v[32:33], v[64:67], off offset:576 sc0 sc1
	v_or_b32_e32 v52, 16, v34
	v_ashrrev_i32_e32 v53, 31, v52
	v_lshlrev_b64 v[52:53], 12, v[52:53]
	v_lshl_add_u64 v[52:53], v[128:129], 0, v[52:53]
	v_lshl_add_u64 v[52:53], v[52:53], 0, v[54:55]
	v_pk_mul_f32 v[60:61], v[106:107], 0.5 op_sel_hi:[1,0]
	v_pk_mul_f32 v[62:63], v[108:109], 0.5 op_sel_hi:[1,0]
	global_store_dwordx4 v[52:53], v[60:63], off sc0 sc1
	v_pk_mul_f32 v[64:65], v[110:111], 0.5 op_sel_hi:[1,0]
	v_pk_mul_f32 v[66:67], v[112:113], 0.5 op_sel_hi:[1,0]
	global_store_dwordx4 v[52:53], v[64:67], off offset:64 sc0 sc1
	v_pk_mul_f32 v[60:61], v[74:75], 0.5 op_sel_hi:[1,0]
	v_pk_mul_f32 v[62:63], v[76:77], 0.5 op_sel_hi:[1,0]
	global_store_dwordx4 v[52:53], v[60:63], off offset:512 sc0 sc1
	v_pk_mul_f32 v[64:65], v[78:79], 0.5 op_sel_hi:[1,0]
	v_pk_mul_f32 v[66:67], v[80:81], 0.5 op_sel_hi:[1,0]
	global_store_dwordx4 v[52:53], v[64:67], off offset:576 sc0 sc1
	v_or_b32_e32 v52, 32, v34
	v_ashrrev_i32_e32 v53, 31, v52
	v_lshlrev_b64 v[52:53], 12, v[52:53]
	v_lshl_add_u64 v[52:53], v[128:129], 0, v[52:53]
	v_lshl_add_u64 v[52:53], v[52:53], 0, v[54:55]
	v_pk_mul_f32 v[60:61], v[114:115], 0.5 op_sel_hi:[1,0]
	v_or_b32_e32 v34, 48, v34
	v_pk_mul_f32 v[62:63], v[116:117], 0.5 op_sel_hi:[1,0]
	global_store_dwordx4 v[52:53], v[60:63], off sc0 sc1
	v_pk_mul_f32 v[64:65], v[118:119], 0.5 op_sel_hi:[1,0]
	v_ashrrev_i32_e32 v35, 31, v34
	v_pk_mul_f32 v[66:67], v[120:121], 0.5 op_sel_hi:[1,0]
	global_store_dwordx4 v[52:53], v[64:67], off offset:64 sc0 sc1
	v_pk_mul_f32 v[60:61], v[82:83], 0.5 op_sel_hi:[1,0]
	v_lshlrev_b64 v[34:35], 12, v[34:35]
	v_pk_mul_f32 v[62:63], v[84:85], 0.5 op_sel_hi:[1,0]
	global_store_dwordx4 v[52:53], v[60:63], off offset:512 sc0 sc1
	v_pk_mul_f32 v[64:65], v[86:87], 0.5 op_sel_hi:[1,0]
	v_lshl_add_u64 v[34:35], v[128:129], 0, v[34:35]
	v_pk_mul_f32 v[66:67], v[88:89], 0.5 op_sel_hi:[1,0]
	global_store_dwordx4 v[52:53], v[64:67], off offset:576 sc0 sc1
	v_lshl_add_u64 v[34:35], v[34:35], 0, v[54:55]
	v_pk_mul_f32 v[60:61], v[122:123], 0.5 op_sel_hi:[1,0]
	v_pk_mul_f32 v[62:63], v[124:125], 0.5 op_sel_hi:[1,0]
	global_store_dwordx4 v[34:35], v[60:63], off sc0 sc1
	v_pk_mul_f32 v[64:65], v[130:131], 0.5 op_sel_hi:[1,0]
	v_pk_mul_f32 v[66:67], v[132:133], 0.5 op_sel_hi:[1,0]
	global_store_dwordx4 v[34:35], v[64:67], off offset:64 sc0 sc1
	v_pk_mul_f32 v[60:61], v[90:91], 0.5 op_sel_hi:[1,0]
	v_pk_mul_f32 v[62:63], v[92:93], 0.5 op_sel_hi:[1,0]
	global_store_dwordx4 v[34:35], v[60:63], off offset:512 sc0 sc1
	v_pk_mul_f32 v[64:65], v[94:95], 0.5 op_sel_hi:[1,0]
	v_add_co_u32_e32 v56, vcc, s23, v32
	v_pk_mul_f32 v[66:67], v[96:97], 0.5 op_sel_hi:[1,0]
	global_store_dwordx4 v[34:35], v[64:67], off offset:576 sc0 sc1
	s_mov_b64 s[2:3], 0x80000
	v_pk_mul_f32 v[60:61], v[238:239], 0.5 op_sel_hi:[1,0]
	v_addc_co_u32_e32 v57, vcc, 0, v33, vcc
	v_lshl_add_u64 v[34:35], v[32:33], 0, s[2:3]
	v_pk_mul_f32 v[62:63], v[240:241], 0.5 op_sel_hi:[1,0]
	global_store_dwordx4 v[34:35], v[60:63], off sc0 sc1
	v_pk_mul_f32 v[64:65], v[242:243], 0.5 op_sel_hi:[1,0]
	v_pk_mul_f32 v[66:67], v[244:245], 0.5 op_sel_hi:[1,0]
	global_store_dwordx4 v[34:35], v[64:67], off offset:64 sc0 sc1
	v_pk_mul_f32 v[38:39], v[38:39], 0.5 op_sel_hi:[1,0]
	v_pk_mul_f32 v[36:37], v[36:37], 0.5 op_sel_hi:[1,0]
	global_store_dwordx4 v[34:35], v[36:39], off offset:512 sc0 sc1
	v_pk_mul_f32 v[64:65], v[40:41], 0.5 op_sel_hi:[1,0]
	v_add_co_u32_e32 v40, vcc, s24, v32
	v_pk_mul_f32 v[66:67], v[42:43], 0.5 op_sel_hi:[1,0]
	global_store_dwordx4 v[34:35], v[64:67], off offset:576 sc0 sc1
	s_mov_b64 s[2:3], 0x90000
	v_pk_mul_f32 v[60:61], v[246:247], 0.5 op_sel_hi:[1,0]
	v_addc_co_u32_e32 v41, vcc, 0, v33, vcc
	v_lshl_add_u64 v[34:35], v[32:33], 0, s[2:3]
	v_pk_mul_f32 v[62:63], v[248:249], 0.5 op_sel_hi:[1,0]
	global_store_dwordx4 v[34:35], v[60:63], off sc0 sc1
	v_pk_mul_f32 v[64:65], v[182:183], 0.5 op_sel_hi:[1,0]
	v_pk_mul_f32 v[66:67], v[184:185], 0.5 op_sel_hi:[1,0]
	global_store_dwordx4 v[34:35], v[64:67], off offset:64 sc0 sc1
	v_pk_mul_f32 v[60:61], v[44:45], 0.5 op_sel_hi:[1,0]
	v_pk_mul_f32 v[62:63], v[46:47], 0.5 op_sel_hi:[1,0]
	global_store_dwordx4 v[34:35], v[60:63], off offset:512 sc0 sc1
	v_pk_mul_f32 v[64:65], v[48:49], 0.5 op_sel_hi:[1,0]
	s_mov_b64 s[2:3], 0xa0000
	v_pk_mul_f32 v[66:67], v[50:51], 0.5 op_sel_hi:[1,0]
	global_store_dwordx4 v[34:35], v[64:67], off offset:576 sc0 sc1
	v_lshl_add_u64 v[34:35], v[32:33], 0, s[2:3]
	s_mov_b32 s2, 0xa0000
	v_add_co_u32_e32 v36, vcc, s2, v32
	v_pk_mul_f32 v[28:29], v[28:29], 0.5 op_sel_hi:[1,0]
	s_nop 0
	v_addc_co_u32_e32 v37, vcc, 0, v33, vcc
	v_pk_mul_f32 v[30:31], v[30:31], 0.5 op_sel_hi:[1,0]
	global_store_dwordx4 v[34:35], v[28:31], off sc0 sc1
	v_pk_mul_f32 v[18:19], v[18:19], 0.5 op_sel_hi:[1,0]
	v_pk_mul_f32 v[16:17], v[16:17], 0.5 op_sel_hi:[1,0]
	global_store_dwordx4 v[34:35], v[16:19], off offset:64 sc0 sc1
	v_pk_mul_f32 v[60:61], v[24:25], 0.5 op_sel_hi:[1,0]
	v_pk_mul_f32 v[62:63], v[26:27], 0.5 op_sel_hi:[1,0]
	global_store_dwordx4 v[34:35], v[60:63], off offset:512 sc0 sc1
	v_pk_mul_f32 v[64:65], v[20:21], 0.5 op_sel_hi:[1,0]
	s_mov_b32 s2, 0xb0000
	v_pk_mul_f32 v[66:67], v[22:23], 0.5 op_sel_hi:[1,0]
	global_store_dwordx4 v[34:35], v[64:67], off offset:576 sc0 sc1
	v_add_co_u32_e32 v18, vcc, s2, v32
	v_pk_mul_f32 v[12:13], v[12:13], 0.5 op_sel_hi:[1,0]
	s_nop 0
	v_addc_co_u32_e32 v19, vcc, 0, v33, vcc
	v_lshl_add_u64 v[16:17], v[32:33], 0, s[28:29]
	v_pk_mul_f32 v[14:15], v[14:15], 0.5 op_sel_hi:[1,0]
	global_store_dwordx4 v[16:17], v[12:15], off sc0 sc1
	v_pk_mul_f32 v[2:3], v[2:3], 0.5 op_sel_hi:[1,0]
	v_pk_mul_f32 v[0:1], v[0:1], 0.5 op_sel_hi:[1,0]
	global_store_dwordx4 v[16:17], v[0:3], off offset:64 sc0 sc1
	v_pk_mul_f32 v[60:61], v[8:9], 0.5 op_sel_hi:[1,0]
	v_pk_mul_f32 v[62:63], v[10:11], 0.5 op_sel_hi:[1,0]
	global_store_dwordx4 v[16:17], v[60:63], off offset:512 sc0 sc1
	v_pk_mul_f32 v[64:65], v[4:5], 0.5 op_sel_hi:[1,0]
	v_pk_mul_f32 v[66:67], v[6:7], 0.5 op_sel_hi:[1,0]
	global_store_dwordx4 v[16:17], v[64:67], off offset:576 sc0 sc1
	s_waitcnt vmcnt(0)
	s_cmpk_gt_u32 s4, 0xff
	s_cbranch_scc1 .LBB0_281
	s_barrier

.LBB0_434:
	s_cmp_eq_u32 s11, 12
	s_cselect_b64 vcc, -1, 0
	s_add_i32 s13, s33, 0x100
	s_add_i32 s14, s92, 0x100
	v_lshl_add_u64 v[164:165], v[154:155], 0, s[44:45]
	v_add_u32_e32 v178, s13, v157
	v_add_u32_e32 v202, s14, v157
	v_cndmask_b32_e32 v187, v165, v149, vcc
	v_cndmask_b32_e32 v186, v164, v148, vcc
	ds_read_b128 v[164:167], v178
	ds_read_b128 v[170:173], v178 offset:1024
	ds_read_b128 v[174:177], v178 offset:2048
	ds_read_b128 v[178:181], v178 offset:3072
	ds_read_b128 v[182:185], v202
	ds_read_b128 v[190:193], v202 offset:1024
	ds_read_b128 v[198:201], v202 offset:2048
	ds_read_b128 v[202:205], v202 offset:3072
	v_cndmask_b32_e32 v239, v153, v151, vcc
	v_cndmask_b32_e32 v238, v152, v150, vcc
	v_lshl_add_u64 v[240:241], v[154:155], 0, v[142:143]
	s_add_i32 m0, s9, 0xc000
	ds_read_b128 v[206:209], v159
	ds_read_b128 v[210:213], v159 offset:1024
	ds_read_b128 v[214:217], v159 offset:2048
	ds_read_b128 v[218:221], v159 offset:3072
	ds_read_b128 v[222:225], v159 offset:4096
	ds_read_b128 v[226:229], v159 offset:5120
	ds_read_b128 v[230:233], v159 offset:6144
	ds_read_b128 v[234:237], v159 offset:7168
	global_load_lds_dwordx4 v[240:241], off
	v_lshl_add_u64 v[240:241], v[154:155], 0, v[140:141]
	s_add_i32 m0, s9, 0xe000
	s_nop 0
	global_load_lds_dwordx4 v[240:241], off
	s_waitcnt vmcnt(8)
	s_waitcnt lgkmcnt(0)
	s_barrier
	s_waitcnt lgkmcnt(0)
	v_mfma_f32_16x16x32_bf16 v[124:127], v[164:167], v[206:209], v[124:127]
	v_mfma_f32_16x16x32_bf16 v[120:123], v[174:177], v[206:209], v[120:123]
	v_mfma_f32_16x16x32_bf16 v[116:119], v[164:167], v[214:217], v[116:119]
	v_mfma_f32_16x16x32_bf16 v[112:115], v[174:177], v[214:217], v[112:115]
	v_mfma_f32_16x16x32_bf16 v[100:103], v[164:167], v[222:225], v[100:103]
	v_mfma_f32_16x16x32_bf16 v[96:99], v[174:177], v[222:225], v[96:99]
	v_mfma_f32_16x16x32_bf16 v[84:87], v[164:167], v[230:233], v[84:87]
	v_mfma_f32_16x16x32_bf16 v[80:83], v[174:177], v[230:233], v[80:83]
	v_mfma_f32_16x16x32_bf16 v[124:127], v[170:173], v[210:213], v[124:127]
	v_mfma_f32_16x16x32_bf16 v[120:123], v[178:181], v[210:213], v[120:123]
	v_mfma_f32_16x16x32_bf16 v[116:119], v[170:173], v[218:221], v[116:119]
	v_mfma_f32_16x16x32_bf16 v[112:115], v[178:181], v[218:221], v[112:115]
	v_mfma_f32_16x16x32_bf16 v[100:103], v[170:173], v[226:229], v[100:103]
	v_mfma_f32_16x16x32_bf16 v[96:99], v[178:181], v[226:229], v[96:99]
	v_mfma_f32_16x16x32_bf16 v[84:87], v[170:173], v[234:237], v[84:87]
	v_mfma_f32_16x16x32_bf16 v[80:83], v[178:181], v[234:237], v[80:83]
	v_mfma_f32_16x16x32_bf16 v[108:111], v[182:185], v[206:209], v[108:111]
	v_mfma_f32_16x16x32_bf16 v[104:107], v[198:201], v[206:209], v[104:107]
	v_mfma_f32_16x16x32_bf16 v[92:95], v[182:185], v[214:217], v[92:95]
	v_mfma_f32_16x16x32_bf16 v[88:91], v[198:201], v[214:217], v[88:91]
	v_mfma_f32_16x16x32_bf16 v[76:79], v[182:185], v[222:225], v[76:79]
	v_mfma_f32_16x16x32_bf16 v[72:75], v[198:201], v[222:225], v[72:75]
	v_mfma_f32_16x16x32_bf16 v[68:71], v[182:185], v[230:233], v[68:71]
	v_mfma_f32_16x16x32_bf16 v[64:67], v[198:201], v[230:233], v[64:67]
	v_mfma_f32_16x16x32_bf16 v[108:111], v[190:193], v[210:213], v[108:111]
	v_mfma_f32_16x16x32_bf16 v[104:107], v[202:205], v[210:213], v[104:107]
	v_mfma_f32_16x16x32_bf16 v[92:95], v[190:193], v[218:221], v[92:95]
	v_mfma_f32_16x16x32_bf16 v[88:91], v[202:205], v[218:221], v[88:91]
	v_mfma_f32_16x16x32_bf16 v[76:79], v[190:193], v[226:229], v[76:79]
	v_mfma_f32_16x16x32_bf16 v[72:75], v[202:205], v[226:229], v[72:75]
	v_mfma_f32_16x16x32_bf16 v[68:71], v[190:193], v[234:237], v[68:71]
	v_mfma_f32_16x16x32_bf16 v[64:67], v[202:205], v[234:237], v[64:67]
	s_barrier
	s_add_i32 s13, s13, s19
	v_lshl_add_u64 v[240:241], v[238:239], 0, v[162:163]
	s_mov_b32 m0, s13
	ds_read_b128 v[206:209], v159 offset:16384
	ds_read_b128 v[210:213], v159 offset:17408
	ds_read_b128 v[214:217], v159 offset:18432
	ds_read_b128 v[218:221], v159 offset:19456
	ds_read_b128 v[222:225], v159 offset:20480
	ds_read_b128 v[226:229], v159 offset:21504
	ds_read_b128 v[230:233], v159 offset:22528
	ds_read_b128 v[234:237], v159 offset:23552
	global_load_lds_dwordx4 v[240:241], off
	v_lshl_add_u64 v[242:243], v[238:239], 0, v[136:137]
	s_add_i32 m0, s13, 0x2000
	v_lshl_add_u64 v[244:245], v[238:239], 0, s[78:79]
	s_add_i32 s13, s14, s19
	global_load_lds_dwordx4 v[242:243], off
	v_lshl_add_u64 v[246:247], v[244:245], 0, v[162:163]
	s_mov_b32 m0, s13
	v_lshl_add_u64 v[244:245], v[244:245], 0, v[136:137]
	global_load_lds_dwordx4 v[246:247], off
	s_add_i32 m0, s13, 0x2000
	v_lshl_add_u64 v[246:247], v[186:187], 0, v[134:135]
	global_load_lds_dwordx4 v[244:245], off
	v_lshl_add_u64 v[244:245], v[186:187], 0, v[132:133]
	s_mov_b32 m0, s9
	s_nop 0
	global_load_lds_dwordx4 v[244:245], off
	s_mov_b32 m0, s20
	s_nop 0
	global_load_lds_dwordx4 v[246:247], off
	s_waitcnt vmcnt(8)
	s_waitcnt lgkmcnt(0)
	s_barrier
	s_waitcnt lgkmcnt(0)
	v_mfma_f32_16x16x32_bf16 v[60:63], v[164:167], v[206:209], v[60:63]
	v_mfma_f32_16x16x32_bf16 v[56:59], v[174:177], v[206:209], v[56:59]
	v_mfma_f32_16x16x32_bf16 v[52:55], v[164:167], v[214:217], v[52:55]
	v_mfma_f32_16x16x32_bf16 v[48:51], v[174:177], v[214:217], v[48:51]
	v_mfma_f32_16x16x32_bf16 v[36:39], v[164:167], v[222:225], v[36:39]
	v_mfma_f32_16x16x32_bf16 v[32:35], v[174:177], v[222:225], v[32:35]
	v_mfma_f32_16x16x32_bf16 v[20:23], v[164:167], v[230:233], v[20:23]
	v_mfma_f32_16x16x32_bf16 v[16:19], v[174:177], v[230:233], v[16:19]
	v_mfma_f32_16x16x32_bf16 v[60:63], v[170:173], v[210:213], v[60:63]
	v_mfma_f32_16x16x32_bf16 v[56:59], v[178:181], v[210:213], v[56:59]
	v_mfma_f32_16x16x32_bf16 v[52:55], v[170:173], v[218:221], v[52:55]
	v_mfma_f32_16x16x32_bf16 v[48:51], v[178:181], v[218:221], v[48:51]
	v_mfma_f32_16x16x32_bf16 v[36:39], v[170:173], v[226:229], v[36:39]
	v_mfma_f32_16x16x32_bf16 v[32:35], v[178:181], v[226:229], v[32:35]
	v_mfma_f32_16x16x32_bf16 v[20:23], v[170:173], v[234:237], v[20:23]
	v_mfma_f32_16x16x32_bf16 v[16:19], v[178:181], v[234:237], v[16:19]
	v_mfma_f32_16x16x32_bf16 v[44:47], v[182:185], v[206:209], v[44:47]
	v_mfma_f32_16x16x32_bf16 v[40:43], v[198:201], v[206:209], v[40:43]
	v_mfma_f32_16x16x32_bf16 v[28:31], v[182:185], v[214:217], v[28:31]
	v_mfma_f32_16x16x32_bf16 v[24:27], v[198:201], v[214:217], v[24:27]
	v_mfma_f32_16x16x32_bf16 v[12:15], v[182:185], v[222:225], v[12:15]
	v_mfma_f32_16x16x32_bf16 v[8:11], v[198:201], v[222:225], v[8:11]
	v_mfma_f32_16x16x32_bf16 v[4:7], v[182:185], v[230:233], v[4:7]
	v_mfma_f32_16x16x32_bf16 v[0:3], v[198:201], v[230:233], v[0:3]
	v_mfma_f32_16x16x32_bf16 v[44:47], v[190:193], v[210:213], v[44:47]
	v_mfma_f32_16x16x32_bf16 v[40:43], v[202:205], v[210:213], v[40:43]
	v_mfma_f32_16x16x32_bf16 v[28:31], v[190:193], v[218:221], v[28:31]
	v_mfma_f32_16x16x32_bf16 v[24:27], v[202:205], v[218:221], v[24:27]
	v_mfma_f32_16x16x32_bf16 v[12:15], v[190:193], v[226:229], v[12:15]
	v_mfma_f32_16x16x32_bf16 v[8:11], v[202:205], v[226:229], v[8:11]
	v_mfma_f32_16x16x32_bf16 v[4:7], v[190:193], v[234:237], v[4:7]
	v_mfma_f32_16x16x32_bf16 v[0:3], v[202:205], v[234:237], v[0:3]
	s_barrier
	s_add_i32 s13, s93, 0x100
	s_add_i32 s14, s82, 0x100
	v_add_u32_e32 v178, s13, v157
	v_add_u32_e32 v202, s14, v157
	ds_read_b128 v[164:167], v178
	ds_read_b128 v[170:173], v178 offset:1024
	ds_read_b128 v[174:177], v178 offset:2048
	ds_read_b128 v[178:181], v178 offset:3072
	ds_read_b128 v[182:185], v202
	ds_read_b128 v[190:193], v202 offset:1024
	ds_read_b128 v[198:201], v202 offset:2048
	ds_read_b128 v[202:205], v202 offset:3072
	v_lshl_add_u64 v[186:187], v[186:187], 0, s[78:79]
	s_mov_b32 m0, s21
	v_lshl_add_u64 v[248:249], v[186:187], 0, v[132:133]
	ds_read_b128 v[206:209], v159 offset:32768
	ds_read_b128 v[210:213], v159 offset:33792
	ds_read_b128 v[214:217], v159 offset:34816
	ds_read_b128 v[218:221], v159 offset:35840
	ds_read_b128 v[222:225], v159 offset:36864
	ds_read_b128 v[226:229], v159 offset:37888
	ds_read_b128 v[230:233], v159 offset:38912
	ds_read_b128 v[234:237], v159 offset:39936
	global_load_lds_dwordx4 v[248:249], off
	v_lshl_add_u64 v[186:187], v[186:187], 0, v[134:135]
	s_mov_b32 m0, s22
	s_nop 0
	global_load_lds_dwordx4 v[186:187], off
	s_waitcnt vmcnt(8)
	s_waitcnt lgkmcnt(0)
	s_barrier
	s_waitcnt lgkmcnt(0)
	v_mfma_f32_16x16x32_bf16 v[124:127], v[164:167], v[206:209], v[124:127]
	v_mfma_f32_16x16x32_bf16 v[120:123], v[174:177], v[206:209], v[120:123]
	v_mfma_f32_16x16x32_bf16 v[116:119], v[164:167], v[214:217], v[116:119]
	v_mfma_f32_16x16x32_bf16 v[112:115], v[174:177], v[214:217], v[112:115]
	v_mfma_f32_16x16x32_bf16 v[100:103], v[164:167], v[222:225], v[100:103]
	v_mfma_f32_16x16x32_bf16 v[96:99], v[174:177], v[222:225], v[96:99]
	v_mfma_f32_16x16x32_bf16 v[84:87], v[164:167], v[230:233], v[84:87]
	v_mfma_f32_16x16x32_bf16 v[80:83], v[174:177], v[230:233], v[80:83]
	v_mfma_f32_16x16x32_bf16 v[124:127], v[170:173], v[210:213], v[124:127]
	v_mfma_f32_16x16x32_bf16 v[120:123], v[178:181], v[210:213], v[120:123]
	v_mfma_f32_16x16x32_bf16 v[116:119], v[170:173], v[218:221], v[116:119]
	v_mfma_f32_16x16x32_bf16 v[112:115], v[178:181], v[218:221], v[112:115]
	v_mfma_f32_16x16x32_bf16 v[100:103], v[170:173], v[226:229], v[100:103]
	v_mfma_f32_16x16x32_bf16 v[96:99], v[178:181], v[226:229], v[96:99]
	v_mfma_f32_16x16x32_bf16 v[84:87], v[170:173], v[234:237], v[84:87]
	v_mfma_f32_16x16x32_bf16 v[80:83], v[178:181], v[234:237], v[80:83]
	v_mfma_f32_16x16x32_bf16 v[108:111], v[182:185], v[206:209], v[108:111]
	v_mfma_f32_16x16x32_bf16 v[104:107], v[198:201], v[206:209], v[104:107]
	v_mfma_f32_16x16x32_bf16 v[92:95], v[182:185], v[214:217], v[92:95]
	v_mfma_f32_16x16x32_bf16 v[88:91], v[198:201], v[214:217], v[88:91]
	v_mfma_f32_16x16x32_bf16 v[76:79], v[182:185], v[222:225], v[76:79]
	v_mfma_f32_16x16x32_bf16 v[72:75], v[198:201], v[222:225], v[72:75]
	v_mfma_f32_16x16x32_bf16 v[68:71], v[182:185], v[230:233], v[68:71]
	v_mfma_f32_16x16x32_bf16 v[64:67], v[198:201], v[230:233], v[64:67]
	v_mfma_f32_16x16x32_bf16 v[108:111], v[190:193], v[210:213], v[108:111]
	v_mfma_f32_16x16x32_bf16 v[104:107], v[202:205], v[210:213], v[104:107]
	v_mfma_f32_16x16x32_bf16 v[92:95], v[190:193], v[218:221], v[92:95]
	v_mfma_f32_16x16x32_bf16 v[88:91], v[202:205], v[218:221], v[88:91]
	v_mfma_f32_16x16x32_bf16 v[76:79], v[190:193], v[226:229], v[76:79]
	v_mfma_f32_16x16x32_bf16 v[72:75], v[202:205], v[226:229], v[72:75]
	v_mfma_f32_16x16x32_bf16 v[68:71], v[190:193], v[234:237], v[68:71]
	v_mfma_f32_16x16x32_bf16 v[64:67], v[202:205], v[234:237], v[64:67]
	s_barrier
	s_add_i32 s13, s13, s19
	v_lshl_add_u64 v[186:187], v[240:241], 0, s[84:85]
	s_mov_b32 m0, s13
	ds_read_b128 v[206:209], v159 offset:49152
	ds_read_b128 v[210:213], v159 offset:50176
	ds_read_b128 v[214:217], v159 offset:51200
	ds_read_b128 v[218:221], v159 offset:52224
	ds_read_b128 v[222:225], v159 offset:53248
	ds_read_b128 v[226:229], v159 offset:54272
	ds_read_b128 v[230:233], v159 offset:55296
	ds_read_b128 v[234:237], v159 offset:56320
	global_load_lds_dwordx4 v[186:187], off
	v_lshl_add_u64 v[186:187], v[242:243], 0, s[84:85]
	s_add_i32 m0, s13, 0x2000
	s_add_i32 s13, s14, s19
	global_load_lds_dwordx4 v[186:187], off
	v_lshl_add_u64 v[186:187], v[238:239], 0, s[86:87]
	v_lshl_add_u64 v[238:239], v[186:187], 0, v[162:163]
	s_mov_b32 m0, s13
	v_lshl_add_u64 v[186:187], v[186:187], 0, v[136:137]
	global_load_lds_dwordx4 v[238:239], off
	s_add_i32 m0, s13, 0x2000
	s_nop 0
	global_load_lds_dwordx4 v[186:187], off
	v_lshl_add_u64 v[186:187], v[244:245], 0, s[84:85]
	s_mov_b32 m0, s23
	s_nop 0
	global_load_lds_dwordx4 v[186:187], off
	v_lshl_add_u64 v[186:187], v[246:247], 0, s[84:85]
	s_mov_b32 m0, s24
	s_nop 0
	global_load_lds_dwordx4 v[186:187], off
	s_waitcnt vmcnt(8)
	s_waitcnt lgkmcnt(0)
	s_barrier
	s_waitcnt lgkmcnt(0)
	v_mfma_f32_16x16x32_bf16 v[60:63], v[164:167], v[206:209], v[60:63]
	v_mfma_f32_16x16x32_bf16 v[56:59], v[174:177], v[206:209], v[56:59]
	v_mfma_f32_16x16x32_bf16 v[52:55], v[164:167], v[214:217], v[52:55]
	v_mfma_f32_16x16x32_bf16 v[48:51], v[174:177], v[214:217], v[48:51]
	v_mfma_f32_16x16x32_bf16 v[36:39], v[164:167], v[222:225], v[36:39]
	v_mfma_f32_16x16x32_bf16 v[32:35], v[174:177], v[222:225], v[32:35]
	v_mfma_f32_16x16x32_bf16 v[20:23], v[164:167], v[230:233], v[20:23]
	v_mfma_f32_16x16x32_bf16 v[16:19], v[174:177], v[230:233], v[16:19]
	v_mfma_f32_16x16x32_bf16 v[60:63], v[170:173], v[210:213], v[60:63]
	v_mfma_f32_16x16x32_bf16 v[56:59], v[178:181], v[210:213], v[56:59]
	v_mfma_f32_16x16x32_bf16 v[52:55], v[170:173], v[218:221], v[52:55]
	v_mfma_f32_16x16x32_bf16 v[48:51], v[178:181], v[218:221], v[48:51]
	v_mfma_f32_16x16x32_bf16 v[36:39], v[170:173], v[226:229], v[36:39]
	v_mfma_f32_16x16x32_bf16 v[32:35], v[178:181], v[226:229], v[32:35]
	v_mfma_f32_16x16x32_bf16 v[20:23], v[170:173], v[234:237], v[20:23]
	v_mfma_f32_16x16x32_bf16 v[16:19], v[178:181], v[234:237], v[16:19]
	v_mfma_f32_16x16x32_bf16 v[44:47], v[182:185], v[206:209], v[44:47]
	v_mfma_f32_16x16x32_bf16 v[40:43], v[198:201], v[206:209], v[40:43]
	v_mfma_f32_16x16x32_bf16 v[28:31], v[182:185], v[214:217], v[28:31]
	v_mfma_f32_16x16x32_bf16 v[24:27], v[198:201], v[214:217], v[24:27]
	v_mfma_f32_16x16x32_bf16 v[12:15], v[182:185], v[222:225], v[12:15]
	v_mfma_f32_16x16x32_bf16 v[8:11], v[198:201], v[222:225], v[8:11]
	v_mfma_f32_16x16x32_bf16 v[4:7], v[182:185], v[230:233], v[4:7]
	v_mfma_f32_16x16x32_bf16 v[0:3], v[198:201], v[230:233], v[0:3]
	v_mfma_f32_16x16x32_bf16 v[44:47], v[190:193], v[210:213], v[44:47]
	v_mfma_f32_16x16x32_bf16 v[40:43], v[202:205], v[210:213], v[40:43]
	v_mfma_f32_16x16x32_bf16 v[28:31], v[190:193], v[218:221], v[28:31]
	v_mfma_f32_16x16x32_bf16 v[24:27], v[202:205], v[218:221], v[24:27]
	v_mfma_f32_16x16x32_bf16 v[12:15], v[190:193], v[226:229], v[12:15]
	v_mfma_f32_16x16x32_bf16 v[8:11], v[202:205], v[226:229], v[8:11]
	v_mfma_f32_16x16x32_bf16 v[4:7], v[190:193], v[234:237], v[4:7]
	v_mfma_f32_16x16x32_bf16 v[0:3], v[202:205], v[234:237], v[0:3]
	s_barrier
	s_add_i32 s11, s11, 2
	v_lshl_add_u64 v[152:153], v[152:153], 0, s[0:1]
	s_cmp_gt_u32 s11, 13
	v_lshl_add_u64 v[154:155], v[154:155], 0, s[0:1]
	s_cbranch_scc0 .LBB0_434
	s_and_b64 vcc, exec, s[6:7]
	s_cbranch_vccz .LBB0_437
	s_barrier

.LBB0_1465:
	s_cmp_eq_u32 s11, 4
	s_mov_b32 s14, 0xfffe0080
	s_mov_b32 s15, -1
	s_cselect_b64 vcc, -1, 0
	s_add_i32 s13, s33, 0x100
	v_lshl_add_u64 v[158:159], v[156:157], 0, s[14:15]
	v_add_u32_e32 v170, s13, v173
	s_add_i32 s14, s92, 0x100
	ds_read_b128 v[164:167], v170
	ds_read_b128 v[176:179], v170 offset:1024
	ds_read_b128 v[180:183], v170 offset:2048
	ds_read_b128 v[184:187], v170 offset:3072
	v_add_u32_e32 v170, s14, v173
	ds_read_b128 v[190:193], v170
	ds_read_b128 v[198:201], v170 offset:1024
	ds_read_b128 v[202:205], v170 offset:2048
	ds_read_b128 v[206:209], v170 offset:3072
	v_cndmask_b32_e32 v159, v159, v151, vcc
	v_cndmask_b32_e32 v158, v158, v150, vcc
	v_cndmask_b32_e32 v171, v155, v153, vcc
	v_cndmask_b32_e32 v170, v154, v152, vcc
	v_lshl_add_u64 v[242:243], v[156:157], 0, v[144:145]
	s_add_i32 m0, s20, 0xc000
	ds_read_b128 v[210:213], v175
	ds_read_b128 v[214:217], v175 offset:1024
	ds_read_b128 v[218:221], v175 offset:2048
	ds_read_b128 v[222:225], v175 offset:3072
	ds_read_b128 v[226:229], v175 offset:4096
	ds_read_b128 v[230:233], v175 offset:5120
	ds_read_b128 v[234:237], v175 offset:6144
	ds_read_b128 v[238:241], v175 offset:7168
	global_load_lds_dwordx4 v[242:243], off
	v_lshl_add_u64 v[242:243], v[156:157], 0, v[142:143]
	s_add_i32 m0, s20, 0xe000
	s_nop 0
	global_load_lds_dwordx4 v[242:243], off
	s_waitcnt vmcnt(8)
	s_waitcnt lgkmcnt(0)
	s_barrier
	s_waitcnt lgkmcnt(0)
	v_mfma_f32_16x16x32_bf16 v[124:127], v[164:167], v[210:213], v[124:127]
	v_mfma_f32_16x16x32_bf16 v[120:123], v[180:183], v[210:213], v[120:123]
	v_mfma_f32_16x16x32_bf16 v[108:111], v[164:167], v[218:221], v[108:111]
	v_mfma_f32_16x16x32_bf16 v[104:107], v[180:183], v[218:221], v[104:107]
	v_mfma_f32_16x16x32_bf16 v[92:95], v[164:167], v[226:229], v[92:95]
	v_mfma_f32_16x16x32_bf16 v[88:91], v[180:183], v[226:229], v[88:91]
	v_mfma_f32_16x16x32_bf16 v[76:79], v[164:167], v[234:237], v[76:79]
	v_mfma_f32_16x16x32_bf16 v[72:75], v[180:183], v[234:237], v[72:75]
	v_mfma_f32_16x16x32_bf16 v[124:127], v[176:179], v[214:217], v[124:127]
	v_mfma_f32_16x16x32_bf16 v[120:123], v[184:187], v[214:217], v[120:123]
	v_mfma_f32_16x16x32_bf16 v[108:111], v[176:179], v[222:225], v[108:111]
	v_mfma_f32_16x16x32_bf16 v[104:107], v[184:187], v[222:225], v[104:107]
	v_mfma_f32_16x16x32_bf16 v[92:95], v[176:179], v[230:233], v[92:95]
	v_mfma_f32_16x16x32_bf16 v[88:91], v[184:187], v[230:233], v[88:91]
	v_mfma_f32_16x16x32_bf16 v[76:79], v[176:179], v[238:241], v[76:79]
	v_mfma_f32_16x16x32_bf16 v[72:75], v[184:187], v[238:241], v[72:75]
	v_mfma_f32_16x16x32_bf16 v[116:119], v[190:193], v[210:213], v[116:119]
	v_mfma_f32_16x16x32_bf16 v[112:115], v[202:205], v[210:213], v[112:115]
	v_mfma_f32_16x16x32_bf16 v[100:103], v[190:193], v[218:221], v[100:103]
	v_mfma_f32_16x16x32_bf16 v[96:99], v[202:205], v[218:221], v[96:99]
	v_mfma_f32_16x16x32_bf16 v[84:87], v[190:193], v[226:229], v[84:87]
	v_mfma_f32_16x16x32_bf16 v[80:83], v[202:205], v[226:229], v[80:83]
	v_mfma_f32_16x16x32_bf16 v[68:71], v[190:193], v[234:237], v[68:71]
	v_mfma_f32_16x16x32_bf16 v[64:67], v[202:205], v[234:237], v[64:67]
	v_mfma_f32_16x16x32_bf16 v[116:119], v[198:201], v[214:217], v[116:119]
	v_mfma_f32_16x16x32_bf16 v[112:115], v[206:209], v[214:217], v[112:115]
	v_mfma_f32_16x16x32_bf16 v[100:103], v[198:201], v[222:225], v[100:103]
	v_mfma_f32_16x16x32_bf16 v[96:99], v[206:209], v[222:225], v[96:99]
	v_mfma_f32_16x16x32_bf16 v[84:87], v[198:201], v[230:233], v[84:87]
	v_mfma_f32_16x16x32_bf16 v[80:83], v[206:209], v[230:233], v[80:83]
	v_mfma_f32_16x16x32_bf16 v[68:71], v[198:201], v[238:241], v[68:71]
	v_mfma_f32_16x16x32_bf16 v[64:67], v[206:209], v[238:241], v[64:67]
	s_barrier
	s_add_i32 s13, s13, s19
	v_lshl_add_u64 v[242:243], v[170:171], 0, v[162:163]
	s_mov_b32 m0, s13
	ds_read_b128 v[210:213], v175 offset:16384
	ds_read_b128 v[214:217], v175 offset:17408
	ds_read_b128 v[218:221], v175 offset:18432
	ds_read_b128 v[222:225], v175 offset:19456
	ds_read_b128 v[226:229], v175 offset:20480
	ds_read_b128 v[230:233], v175 offset:21504
	ds_read_b128 v[234:237], v175 offset:22528
	ds_read_b128 v[238:241], v175 offset:23552
	global_load_lds_dwordx4 v[242:243], off
	v_lshl_add_u64 v[244:245], v[170:171], 0, v[136:137]
	s_add_i32 m0, s13, 0x2000
	v_lshl_add_u64 v[246:247], v[170:171], 0, s[34:35]
	s_add_i32 s13, s14, s19
	global_load_lds_dwordx4 v[244:245], off
	v_lshl_add_u64 v[248:249], v[246:247], 0, v[162:163]
	s_mov_b32 m0, s13
	v_lshl_add_u64 v[246:247], v[246:247], 0, v[136:137]
	global_load_lds_dwordx4 v[248:249], off
	s_add_i32 m0, s13, 0x2000
	v_lshl_add_u64 v[248:249], v[158:159], 0, v[134:135]
	global_load_lds_dwordx4 v[246:247], off
	v_lshl_add_u64 v[246:247], v[158:159], 0, v[132:133]
	s_mov_b32 m0, s20
	s_nop 0
	global_load_lds_dwordx4 v[246:247], off
	s_mov_b32 m0, s21
	s_nop 0
	global_load_lds_dwordx4 v[248:249], off
	s_waitcnt vmcnt(8)
	s_waitcnt lgkmcnt(0)
	s_barrier
	s_waitcnt lgkmcnt(0)
	v_mfma_f32_16x16x32_bf16 v[60:63], v[164:167], v[210:213], v[60:63]
	v_mfma_f32_16x16x32_bf16 v[56:59], v[180:183], v[210:213], v[56:59]
	v_mfma_f32_16x16x32_bf16 v[44:47], v[164:167], v[218:221], v[44:47]
	v_mfma_f32_16x16x32_bf16 v[40:43], v[180:183], v[218:221], v[40:43]
	v_mfma_f32_16x16x32_bf16 v[28:31], v[164:167], v[226:229], v[28:31]
	v_mfma_f32_16x16x32_bf16 v[24:27], v[180:183], v[226:229], v[24:27]
	v_mfma_f32_16x16x32_bf16 v[12:15], v[164:167], v[234:237], v[12:15]
	v_mfma_f32_16x16x32_bf16 v[8:11], v[180:183], v[234:237], v[8:11]
	v_mfma_f32_16x16x32_bf16 v[60:63], v[176:179], v[214:217], v[60:63]
	v_mfma_f32_16x16x32_bf16 v[56:59], v[184:187], v[214:217], v[56:59]
	v_mfma_f32_16x16x32_bf16 v[44:47], v[176:179], v[222:225], v[44:47]
	v_mfma_f32_16x16x32_bf16 v[40:43], v[184:187], v[222:225], v[40:43]
	v_mfma_f32_16x16x32_bf16 v[28:31], v[176:179], v[230:233], v[28:31]
	v_mfma_f32_16x16x32_bf16 v[24:27], v[184:187], v[230:233], v[24:27]
	v_mfma_f32_16x16x32_bf16 v[12:15], v[176:179], v[238:241], v[12:15]
	v_mfma_f32_16x16x32_bf16 v[8:11], v[184:187], v[238:241], v[8:11]
	v_mfma_f32_16x16x32_bf16 v[52:55], v[190:193], v[210:213], v[52:55]
	v_mfma_f32_16x16x32_bf16 v[48:51], v[202:205], v[210:213], v[48:51]
	v_mfma_f32_16x16x32_bf16 v[36:39], v[190:193], v[218:221], v[36:39]
	v_mfma_f32_16x16x32_bf16 v[32:35], v[202:205], v[218:221], v[32:35]
	v_mfma_f32_16x16x32_bf16 v[20:23], v[190:193], v[226:229], v[20:23]
	v_mfma_f32_16x16x32_bf16 v[16:19], v[202:205], v[226:229], v[16:19]
	v_mfma_f32_16x16x32_bf16 v[4:7], v[190:193], v[234:237], v[4:7]
	v_mfma_f32_16x16x32_bf16 v[0:3], v[202:205], v[234:237], v[0:3]
	v_mfma_f32_16x16x32_bf16 v[52:55], v[198:201], v[214:217], v[52:55]
	v_mfma_f32_16x16x32_bf16 v[48:51], v[206:209], v[214:217], v[48:51]
	v_mfma_f32_16x16x32_bf16 v[36:39], v[198:201], v[222:225], v[36:39]
	v_mfma_f32_16x16x32_bf16 v[32:35], v[206:209], v[222:225], v[32:35]
	v_mfma_f32_16x16x32_bf16 v[20:23], v[198:201], v[230:233], v[20:23]
	v_mfma_f32_16x16x32_bf16 v[16:19], v[206:209], v[230:233], v[16:19]
	v_mfma_f32_16x16x32_bf16 v[4:7], v[198:201], v[238:241], v[4:7]
	v_mfma_f32_16x16x32_bf16 v[0:3], v[206:209], v[238:241], v[0:3]
	s_barrier
	s_add_i32 s13, s93, 0x100
	s_add_i32 s14, s82, 0x100
	v_add_u32_e32 v184, s13, v173
	v_add_u32_e32 v206, s14, v173
	ds_read_b128 v[164:167], v184
	ds_read_b128 v[176:179], v184 offset:1024
	ds_read_b128 v[180:183], v184 offset:2048
	ds_read_b128 v[184:187], v184 offset:3072
	ds_read_b128 v[190:193], v206
	ds_read_b128 v[198:201], v206 offset:1024
	ds_read_b128 v[202:205], v206 offset:2048
	ds_read_b128 v[206:209], v206 offset:3072
	v_lshl_add_u64 v[158:159], v[158:159], 0, s[34:35]
	s_mov_b32 m0, s22
	v_lshl_add_u64 v[250:251], v[158:159], 0, v[132:133]
	ds_read_b128 v[210:213], v175 offset:32768
	ds_read_b128 v[214:217], v175 offset:33792
	ds_read_b128 v[218:221], v175 offset:34816
	ds_read_b128 v[222:225], v175 offset:35840
	ds_read_b128 v[226:229], v175 offset:36864
	ds_read_b128 v[230:233], v175 offset:37888
	ds_read_b128 v[234:237], v175 offset:38912
	ds_read_b128 v[238:241], v175 offset:39936
	global_load_lds_dwordx4 v[250:251], off
	v_lshl_add_u64 v[158:159], v[158:159], 0, v[134:135]
	s_mov_b32 m0, s23
	s_nop 0
	global_load_lds_dwordx4 v[158:159], off
	s_waitcnt vmcnt(8)
	s_waitcnt lgkmcnt(0)
	s_barrier
	s_waitcnt lgkmcnt(0)
	v_mfma_f32_16x16x32_bf16 v[124:127], v[164:167], v[210:213], v[124:127]
	v_mfma_f32_16x16x32_bf16 v[120:123], v[180:183], v[210:213], v[120:123]
	v_mfma_f32_16x16x32_bf16 v[108:111], v[164:167], v[218:221], v[108:111]
	v_mfma_f32_16x16x32_bf16 v[104:107], v[180:183], v[218:221], v[104:107]
	v_mfma_f32_16x16x32_bf16 v[92:95], v[164:167], v[226:229], v[92:95]
	v_mfma_f32_16x16x32_bf16 v[88:91], v[180:183], v[226:229], v[88:91]
	v_mfma_f32_16x16x32_bf16 v[76:79], v[164:167], v[234:237], v[76:79]
	v_mfma_f32_16x16x32_bf16 v[72:75], v[180:183], v[234:237], v[72:75]
	v_mfma_f32_16x16x32_bf16 v[124:127], v[176:179], v[214:217], v[124:127]
	v_mfma_f32_16x16x32_bf16 v[120:123], v[184:187], v[214:217], v[120:123]
	v_mfma_f32_16x16x32_bf16 v[108:111], v[176:179], v[222:225], v[108:111]
	v_mfma_f32_16x16x32_bf16 v[104:107], v[184:187], v[222:225], v[104:107]
	v_mfma_f32_16x16x32_bf16 v[92:95], v[176:179], v[230:233], v[92:95]
	v_mfma_f32_16x16x32_bf16 v[88:91], v[184:187], v[230:233], v[88:91]
	v_mfma_f32_16x16x32_bf16 v[76:79], v[176:179], v[238:241], v[76:79]
	v_mfma_f32_16x16x32_bf16 v[72:75], v[184:187], v[238:241], v[72:75]
	v_mfma_f32_16x16x32_bf16 v[116:119], v[190:193], v[210:213], v[116:119]
	v_mfma_f32_16x16x32_bf16 v[112:115], v[202:205], v[210:213], v[112:115]
	v_mfma_f32_16x16x32_bf16 v[100:103], v[190:193], v[218:221], v[100:103]
	v_mfma_f32_16x16x32_bf16 v[96:99], v[202:205], v[218:221], v[96:99]
	v_mfma_f32_16x16x32_bf16 v[84:87], v[190:193], v[226:229], v[84:87]
	v_mfma_f32_16x16x32_bf16 v[80:83], v[202:205], v[226:229], v[80:83]
	v_mfma_f32_16x16x32_bf16 v[68:71], v[190:193], v[234:237], v[68:71]
	v_mfma_f32_16x16x32_bf16 v[64:67], v[202:205], v[234:237], v[64:67]
	v_mfma_f32_16x16x32_bf16 v[116:119], v[198:201], v[214:217], v[116:119]
	v_mfma_f32_16x16x32_bf16 v[112:115], v[206:209], v[214:217], v[112:115]
	v_mfma_f32_16x16x32_bf16 v[100:103], v[198:201], v[222:225], v[100:103]
	v_mfma_f32_16x16x32_bf16 v[96:99], v[206:209], v[222:225], v[96:99]
	v_mfma_f32_16x16x32_bf16 v[84:87], v[198:201], v[230:233], v[84:87]
	v_mfma_f32_16x16x32_bf16 v[80:83], v[206:209], v[230:233], v[80:83]
	v_mfma_f32_16x16x32_bf16 v[68:71], v[198:201], v[238:241], v[68:71]
	v_mfma_f32_16x16x32_bf16 v[64:67], v[206:209], v[238:241], v[64:67]
	s_barrier
	s_add_i32 s13, s13, s19
	v_lshl_add_u64 v[158:159], v[242:243], 0, s[84:85]
	s_mov_b32 m0, s13
	ds_read_b128 v[210:213], v175 offset:49152
	ds_read_b128 v[214:217], v175 offset:50176
	ds_read_b128 v[218:221], v175 offset:51200
	ds_read_b128 v[222:225], v175 offset:52224
	ds_read_b128 v[226:229], v175 offset:53248
	ds_read_b128 v[230:233], v175 offset:54272
	ds_read_b128 v[234:237], v175 offset:55296
	ds_read_b128 v[238:241], v175 offset:56320
	global_load_lds_dwordx4 v[158:159], off
	v_lshl_add_u64 v[158:159], v[244:245], 0, s[84:85]
	s_add_i32 m0, s13, 0x2000
	s_add_i32 s13, s14, s19
	global_load_lds_dwordx4 v[158:159], off
	v_lshl_add_u64 v[158:159], v[170:171], 0, s[36:37]
	v_lshl_add_u64 v[170:171], v[158:159], 0, v[162:163]
	s_mov_b32 m0, s13
	v_lshl_add_u64 v[158:159], v[158:159], 0, v[136:137]
	global_load_lds_dwordx4 v[170:171], off
	s_add_i32 m0, s13, 0x2000
	s_nop 0
	global_load_lds_dwordx4 v[158:159], off
	v_lshl_add_u64 v[158:159], v[246:247], 0, s[84:85]
	s_mov_b32 m0, s24
	s_nop 0
	global_load_lds_dwordx4 v[158:159], off
	v_lshl_add_u64 v[158:159], v[248:249], 0, s[84:85]
	s_mov_b32 m0, s25
	s_nop 0
	global_load_lds_dwordx4 v[158:159], off
	s_waitcnt vmcnt(8)
	s_waitcnt lgkmcnt(0)
	s_barrier
	s_waitcnt lgkmcnt(0)
	v_mfma_f32_16x16x32_bf16 v[60:63], v[164:167], v[210:213], v[60:63]
	v_mfma_f32_16x16x32_bf16 v[56:59], v[180:183], v[210:213], v[56:59]
	v_mfma_f32_16x16x32_bf16 v[44:47], v[164:167], v[218:221], v[44:47]
	v_mfma_f32_16x16x32_bf16 v[40:43], v[180:183], v[218:221], v[40:43]
	v_mfma_f32_16x16x32_bf16 v[28:31], v[164:167], v[226:229], v[28:31]
	v_mfma_f32_16x16x32_bf16 v[24:27], v[180:183], v[226:229], v[24:27]
	v_mfma_f32_16x16x32_bf16 v[12:15], v[164:167], v[234:237], v[12:15]
	v_mfma_f32_16x16x32_bf16 v[8:11], v[180:183], v[234:237], v[8:11]
	v_mfma_f32_16x16x32_bf16 v[60:63], v[176:179], v[214:217], v[60:63]
	v_mfma_f32_16x16x32_bf16 v[56:59], v[184:187], v[214:217], v[56:59]
	v_mfma_f32_16x16x32_bf16 v[44:47], v[176:179], v[222:225], v[44:47]
	v_mfma_f32_16x16x32_bf16 v[40:43], v[184:187], v[222:225], v[40:43]
	v_mfma_f32_16x16x32_bf16 v[28:31], v[176:179], v[230:233], v[28:31]
	v_mfma_f32_16x16x32_bf16 v[24:27], v[184:187], v[230:233], v[24:27]
	v_mfma_f32_16x16x32_bf16 v[12:15], v[176:179], v[238:241], v[12:15]
	v_mfma_f32_16x16x32_bf16 v[8:11], v[184:187], v[238:241], v[8:11]
	v_mfma_f32_16x16x32_bf16 v[52:55], v[190:193], v[210:213], v[52:55]
	v_mfma_f32_16x16x32_bf16 v[48:51], v[202:205], v[210:213], v[48:51]
	v_mfma_f32_16x16x32_bf16 v[36:39], v[190:193], v[218:221], v[36:39]
	v_mfma_f32_16x16x32_bf16 v[32:35], v[202:205], v[218:221], v[32:35]
	v_mfma_f32_16x16x32_bf16 v[20:23], v[190:193], v[226:229], v[20:23]
	v_mfma_f32_16x16x32_bf16 v[16:19], v[202:205], v[226:229], v[16:19]
	v_mfma_f32_16x16x32_bf16 v[4:7], v[190:193], v[234:237], v[4:7]
	v_mfma_f32_16x16x32_bf16 v[0:3], v[202:205], v[234:237], v[0:3]
	v_mfma_f32_16x16x32_bf16 v[52:55], v[198:201], v[214:217], v[52:55]
	v_mfma_f32_16x16x32_bf16 v[48:51], v[206:209], v[214:217], v[48:51]
	v_mfma_f32_16x16x32_bf16 v[36:39], v[198:201], v[222:225], v[36:39]
	v_mfma_f32_16x16x32_bf16 v[32:35], v[206:209], v[222:225], v[32:35]
	v_mfma_f32_16x16x32_bf16 v[20:23], v[198:201], v[230:233], v[20:23]
	v_mfma_f32_16x16x32_bf16 v[16:19], v[206:209], v[230:233], v[16:19]
	v_mfma_f32_16x16x32_bf16 v[4:7], v[198:201], v[238:241], v[4:7]
	v_mfma_f32_16x16x32_bf16 v[0:3], v[206:209], v[238:241], v[0:3]
	s_barrier
	s_add_i32 s11, s11, 2
	v_lshl_add_u64 v[154:155], v[154:155], 0, s[0:1]
	s_cmp_gt_u32 s11, 5
	v_lshl_add_u64 v[156:157], v[156:157], 0, s[0:1]
	s_cbranch_scc0 .LBB0_1465
	s_and_b64 vcc, exec, s[8:9]
	s_cbranch_vccz .LBB0_1468
	s_barrier

.LBB0_1614:
	s_cmp_eq_u32 s3, 12
	s_cselect_b64 vcc, -1, 0
	s_add_i32 s11, s33, 0x100
	v_add_u32_e32 v159, s11, v156
	s_add_i32 s14, s92, 0x100
	ds_read_b128 v[164:167], v159
	ds_read_b128 v[170:173], v159 offset:1024
	ds_read_b128 v[174:177], v159 offset:2048
	ds_read_b128 v[178:181], v159 offset:3072
	v_add_u32_e32 v159, s14, v156
	ds_read_b128 v[182:185], v159
	ds_read_b128 v[190:193], v159 offset:1024
	ds_read_b128 v[198:201], v159 offset:2048
	ds_read_b128 v[202:205], v159 offset:3072
	v_lshl_add_u64 v[152:153], v[150:151], 0, s[0:1]
	v_cndmask_b32_e32 v187, v153, v145, vcc
	v_cndmask_b32_e32 v186, v152, v144, vcc
	v_cndmask_b32_e32 v239, v149, v147, vcc
	v_cndmask_b32_e32 v238, v148, v146, vcc
	v_lshl_add_u64 v[240:241], v[150:151], 0, v[138:139]
	s_add_i32 m0, s22, 0xc000
	ds_read_b128 v[206:209], v158
	ds_read_b128 v[210:213], v158 offset:1024
	ds_read_b128 v[214:217], v158 offset:2048
	ds_read_b128 v[218:221], v158 offset:3072
	ds_read_b128 v[222:225], v158 offset:4096
	ds_read_b128 v[226:229], v158 offset:5120
	ds_read_b128 v[230:233], v158 offset:6144
	ds_read_b128 v[234:237], v158 offset:7168
	global_load_lds_dwordx4 v[240:241], off
	v_lshl_add_u64 v[150:151], v[150:151], 0, v[136:137]
	s_add_i32 m0, s22, 0xe000
	s_nop 0
	global_load_lds_dwordx4 v[150:151], off
	s_waitcnt vmcnt(8)
	s_waitcnt lgkmcnt(0)
	s_barrier
	s_waitcnt lgkmcnt(0)
	v_mfma_f32_16x16x32_bf16 v[124:127], v[164:167], v[206:209], v[124:127]
	v_mfma_f32_16x16x32_bf16 v[120:123], v[174:177], v[206:209], v[120:123]
	v_mfma_f32_16x16x32_bf16 v[108:111], v[164:167], v[214:217], v[108:111]
	v_mfma_f32_16x16x32_bf16 v[104:107], v[174:177], v[214:217], v[104:107]
	v_mfma_f32_16x16x32_bf16 v[92:95], v[164:167], v[222:225], v[92:95]
	v_mfma_f32_16x16x32_bf16 v[88:91], v[174:177], v[222:225], v[88:91]
	v_mfma_f32_16x16x32_bf16 v[76:79], v[164:167], v[230:233], v[76:79]
	v_mfma_f32_16x16x32_bf16 v[72:75], v[174:177], v[230:233], v[72:75]
	v_mfma_f32_16x16x32_bf16 v[124:127], v[170:173], v[210:213], v[124:127]
	v_mfma_f32_16x16x32_bf16 v[120:123], v[178:181], v[210:213], v[120:123]
	v_mfma_f32_16x16x32_bf16 v[108:111], v[170:173], v[218:221], v[108:111]
	v_mfma_f32_16x16x32_bf16 v[104:107], v[178:181], v[218:221], v[104:107]
	v_mfma_f32_16x16x32_bf16 v[92:95], v[170:173], v[226:229], v[92:95]
	v_mfma_f32_16x16x32_bf16 v[88:91], v[178:181], v[226:229], v[88:91]
	v_mfma_f32_16x16x32_bf16 v[76:79], v[170:173], v[234:237], v[76:79]
	v_mfma_f32_16x16x32_bf16 v[72:75], v[178:181], v[234:237], v[72:75]
	v_mfma_f32_16x16x32_bf16 v[116:119], v[182:185], v[206:209], v[116:119]
	v_mfma_f32_16x16x32_bf16 v[112:115], v[198:201], v[206:209], v[112:115]
	v_mfma_f32_16x16x32_bf16 v[100:103], v[182:185], v[214:217], v[100:103]
	v_mfma_f32_16x16x32_bf16 v[96:99], v[198:201], v[214:217], v[96:99]
	v_mfma_f32_16x16x32_bf16 v[84:87], v[182:185], v[222:225], v[84:87]
	v_mfma_f32_16x16x32_bf16 v[80:83], v[198:201], v[222:225], v[80:83]
	v_mfma_f32_16x16x32_bf16 v[68:71], v[182:185], v[230:233], v[68:71]
	v_mfma_f32_16x16x32_bf16 v[64:67], v[198:201], v[230:233], v[64:67]
	v_mfma_f32_16x16x32_bf16 v[116:119], v[190:193], v[210:213], v[116:119]
	v_mfma_f32_16x16x32_bf16 v[112:115], v[202:205], v[210:213], v[112:115]
	v_mfma_f32_16x16x32_bf16 v[100:103], v[190:193], v[218:221], v[100:103]
	v_mfma_f32_16x16x32_bf16 v[96:99], v[202:205], v[218:221], v[96:99]
	v_mfma_f32_16x16x32_bf16 v[84:87], v[190:193], v[226:229], v[84:87]
	v_mfma_f32_16x16x32_bf16 v[80:83], v[202:205], v[226:229], v[80:83]
	v_mfma_f32_16x16x32_bf16 v[68:71], v[190:193], v[234:237], v[68:71]
	v_mfma_f32_16x16x32_bf16 v[64:67], v[202:205], v[234:237], v[64:67]
	s_barrier
	s_add_i32 s11, s11, s21
	v_lshl_add_u64 v[150:151], v[238:239], 0, v[162:163]
	s_mov_b32 m0, s11
	ds_read_b128 v[206:209], v158 offset:16384
	ds_read_b128 v[210:213], v158 offset:17408
	ds_read_b128 v[214:217], v158 offset:18432
	ds_read_b128 v[218:221], v158 offset:19456
	ds_read_b128 v[222:225], v158 offset:20480
	ds_read_b128 v[226:229], v158 offset:21504
	ds_read_b128 v[230:233], v158 offset:22528
	ds_read_b128 v[234:237], v158 offset:23552
	global_load_lds_dwordx4 v[150:151], off
	v_lshl_add_u64 v[240:241], v[238:239], 0, v[134:135]
	s_add_i32 m0, s11, 0x2000
	v_lshl_add_u64 v[242:243], v[238:239], 0, s[78:79]
	s_add_i32 s11, s14, s21
	global_load_lds_dwordx4 v[240:241], off
	v_lshl_add_u64 v[244:245], v[242:243], 0, v[162:163]
	s_mov_b32 m0, s11
	v_lshl_add_u64 v[242:243], v[242:243], 0, v[134:135]
	global_load_lds_dwordx4 v[244:245], off
	s_add_i32 m0, s11, 0x2000
	v_lshl_add_u64 v[244:245], v[186:187], 0, v[134:135]
	global_load_lds_dwordx4 v[242:243], off
	v_lshl_add_u64 v[242:243], v[186:187], 0, v[162:163]
	s_mov_b32 m0, s22
	s_nop 0
	global_load_lds_dwordx4 v[242:243], off
	s_mov_b32 m0, s23
	s_nop 0
	global_load_lds_dwordx4 v[244:245], off
	s_waitcnt vmcnt(8)
	s_waitcnt lgkmcnt(0)
	s_barrier
	s_waitcnt lgkmcnt(0)
	v_mfma_f32_16x16x32_bf16 v[60:63], v[164:167], v[206:209], v[60:63]
	v_mfma_f32_16x16x32_bf16 v[56:59], v[174:177], v[206:209], v[56:59]
	v_mfma_f32_16x16x32_bf16 v[44:47], v[164:167], v[214:217], v[44:47]
	v_mfma_f32_16x16x32_bf16 v[40:43], v[174:177], v[214:217], v[40:43]
	v_mfma_f32_16x16x32_bf16 v[28:31], v[164:167], v[222:225], v[28:31]
	v_mfma_f32_16x16x32_bf16 v[24:27], v[174:177], v[222:225], v[24:27]
	v_mfma_f32_16x16x32_bf16 v[12:15], v[164:167], v[230:233], v[12:15]
	v_mfma_f32_16x16x32_bf16 v[8:11], v[174:177], v[230:233], v[8:11]
	v_mfma_f32_16x16x32_bf16 v[60:63], v[170:173], v[210:213], v[60:63]
	v_mfma_f32_16x16x32_bf16 v[56:59], v[178:181], v[210:213], v[56:59]
	v_mfma_f32_16x16x32_bf16 v[44:47], v[170:173], v[218:221], v[44:47]
	v_mfma_f32_16x16x32_bf16 v[40:43], v[178:181], v[218:221], v[40:43]
	v_mfma_f32_16x16x32_bf16 v[28:31], v[170:173], v[226:229], v[28:31]
	v_mfma_f32_16x16x32_bf16 v[24:27], v[178:181], v[226:229], v[24:27]
	v_mfma_f32_16x16x32_bf16 v[12:15], v[170:173], v[234:237], v[12:15]
	v_mfma_f32_16x16x32_bf16 v[8:11], v[178:181], v[234:237], v[8:11]
	v_mfma_f32_16x16x32_bf16 v[52:55], v[182:185], v[206:209], v[52:55]
	v_mfma_f32_16x16x32_bf16 v[48:51], v[198:201], v[206:209], v[48:51]
	v_mfma_f32_16x16x32_bf16 v[36:39], v[182:185], v[214:217], v[36:39]
	v_mfma_f32_16x16x32_bf16 v[32:35], v[198:201], v[214:217], v[32:35]
	v_mfma_f32_16x16x32_bf16 v[20:23], v[182:185], v[222:225], v[20:23]
	v_mfma_f32_16x16x32_bf16 v[16:19], v[198:201], v[222:225], v[16:19]
	v_mfma_f32_16x16x32_bf16 v[4:7], v[182:185], v[230:233], v[4:7]
	v_mfma_f32_16x16x32_bf16 v[0:3], v[198:201], v[230:233], v[0:3]
	v_mfma_f32_16x16x32_bf16 v[52:55], v[190:193], v[210:213], v[52:55]
	v_mfma_f32_16x16x32_bf16 v[48:51], v[202:205], v[210:213], v[48:51]
	v_mfma_f32_16x16x32_bf16 v[36:39], v[190:193], v[218:221], v[36:39]
	v_mfma_f32_16x16x32_bf16 v[32:35], v[202:205], v[218:221], v[32:35]
	v_mfma_f32_16x16x32_bf16 v[20:23], v[190:193], v[226:229], v[20:23]
	v_mfma_f32_16x16x32_bf16 v[16:19], v[202:205], v[226:229], v[16:19]
	v_mfma_f32_16x16x32_bf16 v[4:7], v[190:193], v[234:237], v[4:7]
	v_mfma_f32_16x16x32_bf16 v[0:3], v[202:205], v[234:237], v[0:3]
	s_barrier
	s_add_i32 s11, s93, 0x100
	v_add_u32_e32 v159, s11, v156
	s_add_i32 s14, s82, 0x100
	ds_read_b128 v[164:167], v159
	ds_read_b128 v[170:173], v159 offset:1024
	ds_read_b128 v[174:177], v159 offset:2048
	ds_read_b128 v[178:181], v159 offset:3072
	v_add_u32_e32 v159, s14, v156
	ds_read_b128 v[182:185], v159
	ds_read_b128 v[190:193], v159 offset:1024
	ds_read_b128 v[198:201], v159 offset:2048
	ds_read_b128 v[202:205], v159 offset:3072
	v_lshl_add_u64 v[186:187], v[186:187], 0, s[78:79]
	s_mov_b32 m0, s24
	v_lshl_add_u64 v[246:247], v[186:187], 0, v[162:163]
	ds_read_b128 v[206:209], v158 offset:32768
	ds_read_b128 v[210:213], v158 offset:33792
	ds_read_b128 v[214:217], v158 offset:34816
	ds_read_b128 v[218:221], v158 offset:35840
	ds_read_b128 v[222:225], v158 offset:36864
	ds_read_b128 v[226:229], v158 offset:37888
	ds_read_b128 v[230:233], v158 offset:38912
	ds_read_b128 v[234:237], v158 offset:39936
	global_load_lds_dwordx4 v[246:247], off
	v_lshl_add_u64 v[186:187], v[186:187], 0, v[134:135]
	s_mov_b32 m0, s25
	s_nop 0
	global_load_lds_dwordx4 v[186:187], off
	s_waitcnt vmcnt(8)
	s_waitcnt lgkmcnt(0)
	s_barrier
	s_waitcnt lgkmcnt(0)
	v_mfma_f32_16x16x32_bf16 v[124:127], v[164:167], v[206:209], v[124:127]
	v_mfma_f32_16x16x32_bf16 v[120:123], v[174:177], v[206:209], v[120:123]
	v_mfma_f32_16x16x32_bf16 v[108:111], v[164:167], v[214:217], v[108:111]
	v_mfma_f32_16x16x32_bf16 v[104:107], v[174:177], v[214:217], v[104:107]
	v_mfma_f32_16x16x32_bf16 v[92:95], v[164:167], v[222:225], v[92:95]
	v_mfma_f32_16x16x32_bf16 v[88:91], v[174:177], v[222:225], v[88:91]
	v_mfma_f32_16x16x32_bf16 v[76:79], v[164:167], v[230:233], v[76:79]
	v_mfma_f32_16x16x32_bf16 v[72:75], v[174:177], v[230:233], v[72:75]
	v_mfma_f32_16x16x32_bf16 v[124:127], v[170:173], v[210:213], v[124:127]
	v_mfma_f32_16x16x32_bf16 v[120:123], v[178:181], v[210:213], v[120:123]
	v_mfma_f32_16x16x32_bf16 v[108:111], v[170:173], v[218:221], v[108:111]
	v_mfma_f32_16x16x32_bf16 v[104:107], v[178:181], v[218:221], v[104:107]
	v_mfma_f32_16x16x32_bf16 v[92:95], v[170:173], v[226:229], v[92:95]
	v_mfma_f32_16x16x32_bf16 v[88:91], v[178:181], v[226:229], v[88:91]
	v_mfma_f32_16x16x32_bf16 v[76:79], v[170:173], v[234:237], v[76:79]
	v_mfma_f32_16x16x32_bf16 v[72:75], v[178:181], v[234:237], v[72:75]
	v_mfma_f32_16x16x32_bf16 v[116:119], v[182:185], v[206:209], v[116:119]
	v_mfma_f32_16x16x32_bf16 v[112:115], v[198:201], v[206:209], v[112:115]
	v_mfma_f32_16x16x32_bf16 v[100:103], v[182:185], v[214:217], v[100:103]
	v_mfma_f32_16x16x32_bf16 v[96:99], v[198:201], v[214:217], v[96:99]
	v_mfma_f32_16x16x32_bf16 v[84:87], v[182:185], v[222:225], v[84:87]
	v_mfma_f32_16x16x32_bf16 v[80:83], v[198:201], v[222:225], v[80:83]
	v_mfma_f32_16x16x32_bf16 v[68:71], v[182:185], v[230:233], v[68:71]
	v_mfma_f32_16x16x32_bf16 v[64:67], v[198:201], v[230:233], v[64:67]
	v_mfma_f32_16x16x32_bf16 v[116:119], v[190:193], v[210:213], v[116:119]
	v_mfma_f32_16x16x32_bf16 v[112:115], v[202:205], v[210:213], v[112:115]
	v_mfma_f32_16x16x32_bf16 v[100:103], v[190:193], v[218:221], v[100:103]
	v_mfma_f32_16x16x32_bf16 v[96:99], v[202:205], v[218:221], v[96:99]
	v_mfma_f32_16x16x32_bf16 v[84:87], v[190:193], v[226:229], v[84:87]
	v_mfma_f32_16x16x32_bf16 v[80:83], v[202:205], v[226:229], v[80:83]
	v_mfma_f32_16x16x32_bf16 v[68:71], v[190:193], v[234:237], v[68:71]
	v_mfma_f32_16x16x32_bf16 v[64:67], v[202:205], v[234:237], v[64:67]
	s_barrier
	s_add_i32 s11, s11, s21
	v_lshl_add_u64 v[150:151], v[150:151], 0, s[84:85]
	s_mov_b32 m0, s11
	ds_read_b128 v[206:209], v158 offset:49152
	ds_read_b128 v[210:213], v158 offset:50176
	ds_read_b128 v[214:217], v158 offset:51200
	ds_read_b128 v[218:221], v158 offset:52224
	ds_read_b128 v[222:225], v158 offset:53248
	ds_read_b128 v[226:229], v158 offset:54272
	ds_read_b128 v[230:233], v158 offset:55296
	ds_read_b128 v[234:237], v158 offset:56320
	global_load_lds_dwordx4 v[150:151], off
	v_lshl_add_u64 v[150:151], v[240:241], 0, s[84:85]
	s_add_i32 m0, s11, 0x2000
	s_add_i32 s11, s14, s21
	global_load_lds_dwordx4 v[150:151], off
	v_lshl_add_u64 v[150:151], v[238:239], 0, s[86:87]
	v_lshl_add_u64 v[186:187], v[150:151], 0, v[162:163]
	s_mov_b32 m0, s11
	v_lshl_add_u64 v[150:151], v[150:151], 0, v[134:135]
	global_load_lds_dwordx4 v[186:187], off
	s_add_i32 m0, s11, 0x2000
	s_nop 0
	global_load_lds_dwordx4 v[150:151], off
	v_lshl_add_u64 v[150:151], v[242:243], 0, s[84:85]
	s_mov_b32 m0, s26
	s_nop 0
	global_load_lds_dwordx4 v[150:151], off
	v_lshl_add_u64 v[150:151], v[244:245], 0, s[84:85]
	s_mov_b32 m0, s27
	s_nop 0
	global_load_lds_dwordx4 v[150:151], off
	s_waitcnt vmcnt(8)
	s_waitcnt lgkmcnt(0)
	s_barrier
	s_waitcnt lgkmcnt(0)
	v_mfma_f32_16x16x32_bf16 v[60:63], v[164:167], v[206:209], v[60:63]
	v_mfma_f32_16x16x32_bf16 v[56:59], v[174:177], v[206:209], v[56:59]
	v_mfma_f32_16x16x32_bf16 v[44:47], v[164:167], v[214:217], v[44:47]
	v_mfma_f32_16x16x32_bf16 v[40:43], v[174:177], v[214:217], v[40:43]
	v_mfma_f32_16x16x32_bf16 v[28:31], v[164:167], v[222:225], v[28:31]
	v_mfma_f32_16x16x32_bf16 v[24:27], v[174:177], v[222:225], v[24:27]
	v_mfma_f32_16x16x32_bf16 v[12:15], v[164:167], v[230:233], v[12:15]
	v_mfma_f32_16x16x32_bf16 v[8:11], v[174:177], v[230:233], v[8:11]
	v_mfma_f32_16x16x32_bf16 v[60:63], v[170:173], v[210:213], v[60:63]
	v_mfma_f32_16x16x32_bf16 v[56:59], v[178:181], v[210:213], v[56:59]
	v_mfma_f32_16x16x32_bf16 v[44:47], v[170:173], v[218:221], v[44:47]
	v_mfma_f32_16x16x32_bf16 v[40:43], v[178:181], v[218:221], v[40:43]
	v_mfma_f32_16x16x32_bf16 v[28:31], v[170:173], v[226:229], v[28:31]
	v_mfma_f32_16x16x32_bf16 v[24:27], v[178:181], v[226:229], v[24:27]
	v_mfma_f32_16x16x32_bf16 v[12:15], v[170:173], v[234:237], v[12:15]
	v_mfma_f32_16x16x32_bf16 v[8:11], v[178:181], v[234:237], v[8:11]
	v_mfma_f32_16x16x32_bf16 v[52:55], v[182:185], v[206:209], v[52:55]
	v_mfma_f32_16x16x32_bf16 v[48:51], v[198:201], v[206:209], v[48:51]
	v_mfma_f32_16x16x32_bf16 v[36:39], v[182:185], v[214:217], v[36:39]
	v_mfma_f32_16x16x32_bf16 v[32:35], v[198:201], v[214:217], v[32:35]
	v_mfma_f32_16x16x32_bf16 v[20:23], v[182:185], v[222:225], v[20:23]
	v_mfma_f32_16x16x32_bf16 v[16:19], v[198:201], v[222:225], v[16:19]
	v_mfma_f32_16x16x32_bf16 v[4:7], v[182:185], v[230:233], v[4:7]
	v_mfma_f32_16x16x32_bf16 v[0:3], v[198:201], v[230:233], v[0:3]
	v_mfma_f32_16x16x32_bf16 v[52:55], v[190:193], v[210:213], v[52:55]
	v_mfma_f32_16x16x32_bf16 v[48:51], v[202:205], v[210:213], v[48:51]
	v_mfma_f32_16x16x32_bf16 v[36:39], v[190:193], v[218:221], v[36:39]
	v_mfma_f32_16x16x32_bf16 v[32:35], v[202:205], v[218:221], v[32:35]
	v_mfma_f32_16x16x32_bf16 v[20:23], v[190:193], v[226:229], v[20:23]
	v_mfma_f32_16x16x32_bf16 v[16:19], v[202:205], v[226:229], v[16:19]
	v_mfma_f32_16x16x32_bf16 v[4:7], v[190:193], v[234:237], v[4:7]
	v_mfma_f32_16x16x32_bf16 v[0:3], v[202:205], v[234:237], v[0:3]
	s_barrier
	s_add_i32 s3, s3, 2
	v_lshl_add_u64 v[148:149], v[148:149], 0, s[0:1]
	s_cmp_gt_u32 s3, 13
	v_mov_b64_e32 v[150:151], v[152:153]
	s_cbranch_scc0 .LBB0_1614
	s_and_b64 vcc, exec, s[8:9]
	s_cbranch_vccz .LBB0_1617
	s_barrier

.LBB0_1629:
	v_bfe_u32 v35, v4, 4, 2
	v_and_b32_e32 v5, 15, v4
	v_lshlrev_b32_e32 v6, 4, v35
	v_lshlrev_b32_e32 v4, 2, v4
	v_lshl_or_b32 v34, s8, 6, v5
	v_lshl_or_b32 v5, v5, 6, v6
	s_lshl_b32 s3, s8, 13
	v_and_b32_e32 v4, 32, v4
	v_bitop3_b32 v36, v5, s3, v4 bitop3:0xde
	s_lshl_b32 s3, s9, 5
	s_and_b32 s3, s3, 0x60
	s_lshl_b32 s8, s3, 7
	s_add_i32 s18, s93, 0x100
	v_bitop3_b32 v37, v5, s8, v4 bitop3:0xde
	s_add_i32 s8, s18, s17
	v_lshl_add_u64 v[6:7], v[12:13], 0, s[84:85]
	s_mov_b32 m0, s8
	s_add_i32 s11, s8, 0x2000
	s_waitcnt vmcnt(2)
	s_barrier
	global_load_lds_dwordx4 v[6:7], off
	v_lshl_add_u64 v[8:9], v[20:21], 0, s[84:85]
	s_mov_b32 m0, s11
	s_add_i32 s9, s10, 0x8000
	global_load_lds_dwordx4 v[8:9], off
	v_lshl_add_u64 v[4:5], v[26:27], 0, s[84:85]
	s_mov_b32 m0, s9
	s_add_i32 s12, s10, 0xa000
	s_add_i32 s19, s82, 0x100
	global_load_lds_dwordx4 v[4:5], off
	v_lshl_add_u64 v[10:11], v[28:29], 0, s[84:85]
	s_mov_b32 m0, s12
	v_lshl_add_u64 v[18:19], v[32:33], 0, s[86:87]
	s_add_i32 s13, s19, s17
	global_load_lds_dwordx4 v[10:11], off
	v_lshl_add_u64 v[16:17], v[18:19], 0, v[162:163]
	s_mov_b32 m0, s13
	s_add_i32 s14, s13, 0x2000
	global_load_lds_dwordx4 v[16:17], off
	v_lshl_add_u64 v[18:19], v[18:19], 0, v[14:15]
	s_mov_b32 m0, s14
	s_add_i32 s20, s33, 0x100
	global_load_lds_dwordx4 v[18:19], off
	v_add_u32_e32 v186, s20, v37
	s_add_i32 s21, s92, 0x100
	s_waitcnt vmcnt(6)
	s_barrier
	v_add_u32_e32 v187, s21, v37
	ds_read_b128 v[38:41], v186
	ds_read_b128 v[42:45], v186 offset:1024
	ds_read_b128 v[46:49], v186 offset:2048
	ds_read_b128 v[50:53], v186 offset:3072
	ds_read_b128 v[54:57], v187
	ds_read_b128 v[58:61], v187 offset:1024
	ds_read_b128 v[62:65], v187 offset:2048
	ds_read_b128 v[66:69], v187 offset:3072
	v_add_u32_e32 v36, 0x100, v36
	v_add_u32_e32 v250, s18, v37
	v_add_u32_e32 v37, s19, v37
	v_lshlrev_b32_e32 v35, 2, v35
	v_lshl_add_u64 v[102:103], v[30:31], 0, s[86:87]
	s_add_i32 s22, s10, 0xc000
	v_lshl_add_u64 v[104:105], v[102:103], 0, v[162:163]
	s_mov_b32 m0, s22
	s_add_i32 s18, s10, 0xe000
	ds_read_b128 v[70:73], v36
	ds_read_b128 v[74:77], v36 offset:1024
	ds_read_b128 v[78:81], v36 offset:2048
	ds_read_b128 v[82:85], v36 offset:3072
	ds_read_b128 v[86:89], v36 offset:4096
	ds_read_b128 v[90:93], v36 offset:5120
	ds_read_b128 v[94:97], v36 offset:6144
	ds_read_b128 v[98:101], v36 offset:7168
	global_load_lds_dwordx4 v[104:105], off
	v_lshl_add_u64 v[102:103], v[102:103], 0, v[14:15]
	s_mov_b32 m0, s18
	s_nop 0
	global_load_lds_dwordx4 v[102:103], off
	s_waitcnt vmcnt(8)
	s_waitcnt lgkmcnt(0)
	s_barrier
	s_waitcnt lgkmcnt(0)
	v_mfma_f32_16x16x32_bf16 v[102:105], v[38:41], v[70:73], 0
	v_mfma_f32_16x16x32_bf16 v[106:109], v[46:49], v[70:73], 0
	v_mfma_f32_16x16x32_bf16 v[110:113], v[38:41], v[78:81], 0
	v_mfma_f32_16x16x32_bf16 v[114:117], v[46:49], v[78:81], 0
	v_mfma_f32_16x16x32_bf16 v[118:121], v[38:41], v[86:89], 0
	v_mfma_f32_16x16x32_bf16 v[122:125], v[46:49], v[86:89], 0
	v_mfma_f32_16x16x32_bf16 v[130:133], v[38:41], v[94:97], 0
	v_mfma_f32_16x16x32_bf16 v[134:137], v[46:49], v[94:97], 0
	v_mfma_f32_16x16x32_bf16 v[102:105], v[42:45], v[74:77], v[102:105]
	v_mfma_f32_16x16x32_bf16 v[106:109], v[50:53], v[74:77], v[106:109]
	v_mfma_f32_16x16x32_bf16 v[110:113], v[42:45], v[82:85], v[110:113]
	v_mfma_f32_16x16x32_bf16 v[114:117], v[50:53], v[82:85], v[114:117]
	v_mfma_f32_16x16x32_bf16 v[118:121], v[42:45], v[90:93], v[118:121]
	v_mfma_f32_16x16x32_bf16 v[122:125], v[50:53], v[90:93], v[122:125]
	v_mfma_f32_16x16x32_bf16 v[130:133], v[42:45], v[98:101], v[130:133]
	v_mfma_f32_16x16x32_bf16 v[134:137], v[50:53], v[98:101], v[134:137]
	v_mfma_f32_16x16x32_bf16 v[138:141], v[54:57], v[70:73], 0
	v_mfma_f32_16x16x32_bf16 v[70:73], v[62:65], v[70:73], 0
	v_mfma_f32_16x16x32_bf16 v[138:141], v[58:61], v[74:77], v[138:141]
	v_mfma_f32_16x16x32_bf16 v[70:73], v[66:69], v[74:77], v[70:73]
	v_mfma_f32_16x16x32_bf16 v[74:77], v[54:57], v[78:81], 0
	v_mfma_f32_16x16x32_bf16 v[78:81], v[62:65], v[78:81], 0
	v_mfma_f32_16x16x32_bf16 v[74:77], v[58:61], v[82:85], v[74:77]
	v_mfma_f32_16x16x32_bf16 v[78:81], v[66:69], v[82:85], v[78:81]
	v_mfma_f32_16x16x32_bf16 v[82:85], v[54:57], v[86:89], 0
	v_mfma_f32_16x16x32_bf16 v[86:89], v[62:65], v[86:89], 0
	v_mfma_f32_16x16x32_bf16 v[82:85], v[58:61], v[90:93], v[82:85]
	v_mfma_f32_16x16x32_bf16 v[86:89], v[66:69], v[90:93], v[86:89]
	v_mfma_f32_16x16x32_bf16 v[90:93], v[54:57], v[94:97], 0
	v_mfma_f32_16x16x32_bf16 v[94:97], v[62:65], v[94:97], 0
	v_mfma_f32_16x16x32_bf16 v[90:93], v[58:61], v[98:101], v[90:93]
	v_mfma_f32_16x16x32_bf16 v[94:97], v[66:69], v[98:101], v[94:97]
	s_barrier
	s_add_i32 s19, s20, s17
	v_lshl_add_u64 v[126:127], v[12:13], 0, s[0:1]
	s_mov_b32 m0, s19
	s_add_i32 s20, s19, 0x2000
	ds_read_b128 v[98:101], v36 offset:16384
	ds_read_b128 v[142:145], v36 offset:17408
	ds_read_b128 v[146:149], v36 offset:18432
	ds_read_b128 v[150:153], v36 offset:19456
	ds_read_b128 v[154:157], v36 offset:20480
	ds_read_b128 v[164:167], v36 offset:21504
	ds_read_b128 v[170:173], v36 offset:22528
	ds_read_b128 v[174:177], v36 offset:23552
	global_load_lds_dwordx4 v[126:127], off
	v_lshl_add_u64 v[126:127], v[20:21], 0, s[0:1]
	s_mov_b32 m0, s20
	s_mov_b64 s[28:29], 0x40100
	global_load_lds_dwordx4 v[126:127], off
	v_lshl_add_u64 v[126:127], v[32:33], 0, s[28:29]
	s_add_i32 s17, s21, s17
	v_lshl_add_u64 v[158:159], v[126:127], 0, v[162:163]
	s_mov_b32 m0, s17
	s_add_i32 s21, s17, 0x2000
	global_load_lds_dwordx4 v[158:159], off
	v_lshl_add_u64 v[126:127], v[126:127], 0, v[14:15]
	s_mov_b32 m0, s21
	s_nop 0
	global_load_lds_dwordx4 v[126:127], off
	v_lshl_add_u64 v[126:127], v[26:27], 0, s[0:1]
	s_mov_b32 m0, s10
	s_nop 0
	global_load_lds_dwordx4 v[126:127], off
	v_lshl_add_u64 v[126:127], v[28:29], 0, s[0:1]
	s_mov_b32 m0, s15
	s_nop 0
	global_load_lds_dwordx4 v[126:127], off
	s_waitcnt vmcnt(8)
	s_waitcnt lgkmcnt(0)
	s_barrier
	s_waitcnt lgkmcnt(0)
	v_mfma_f32_16x16x32_bf16 v[178:181], v[38:41], v[98:101], 0
	v_mfma_f32_16x16x32_bf16 v[190:193], v[38:41], v[146:149], 0
	v_mfma_f32_16x16x32_bf16 v[202:205], v[38:41], v[154:157], 0
	v_mfma_f32_16x16x32_bf16 v[38:41], v[38:41], v[170:173], 0
	v_mfma_f32_16x16x32_bf16 v[178:181], v[42:45], v[142:145], v[178:181]
	v_mfma_f32_16x16x32_bf16 v[182:185], v[46:49], v[98:101], 0
	v_mfma_f32_16x16x32_bf16 v[190:193], v[42:45], v[150:153], v[190:193]
	v_mfma_f32_16x16x32_bf16 v[198:201], v[46:49], v[146:149], 0
	v_mfma_f32_16x16x32_bf16 v[202:205], v[42:45], v[164:167], v[202:205]
	v_mfma_f32_16x16x32_bf16 v[206:209], v[46:49], v[154:157], 0
	v_mfma_f32_16x16x32_bf16 v[38:41], v[42:45], v[174:177], v[38:41]
	v_mfma_f32_16x16x32_bf16 v[42:45], v[46:49], v[170:173], 0
	v_mfma_f32_16x16x32_bf16 v[182:185], v[50:53], v[142:145], v[182:185]
	v_mfma_f32_16x16x32_bf16 v[198:201], v[50:53], v[150:153], v[198:201]
	v_mfma_f32_16x16x32_bf16 v[206:209], v[50:53], v[164:167], v[206:209]
	v_mfma_f32_16x16x32_bf16 v[42:45], v[50:53], v[174:177], v[42:45]
	v_mfma_f32_16x16x32_bf16 v[46:49], v[54:57], v[98:101], 0
	v_mfma_f32_16x16x32_bf16 v[50:53], v[62:65], v[98:101], 0
	v_mfma_f32_16x16x32_bf16 v[46:49], v[58:61], v[142:145], v[46:49]
	v_mfma_f32_16x16x32_bf16 v[50:53], v[66:69], v[142:145], v[50:53]
	v_mfma_f32_16x16x32_bf16 v[98:101], v[54:57], v[146:149], 0
	v_mfma_f32_16x16x32_bf16 v[142:145], v[62:65], v[146:149], 0
	v_mfma_f32_16x16x32_bf16 v[146:149], v[54:57], v[154:157], 0
	v_mfma_f32_16x16x32_bf16 v[54:57], v[54:57], v[170:173], 0
	v_mfma_f32_16x16x32_bf16 v[98:101], v[58:61], v[150:153], v[98:101]
	v_mfma_f32_16x16x32_bf16 v[142:145], v[66:69], v[150:153], v[142:145]
	v_mfma_f32_16x16x32_bf16 v[146:149], v[58:61], v[164:167], v[146:149]
	v_mfma_f32_16x16x32_bf16 v[150:153], v[62:65], v[154:157], 0
	v_mfma_f32_16x16x32_bf16 v[54:57], v[58:61], v[174:177], v[54:57]
	v_mfma_f32_16x16x32_bf16 v[58:61], v[62:65], v[170:173], 0
	v_mfma_f32_16x16x32_bf16 v[150:153], v[66:69], v[164:167], v[150:153]
	v_mfma_f32_16x16x32_bf16 v[58:61], v[66:69], v[174:177], v[58:61]
	s_barrier
	ds_read_b128 v[62:65], v250
	ds_read_b128 v[66:69], v250 offset:1024
	ds_read_b128 v[154:157], v250 offset:2048
	ds_read_b128 v[164:167], v250 offset:3072
	ds_read_b128 v[170:173], v37
	ds_read_b128 v[174:177], v37 offset:1024
	ds_read_b128 v[210:213], v37 offset:2048
	ds_read_b128 v[214:217], v37 offset:3072
	v_lshl_add_u64 v[126:127], v[30:31], 0, s[28:29]
	s_mov_b32 m0, s5
	v_lshl_add_u64 v[158:159], v[126:127], 0, v[162:163]
	ds_read_b128 v[218:221], v36 offset:32768
	ds_read_b128 v[222:225], v36 offset:33792
	ds_read_b128 v[226:229], v36 offset:34816
	ds_read_b128 v[230:233], v36 offset:35840
	ds_read_b128 v[234:237], v36 offset:36864
	ds_read_b128 v[238:241], v36 offset:37888
	ds_read_b128 v[242:245], v36 offset:38912
	ds_read_b128 v[246:249], v36 offset:39936
	global_load_lds_dwordx4 v[158:159], off
	v_lshl_add_u64 v[126:127], v[126:127], 0, v[14:15]
	s_mov_b32 m0, s7
	s_nop 0
	global_load_lds_dwordx4 v[126:127], off
	s_waitcnt vmcnt(8)
	s_waitcnt lgkmcnt(0)
	s_barrier
	s_waitcnt lgkmcnt(0)
	v_mfma_f32_16x16x32_bf16 v[102:105], v[62:65], v[218:221], v[102:105]
	v_mfma_f32_16x16x32_bf16 v[106:109], v[154:157], v[218:221], v[106:109]
	v_mfma_f32_16x16x32_bf16 v[110:113], v[62:65], v[226:229], v[110:113]
	v_mfma_f32_16x16x32_bf16 v[114:117], v[154:157], v[226:229], v[114:117]
	v_mfma_f32_16x16x32_bf16 v[118:121], v[62:65], v[234:237], v[118:121]
	v_mfma_f32_16x16x32_bf16 v[122:125], v[154:157], v[234:237], v[122:125]
	v_mfma_f32_16x16x32_bf16 v[130:133], v[62:65], v[242:245], v[130:133]
	v_mfma_f32_16x16x32_bf16 v[134:137], v[154:157], v[242:245], v[134:137]
	v_mfma_f32_16x16x32_bf16 v[102:105], v[66:69], v[222:225], v[102:105]
	v_mfma_f32_16x16x32_bf16 v[106:109], v[164:167], v[222:225], v[106:109]
	v_mfma_f32_16x16x32_bf16 v[110:113], v[66:69], v[230:233], v[110:113]
	v_mfma_f32_16x16x32_bf16 v[114:117], v[164:167], v[230:233], v[114:117]
	v_mfma_f32_16x16x32_bf16 v[118:121], v[66:69], v[238:241], v[118:121]
	v_mfma_f32_16x16x32_bf16 v[122:125], v[164:167], v[238:241], v[122:125]
	v_mfma_f32_16x16x32_bf16 v[130:133], v[66:69], v[246:249], v[130:133]
	v_mfma_f32_16x16x32_bf16 v[134:137], v[164:167], v[246:249], v[134:137]
	v_mfma_f32_16x16x32_bf16 v[138:141], v[170:173], v[218:221], v[138:141]
	v_mfma_f32_16x16x32_bf16 v[70:73], v[210:213], v[218:221], v[70:73]
	v_mfma_f32_16x16x32_bf16 v[74:77], v[170:173], v[226:229], v[74:77]
	v_mfma_f32_16x16x32_bf16 v[78:81], v[210:213], v[226:229], v[78:81]
	v_mfma_f32_16x16x32_bf16 v[82:85], v[170:173], v[234:237], v[82:85]
	v_mfma_f32_16x16x32_bf16 v[86:89], v[210:213], v[234:237], v[86:89]
	v_mfma_f32_16x16x32_bf16 v[90:93], v[170:173], v[242:245], v[90:93]
	v_mfma_f32_16x16x32_bf16 v[94:97], v[210:213], v[242:245], v[94:97]
	v_mfma_f32_16x16x32_bf16 v[138:141], v[174:177], v[222:225], v[138:141]
	v_mfma_f32_16x16x32_bf16 v[70:73], v[214:217], v[222:225], v[70:73]
	v_mfma_f32_16x16x32_bf16 v[74:77], v[174:177], v[230:233], v[74:77]
	v_mfma_f32_16x16x32_bf16 v[78:81], v[214:217], v[230:233], v[78:81]
	v_mfma_f32_16x16x32_bf16 v[82:85], v[174:177], v[238:241], v[82:85]
	v_mfma_f32_16x16x32_bf16 v[86:89], v[214:217], v[238:241], v[86:89]
	v_mfma_f32_16x16x32_bf16 v[90:93], v[174:177], v[246:249], v[90:93]
	v_mfma_f32_16x16x32_bf16 v[94:97], v[214:217], v[246:249], v[94:97]
	s_barrier
	s_mov_b64 s[28:29], 0x180
	s_mov_b32 m0, s8
	v_lshl_add_u64 v[126:127], v[12:13], 0, s[28:29]
	s_mov_b64 s[30:31], 0x40180
	ds_read_b128 v[218:221], v36 offset:49152
	ds_read_b128 v[222:225], v36 offset:50176
	ds_read_b128 v[226:229], v36 offset:51200
	ds_read_b128 v[230:233], v36 offset:52224
	ds_read_b128 v[234:237], v36 offset:53248
	ds_read_b128 v[238:241], v36 offset:54272
	ds_read_b128 v[242:245], v36 offset:55296
	ds_read_b128 v[246:249], v36 offset:56320
	global_load_lds_dwordx4 v[126:127], off
	v_lshl_add_u64 v[126:127], v[20:21], 0, s[28:29]
	s_mov_b32 m0, s11
	v_lshl_add_u64 v[32:33], v[32:33], 0, s[30:31]
	global_load_lds_dwordx4 v[126:127], off
	v_lshl_add_u64 v[126:127], v[32:33], 0, v[162:163]
	s_mov_b32 m0, s13
	v_lshl_add_u64 v[32:33], v[32:33], 0, v[14:15]
	global_load_lds_dwordx4 v[126:127], off
	s_mov_b32 m0, s14
	s_nop 0
	global_load_lds_dwordx4 v[32:33], off
	v_lshl_add_u64 v[32:33], v[26:27], 0, s[28:29]
	s_mov_b32 m0, s9
	s_nop 0
	global_load_lds_dwordx4 v[32:33], off
	v_lshl_add_u64 v[32:33], v[28:29], 0, s[28:29]
	s_mov_b32 m0, s12
	s_nop 0
	global_load_lds_dwordx4 v[32:33], off
	s_waitcnt vmcnt(8)
	s_waitcnt lgkmcnt(0)
	s_barrier
	s_waitcnt lgkmcnt(0)
	v_mfma_f32_16x16x32_bf16 v[178:181], v[62:65], v[218:221], v[178:181]
	v_mfma_f32_16x16x32_bf16 v[182:185], v[154:157], v[218:221], v[182:185]
	v_mfma_f32_16x16x32_bf16 v[190:193], v[62:65], v[226:229], v[190:193]
	v_mfma_f32_16x16x32_bf16 v[198:201], v[154:157], v[226:229], v[198:201]
	v_mfma_f32_16x16x32_bf16 v[202:205], v[62:65], v[234:237], v[202:205]
	v_mfma_f32_16x16x32_bf16 v[206:209], v[154:157], v[234:237], v[206:209]
	v_mfma_f32_16x16x32_bf16 v[38:41], v[62:65], v[242:245], v[38:41]
	v_mfma_f32_16x16x32_bf16 v[42:45], v[154:157], v[242:245], v[42:45]
	v_mfma_f32_16x16x32_bf16 v[178:181], v[66:69], v[222:225], v[178:181]
	v_mfma_f32_16x16x32_bf16 v[182:185], v[164:167], v[222:225], v[182:185]
	v_mfma_f32_16x16x32_bf16 v[190:193], v[66:69], v[230:233], v[190:193]
	v_mfma_f32_16x16x32_bf16 v[198:201], v[164:167], v[230:233], v[198:201]
	v_mfma_f32_16x16x32_bf16 v[202:205], v[66:69], v[238:241], v[202:205]
	v_mfma_f32_16x16x32_bf16 v[206:209], v[164:167], v[238:241], v[206:209]
	v_mfma_f32_16x16x32_bf16 v[38:41], v[66:69], v[246:249], v[38:41]
	v_mfma_f32_16x16x32_bf16 v[42:45], v[164:167], v[246:249], v[42:45]
	v_mfma_f32_16x16x32_bf16 v[46:49], v[170:173], v[218:221], v[46:49]
	v_mfma_f32_16x16x32_bf16 v[50:53], v[210:213], v[218:221], v[50:53]
	v_mfma_f32_16x16x32_bf16 v[62:65], v[170:173], v[226:229], v[98:101]
	v_mfma_f32_16x16x32_bf16 v[66:69], v[210:213], v[226:229], v[142:145]
	v_mfma_f32_16x16x32_bf16 v[98:101], v[170:173], v[234:237], v[146:149]
	v_mfma_f32_16x16x32_bf16 v[142:145], v[210:213], v[234:237], v[150:153]
	v_mfma_f32_16x16x32_bf16 v[54:57], v[170:173], v[242:245], v[54:57]
	v_mfma_f32_16x16x32_bf16 v[58:61], v[210:213], v[242:245], v[58:61]
	v_mfma_f32_16x16x32_bf16 v[46:49], v[174:177], v[222:225], v[46:49]
	v_mfma_f32_16x16x32_bf16 v[50:53], v[214:217], v[222:225], v[50:53]
	v_mfma_f32_16x16x32_bf16 v[62:65], v[174:177], v[230:233], v[62:65]
	v_mfma_f32_16x16x32_bf16 v[66:69], v[214:217], v[230:233], v[66:69]
	v_mfma_f32_16x16x32_bf16 v[98:101], v[174:177], v[238:241], v[98:101]
	v_mfma_f32_16x16x32_bf16 v[142:145], v[214:217], v[238:241], v[142:145]
	v_mfma_f32_16x16x32_bf16 v[54:57], v[174:177], v[246:249], v[54:57]
	v_mfma_f32_16x16x32_bf16 v[58:61], v[214:217], v[246:249], v[58:61]
	s_barrier
	ds_read_b128 v[146:149], v186
	ds_read_b128 v[150:153], v186 offset:1024
	ds_read_b128 v[154:157], v186 offset:2048
	ds_read_b128 v[164:167], v186 offset:3072
	ds_read_b128 v[170:173], v187
	ds_read_b128 v[174:177], v187 offset:1024
	ds_read_b128 v[210:213], v187 offset:2048
	ds_read_b128 v[214:217], v187 offset:3072
	v_lshl_add_u64 v[30:31], v[30:31], 0, s[30:31]
	s_mov_b32 m0, s22
	v_lshl_add_u64 v[32:33], v[30:31], 0, v[162:163]
	ds_read_b128 v[218:221], v36
	ds_read_b128 v[222:225], v36 offset:1024
	ds_read_b128 v[226:229], v36 offset:2048
	ds_read_b128 v[230:233], v36 offset:3072
	ds_read_b128 v[234:237], v36 offset:4096
	ds_read_b128 v[238:241], v36 offset:5120
	ds_read_b128 v[242:245], v36 offset:6144
	ds_read_b128 v[246:249], v36 offset:7168
	global_load_lds_dwordx4 v[32:33], off
	v_lshl_add_u64 v[14:15], v[30:31], 0, v[14:15]
	s_mov_b32 m0, s18
	s_nop 0
	global_load_lds_dwordx4 v[14:15], off
	s_waitcnt vmcnt(8)
	s_waitcnt lgkmcnt(0)
	s_barrier
	s_waitcnt lgkmcnt(0)
	v_mfma_f32_16x16x32_bf16 v[30:33], v[146:149], v[218:221], v[102:105]
	v_mfma_f32_16x16x32_bf16 v[102:105], v[154:157], v[218:221], v[106:109]
	v_mfma_f32_16x16x32_bf16 v[106:109], v[146:149], v[226:229], v[110:113]
	v_mfma_f32_16x16x32_bf16 v[110:113], v[154:157], v[226:229], v[114:117]
	v_mfma_f32_16x16x32_bf16 v[114:117], v[146:149], v[234:237], v[118:121]
	v_mfma_f32_16x16x32_bf16 v[118:121], v[154:157], v[234:237], v[122:125]
	v_mfma_f32_16x16x32_bf16 v[122:125], v[146:149], v[242:245], v[130:133]
	v_mfma_f32_16x16x32_bf16 v[130:133], v[154:157], v[242:245], v[134:137]
	v_mfma_f32_16x16x32_bf16 v[30:33], v[150:153], v[222:225], v[30:33]
	v_mfma_f32_16x16x32_bf16 v[102:105], v[164:167], v[222:225], v[102:105]
	v_mfma_f32_16x16x32_bf16 v[106:109], v[150:153], v[230:233], v[106:109]
	v_mfma_f32_16x16x32_bf16 v[110:113], v[164:167], v[230:233], v[110:113]
	v_mfma_f32_16x16x32_bf16 v[114:117], v[150:153], v[238:241], v[114:117]
	v_mfma_f32_16x16x32_bf16 v[118:121], v[164:167], v[238:241], v[118:121]
	v_mfma_f32_16x16x32_bf16 v[122:125], v[150:153], v[246:249], v[122:125]
	v_mfma_f32_16x16x32_bf16 v[130:133], v[164:167], v[246:249], v[130:133]
	v_mfma_f32_16x16x32_bf16 v[134:137], v[170:173], v[218:221], v[138:141]
	v_mfma_f32_16x16x32_bf16 v[70:73], v[210:213], v[218:221], v[70:73]
	v_mfma_f32_16x16x32_bf16 v[74:77], v[170:173], v[226:229], v[74:77]
	v_mfma_f32_16x16x32_bf16 v[78:81], v[210:213], v[226:229], v[78:81]
	v_mfma_f32_16x16x32_bf16 v[82:85], v[170:173], v[234:237], v[82:85]
	v_mfma_f32_16x16x32_bf16 v[86:89], v[210:213], v[234:237], v[86:89]
	v_mfma_f32_16x16x32_bf16 v[90:93], v[170:173], v[242:245], v[90:93]
	v_mfma_f32_16x16x32_bf16 v[94:97], v[210:213], v[242:245], v[94:97]
	v_mfma_f32_16x16x32_bf16 v[134:137], v[174:177], v[222:225], v[134:137]
	v_mfma_f32_16x16x32_bf16 v[70:73], v[214:217], v[222:225], v[70:73]
	v_mfma_f32_16x16x32_bf16 v[74:77], v[174:177], v[230:233], v[74:77]
	v_mfma_f32_16x16x32_bf16 v[78:81], v[214:217], v[230:233], v[78:81]
	v_mfma_f32_16x16x32_bf16 v[82:85], v[174:177], v[238:241], v[82:85]
	v_mfma_f32_16x16x32_bf16 v[86:89], v[214:217], v[238:241], v[86:89]
	v_mfma_f32_16x16x32_bf16 v[90:93], v[174:177], v[246:249], v[90:93]
	v_mfma_f32_16x16x32_bf16 v[94:97], v[214:217], v[246:249], v[94:97]
	s_barrier
	s_mov_b32 m0, s19
	ds_read_b128 v[138:141], v36 offset:16384
	ds_read_b128 v[218:221], v36 offset:17408
	ds_read_b128 v[222:225], v36 offset:18432
	ds_read_b128 v[226:229], v36 offset:19456
	ds_read_b128 v[230:233], v36 offset:20480
	ds_read_b128 v[234:237], v36 offset:21504
	ds_read_b128 v[238:241], v36 offset:22528
	ds_read_b128 v[242:245], v36 offset:23552
	global_load_lds_dwordx4 v[12:13], off
	s_mov_b32 m0, s20
	s_nop 0
	global_load_lds_dwordx4 v[20:21], off
	s_mov_b32 m0, s17
	s_nop 0
	global_load_lds_dwordx4 v[22:23], off
	s_mov_b32 m0, s21
	s_nop 0
	global_load_lds_dwordx4 v[24:25], off
	s_mov_b32 m0, s10
	s_nop 0
	global_load_lds_dwordx4 v[26:27], off
	s_mov_b32 m0, s15
	s_nop 0
	global_load_lds_dwordx4 v[28:29], off
	s_waitcnt vmcnt(8)
	s_waitcnt lgkmcnt(0)
	s_barrier
	s_waitcnt lgkmcnt(0)
	v_mfma_f32_16x16x32_bf16 v[12:15], v[146:149], v[138:141], v[178:181]
	v_mfma_f32_16x16x32_bf16 v[20:23], v[154:157], v[138:141], v[182:185]
	v_mfma_f32_16x16x32_bf16 v[24:27], v[146:149], v[222:225], v[190:193]
	v_mfma_f32_16x16x32_bf16 v[178:181], v[154:157], v[222:225], v[198:201]
	v_mfma_f32_16x16x32_bf16 v[182:185], v[146:149], v[230:233], v[202:205]
	v_mfma_f32_16x16x32_bf16 v[190:193], v[154:157], v[230:233], v[206:209]
	v_mfma_f32_16x16x32_bf16 v[38:41], v[146:149], v[238:241], v[38:41]
	v_mfma_f32_16x16x32_bf16 v[42:45], v[154:157], v[238:241], v[42:45]
	v_mfma_f32_16x16x32_bf16 v[12:15], v[150:153], v[218:221], v[12:15]
	v_mfma_f32_16x16x32_bf16 v[20:23], v[164:167], v[218:221], v[20:23]
	v_mfma_f32_16x16x32_bf16 v[24:27], v[150:153], v[226:229], v[24:27]
	v_mfma_f32_16x16x32_bf16 v[178:181], v[164:167], v[226:229], v[178:181]
	v_mfma_f32_16x16x32_bf16 v[182:185], v[150:153], v[234:237], v[182:185]
	v_mfma_f32_16x16x32_bf16 v[190:193], v[164:167], v[234:237], v[190:193]
	v_mfma_f32_16x16x32_bf16 v[38:41], v[150:153], v[242:245], v[38:41]
	v_mfma_f32_16x16x32_bf16 v[42:45], v[164:167], v[242:245], v[42:45]
	v_mfma_f32_16x16x32_bf16 v[46:49], v[170:173], v[138:141], v[46:49]
	v_mfma_f32_16x16x32_bf16 v[50:53], v[210:213], v[138:141], v[50:53]
	v_mfma_f32_16x16x32_bf16 v[62:65], v[170:173], v[222:225], v[62:65]
	v_mfma_f32_16x16x32_bf16 v[66:69], v[210:213], v[222:225], v[66:69]
	v_mfma_f32_16x16x32_bf16 v[98:101], v[170:173], v[230:233], v[98:101]
	v_mfma_f32_16x16x32_bf16 v[138:141], v[210:213], v[230:233], v[142:145]
	v_mfma_f32_16x16x32_bf16 v[54:57], v[170:173], v[238:241], v[54:57]
	v_mfma_f32_16x16x32_bf16 v[58:61], v[210:213], v[238:241], v[58:61]
	v_mfma_f32_16x16x32_bf16 v[46:49], v[174:177], v[218:221], v[46:49]
	v_mfma_f32_16x16x32_bf16 v[50:53], v[214:217], v[218:221], v[50:53]
	v_mfma_f32_16x16x32_bf16 v[62:65], v[174:177], v[226:229], v[62:65]
	v_mfma_f32_16x16x32_bf16 v[66:69], v[214:217], v[226:229], v[66:69]
	v_mfma_f32_16x16x32_bf16 v[98:101], v[174:177], v[234:237], v[98:101]
	v_mfma_f32_16x16x32_bf16 v[138:141], v[214:217], v[234:237], v[138:141]
	v_mfma_f32_16x16x32_bf16 v[54:57], v[174:177], v[242:245], v[54:57]
	v_mfma_f32_16x16x32_bf16 v[58:61], v[214:217], v[242:245], v[58:61]
	s_barrier
	ds_read_b128 v[142:145], v250
	ds_read_b128 v[146:149], v250 offset:1024
	ds_read_b128 v[150:153], v250 offset:2048
	ds_read_b128 v[154:157], v250 offset:3072
	ds_read_b128 v[164:167], v37
	ds_read_b128 v[170:173], v37 offset:1024
	ds_read_b128 v[174:177], v37 offset:2048
	ds_read_b128 v[198:201], v37 offset:3072
	s_mov_b32 m0, s5
	ds_read_b128 v[202:205], v36 offset:32768
	ds_read_b128 v[206:209], v36 offset:33792
	ds_read_b128 v[210:213], v36 offset:34816
	ds_read_b128 v[214:217], v36 offset:35840
	ds_read_b128 v[218:221], v36 offset:36864
	ds_read_b128 v[222:225], v36 offset:37888
	ds_read_b128 v[226:229], v36 offset:38912
	ds_read_b128 v[230:233], v36 offset:39936
	global_load_lds_dwordx4 v[0:1], off
	s_mov_b32 m0, s7
	s_nop 0
	global_load_lds_dwordx4 v[2:3], off
	s_waitcnt vmcnt(8)
	s_waitcnt lgkmcnt(0)
	s_barrier
	s_waitcnt lgkmcnt(0)
	v_mfma_f32_16x16x32_bf16 v[0:3], v[142:145], v[202:205], v[30:33]
	v_mfma_f32_16x16x32_bf16 v[28:31], v[150:153], v[202:205], v[102:105]
	v_mfma_f32_16x16x32_bf16 v[102:105], v[142:145], v[210:213], v[106:109]
	v_mfma_f32_16x16x32_bf16 v[106:109], v[150:153], v[210:213], v[110:113]
	v_mfma_f32_16x16x32_bf16 v[110:113], v[142:145], v[218:221], v[114:117]
	v_mfma_f32_16x16x32_bf16 v[114:117], v[150:153], v[218:221], v[118:121]
	v_mfma_f32_16x16x32_bf16 v[118:121], v[142:145], v[226:229], v[122:125]
	v_mfma_f32_16x16x32_bf16 v[122:125], v[150:153], v[226:229], v[130:133]
	v_mfma_f32_16x16x32_bf16 v[0:3], v[146:149], v[206:209], v[0:3]
	v_mfma_f32_16x16x32_bf16 v[28:31], v[154:157], v[206:209], v[28:31]
	v_mfma_f32_16x16x32_bf16 v[102:105], v[146:149], v[214:217], v[102:105]
	v_mfma_f32_16x16x32_bf16 v[106:109], v[154:157], v[214:217], v[106:109]
	v_mfma_f32_16x16x32_bf16 v[110:113], v[146:149], v[222:225], v[110:113]
	v_mfma_f32_16x16x32_bf16 v[114:117], v[154:157], v[222:225], v[114:117]
	v_mfma_f32_16x16x32_bf16 v[118:121], v[146:149], v[230:233], v[118:121]
	v_mfma_f32_16x16x32_bf16 v[122:125], v[154:157], v[230:233], v[122:125]
	v_mfma_f32_16x16x32_bf16 v[130:133], v[164:167], v[202:205], v[134:137]
	v_mfma_f32_16x16x32_bf16 v[70:73], v[174:177], v[202:205], v[70:73]
	v_mfma_f32_16x16x32_bf16 v[74:77], v[164:167], v[210:213], v[74:77]
	v_mfma_f32_16x16x32_bf16 v[78:81], v[174:177], v[210:213], v[78:81]
	v_mfma_f32_16x16x32_bf16 v[82:85], v[164:167], v[218:221], v[82:85]
	v_mfma_f32_16x16x32_bf16 v[86:89], v[174:177], v[218:221], v[86:89]
	v_mfma_f32_16x16x32_bf16 v[90:93], v[164:167], v[226:229], v[90:93]
	v_mfma_f32_16x16x32_bf16 v[94:97], v[174:177], v[226:229], v[94:97]
	v_mfma_f32_16x16x32_bf16 v[130:133], v[170:173], v[206:209], v[130:133]
	v_mfma_f32_16x16x32_bf16 v[70:73], v[198:201], v[206:209], v[70:73]
	v_mfma_f32_16x16x32_bf16 v[74:77], v[170:173], v[214:217], v[74:77]
	v_mfma_f32_16x16x32_bf16 v[78:81], v[198:201], v[214:217], v[78:81]
	v_mfma_f32_16x16x32_bf16 v[82:85], v[170:173], v[222:225], v[82:85]
	v_mfma_f32_16x16x32_bf16 v[86:89], v[198:201], v[222:225], v[86:89]
	v_mfma_f32_16x16x32_bf16 v[90:93], v[170:173], v[230:233], v[90:93]
	v_mfma_f32_16x16x32_bf16 v[94:97], v[198:201], v[230:233], v[94:97]
	s_barrier
	s_mov_b32 m0, s8
	ds_read_b128 v[134:137], v36 offset:49152
	ds_read_b128 v[202:205], v36 offset:50176
	ds_read_b128 v[206:209], v36 offset:51200
	ds_read_b128 v[210:213], v36 offset:52224
	ds_read_b128 v[214:217], v36 offset:53248
	ds_read_b128 v[218:221], v36 offset:54272
	ds_read_b128 v[222:225], v36 offset:55296
	ds_read_b128 v[226:229], v36 offset:56320
	global_load_lds_dwordx4 v[6:7], off
	s_mov_b32 m0, s11
	s_nop 0
	global_load_lds_dwordx4 v[8:9], off
	s_mov_b32 m0, s13
	s_nop 0
	global_load_lds_dwordx4 v[16:17], off
	s_mov_b32 m0, s14
	s_nop 0
	global_load_lds_dwordx4 v[18:19], off
	s_mov_b32 m0, s9
	s_nop 0
	global_load_lds_dwordx4 v[4:5], off
	s_mov_b32 m0, s12
	s_nop 0
	global_load_lds_dwordx4 v[10:11], off
	s_waitcnt vmcnt(8)
	s_waitcnt lgkmcnt(0)
	s_barrier
	s_waitcnt lgkmcnt(0)
	v_mfma_f32_16x16x32_bf16 v[4:7], v[142:145], v[134:137], v[12:15]
	v_mfma_f32_16x16x32_bf16 v[8:11], v[150:153], v[134:137], v[20:23]
	v_mfma_f32_16x16x32_bf16 v[12:15], v[142:145], v[206:209], v[24:27]
	v_mfma_f32_16x16x32_bf16 v[16:19], v[150:153], v[206:209], v[178:181]
	v_mfma_f32_16x16x32_bf16 v[20:23], v[142:145], v[214:217], v[182:185]
	v_mfma_f32_16x16x32_bf16 v[24:27], v[150:153], v[214:217], v[190:193]
	v_mfma_f32_16x16x32_bf16 v[36:39], v[142:145], v[222:225], v[38:41]
	v_mfma_f32_16x16x32_bf16 v[40:43], v[150:153], v[222:225], v[42:45]
	v_mfma_f32_16x16x32_bf16 v[4:7], v[146:149], v[202:205], v[4:7]
	v_mfma_f32_16x16x32_bf16 v[8:11], v[154:157], v[202:205], v[8:11]
	v_mfma_f32_16x16x32_bf16 v[12:15], v[146:149], v[210:213], v[12:15]
	v_mfma_f32_16x16x32_bf16 v[16:19], v[154:157], v[210:213], v[16:19]
	v_mfma_f32_16x16x32_bf16 v[20:23], v[146:149], v[218:221], v[20:23]
	v_mfma_f32_16x16x32_bf16 v[24:27], v[154:157], v[218:221], v[24:27]
	v_mfma_f32_16x16x32_bf16 v[36:39], v[146:149], v[226:229], v[36:39]
	v_mfma_f32_16x16x32_bf16 v[40:43], v[154:157], v[226:229], v[40:43]
	v_mfma_f32_16x16x32_bf16 v[44:47], v[164:167], v[134:137], v[46:49]
	v_mfma_f32_16x16x32_bf16 v[48:51], v[174:177], v[134:137], v[50:53]
	v_mfma_f32_16x16x32_bf16 v[62:65], v[164:167], v[206:209], v[62:65]
	v_mfma_f32_16x16x32_bf16 v[66:69], v[174:177], v[206:209], v[66:69]
	v_mfma_f32_16x16x32_bf16 v[98:101], v[164:167], v[214:217], v[98:101]
	v_mfma_f32_16x16x32_bf16 v[134:137], v[174:177], v[214:217], v[138:141]
	v_mfma_f32_16x16x32_bf16 v[52:55], v[164:167], v[222:225], v[54:57]
	v_mfma_f32_16x16x32_bf16 v[56:59], v[174:177], v[222:225], v[58:61]
	v_mfma_f32_16x16x32_bf16 v[44:47], v[170:173], v[202:205], v[44:47]
	v_mfma_f32_16x16x32_bf16 v[48:51], v[198:201], v[202:205], v[48:51]
	v_mfma_f32_16x16x32_bf16 v[62:65], v[170:173], v[210:213], v[62:65]
	v_mfma_f32_16x16x32_bf16 v[66:69], v[198:201], v[210:213], v[66:69]
	v_mfma_f32_16x16x32_bf16 v[98:101], v[170:173], v[218:221], v[98:101]
	v_mfma_f32_16x16x32_bf16 v[134:137], v[198:201], v[218:221], v[134:137]
	v_mfma_f32_16x16x32_bf16 v[52:55], v[170:173], v[226:229], v[52:55]
	v_mfma_f32_16x16x32_bf16 v[56:59], v[198:201], v[226:229], v[56:59]
	s_barrier
	v_readlane_b32 vcc_lo, v253, 0
	s_lshr_b32 vcc_hi, vcc_lo, 2
	s_and_b32 vcc_lo, vcc_lo, 3
	s_mul_i32 s100, vcc_hi, 0x300000
	s_lshr_b32 s101, vcc_lo, 2
	s_lshl_b32 s101, s101, 20
	s_add_u32 s100, s100, s101
	s_and_b32 s101, vcc_lo, 3
	s_lshl_b32 s101, s101, 10
	s_add_u32 s100, s100, s101
	s_lshl_b32 s101, s4, 20
	s_sub_u32 s100, s100, s101
	s_lshl_b32 s101, s2, 10
	s_sub_u32 s100, s100, s101
	s_add_u32 s100, s100, 0x70e2000
	s_load_dwordx2 vcc, s[40:41], 0xf0
	s_waitcnt lgkmcnt(0)
	s_add_u32 vcc_lo, vcc_lo, s100
	s_addc_u32 vcc_hi, vcc_hi, 0
	v_mov_b32_e32 v128, vcc_lo
	v_mov_b32_e32 v129, vcc_hi
	v_lshl_add_u32 v32, s4, 8, v34
	v_lshl_or_b32 v33, s2, 8, v35
	v_or_b32_e32 v34, s3, v33
	v_ashrrev_i32_e32 v33, 31, v32
	v_ashrrev_i32_e32 v35, 31, v34
	v_lshlrev_b64 v[60:61], 12, v[32:33]
	v_lshl_add_u64 v[60:61], v[128:129], 0, v[60:61]
	v_lshlrev_b64 v[34:35], 2, v[34:35]
	v_lshl_add_u64 v[60:61], v[60:61], 0, v[34:35]
	global_store_dwordx4 v[60:61], v[0:3], off sc0 sc1
	global_store_dwordx4 v[60:61], v[28:31], off offset:64 sc0 sc1
	global_store_dwordx4 v[60:61], v[130:133], off offset:512 sc0 sc1
	global_store_dwordx4 v[60:61], v[70:73], off offset:576 sc0 sc1
	v_or_b32_e32 v0, 16, v32
	v_ashrrev_i32_e32 v1, 31, v0
	v_lshlrev_b64 v[0:1], 12, v[0:1]
	v_lshl_add_u64 v[0:1], v[128:129], 0, v[0:1]
	v_lshl_add_u64 v[0:1], v[0:1], 0, v[34:35]
	global_store_dwordx4 v[0:1], v[102:105], off sc0 sc1
	global_store_dwordx4 v[0:1], v[106:109], off offset:64 sc0 sc1
	global_store_dwordx4 v[0:1], v[74:77], off offset:512 sc0 sc1
	global_store_dwordx4 v[0:1], v[78:81], off offset:576 sc0 sc1
	v_or_b32_e32 v0, 32, v32
	v_ashrrev_i32_e32 v1, 31, v0
	v_lshlrev_b64 v[0:1], 12, v[0:1]
	v_lshl_add_u64 v[0:1], v[128:129], 0, v[0:1]
	v_lshl_add_u64 v[0:1], v[0:1], 0, v[34:35]
	global_store_dwordx4 v[0:1], v[110:113], off sc0 sc1
	global_store_dwordx4 v[0:1], v[114:117], off offset:64 sc0 sc1
	global_store_dwordx4 v[0:1], v[82:85], off offset:512 sc0 sc1
	global_store_dwordx4 v[0:1], v[86:89], off offset:576 sc0 sc1
	v_or_b32_e32 v0, 48, v32
	v_ashrrev_i32_e32 v1, 31, v0
	v_lshlrev_b64 v[0:1], 12, v[0:1]
	v_lshl_add_u64 v[0:1], v[128:129], 0, v[0:1]
	v_lshl_add_u64 v[0:1], v[0:1], 0, v[34:35]
	v_add_co_u32_e32 v2, vcc, s23, v60
	global_store_dwordx4 v[0:1], v[118:121], off sc0 sc1
	global_store_dwordx4 v[0:1], v[122:125], off offset:64 sc0 sc1
	global_store_dwordx4 v[0:1], v[90:93], off offset:512 sc0 sc1
	global_store_dwordx4 v[0:1], v[94:97], off offset:576 sc0 sc1
	s_mov_b64 s[2:3], 0x80000
	v_addc_co_u32_e32 v3, vcc, 0, v61, vcc
	v_lshl_add_u64 v[0:1], v[60:61], 0, s[2:3]
	global_store_dwordx4 v[0:1], v[4:7], off sc0 sc1
	global_store_dwordx4 v[0:1], v[8:11], off offset:64 sc0 sc1
	global_store_dwordx4 v[0:1], v[44:47], off offset:512 sc0 sc1
	global_store_dwordx4 v[0:1], v[48:51], off offset:576 sc0 sc1
	s_mov_b64 s[2:3], 0x90000
	v_add_co_u32_e32 v2, vcc, s24, v60
	v_lshl_add_u64 v[0:1], v[60:61], 0, s[2:3]
	s_nop 0
	v_addc_co_u32_e32 v3, vcc, 0, v61, vcc
	s_mov_b64 s[2:3], 0xa0000
	global_store_dwordx4 v[0:1], v[12:15], off sc0 sc1
	global_store_dwordx4 v[0:1], v[16:19], off offset:64 sc0 sc1
	global_store_dwordx4 v[0:1], v[62:65], off offset:512 sc0 sc1
	global_store_dwordx4 v[0:1], v[66:69], off offset:576 sc0 sc1
	v_lshl_add_u64 v[0:1], v[60:61], 0, s[2:3]
	s_mov_b32 s2, 0xa0000
	v_add_co_u32_e32 v2, vcc, s2, v60
	s_mov_b32 s2, 0xb0000
	s_nop 0
	v_addc_co_u32_e32 v3, vcc, 0, v61, vcc
	global_store_dwordx4 v[0:1], v[20:23], off sc0 sc1
	global_store_dwordx4 v[0:1], v[24:27], off offset:64 sc0 sc1
	global_store_dwordx4 v[0:1], v[98:101], off offset:512 sc0 sc1
	global_store_dwordx4 v[0:1], v[134:137], off offset:576 sc0 sc1
	v_add_co_u32_e32 v2, vcc, s2, v60
	v_lshl_add_u64 v[0:1], v[60:61], 0, s[26:27]
	s_nop 0
	v_addc_co_u32_e32 v3, vcc, 0, v61, vcc
	global_store_dwordx4 v[0:1], v[36:39], off sc0 sc1
	global_store_dwordx4 v[0:1], v[40:43], off offset:64 sc0 sc1
	global_store_dwordx4 v[0:1], v[52:55], off offset:512 sc0 sc1
	global_store_dwordx4 v[0:1], v[56:59], off offset:576 sc0 sc1
	s_waitcnt vmcnt(0)
	s_cmpk_gt_u32 s6, 0xff
	s_cbranch_scc1 .LBB0_1631
	s_barrier

.LBB0_1778:
	s_cmp_eq_u32 s11, 12
	s_cselect_b64 vcc, -1, 0
	s_add_i32 s13, s33, 0x100
	s_add_i32 s14, s92, 0x100
	v_lshl_add_u64 v[164:165], v[154:155], 0, s[44:45]
	v_add_u32_e32 v178, s13, v157
	v_add_u32_e32 v202, s14, v157
	v_cndmask_b32_e32 v187, v165, v149, vcc
	v_cndmask_b32_e32 v186, v164, v148, vcc
	ds_read_b128 v[164:167], v178
	ds_read_b128 v[170:173], v178 offset:1024
	ds_read_b128 v[174:177], v178 offset:2048
	ds_read_b128 v[178:181], v178 offset:3072
	ds_read_b128 v[182:185], v202
	ds_read_b128 v[190:193], v202 offset:1024
	ds_read_b128 v[198:201], v202 offset:2048
	ds_read_b128 v[202:205], v202 offset:3072
	v_cndmask_b32_e32 v239, v153, v151, vcc
	v_cndmask_b32_e32 v238, v152, v150, vcc
	v_lshl_add_u64 v[240:241], v[154:155], 0, v[142:143]
	s_add_i32 m0, s20, 0xc000
	ds_read_b128 v[206:209], v159
	ds_read_b128 v[210:213], v159 offset:1024
	ds_read_b128 v[214:217], v159 offset:2048
	ds_read_b128 v[218:221], v159 offset:3072
	ds_read_b128 v[222:225], v159 offset:4096
	ds_read_b128 v[226:229], v159 offset:5120
	ds_read_b128 v[230:233], v159 offset:6144
	ds_read_b128 v[234:237], v159 offset:7168
	global_load_lds_dwordx4 v[240:241], off
	v_lshl_add_u64 v[240:241], v[154:155], 0, v[140:141]
	s_add_i32 m0, s20, 0xe000
	s_nop 0
	global_load_lds_dwordx4 v[240:241], off
	s_waitcnt vmcnt(8)
	s_waitcnt lgkmcnt(0)
	s_barrier
	s_waitcnt lgkmcnt(0)
	v_mfma_f32_16x16x32_bf16 v[124:127], v[164:167], v[206:209], v[124:127]
	v_mfma_f32_16x16x32_bf16 v[116:119], v[174:177], v[206:209], v[116:119]
	v_mfma_f32_16x16x32_bf16 v[108:111], v[164:167], v[214:217], v[108:111]
	v_mfma_f32_16x16x32_bf16 v[100:103], v[174:177], v[214:217], v[100:103]
	v_mfma_f32_16x16x32_bf16 v[92:95], v[164:167], v[222:225], v[92:95]
	v_mfma_f32_16x16x32_bf16 v[84:87], v[174:177], v[222:225], v[84:87]
	v_mfma_f32_16x16x32_bf16 v[76:79], v[164:167], v[230:233], v[76:79]
	v_mfma_f32_16x16x32_bf16 v[68:71], v[174:177], v[230:233], v[68:71]
	v_mfma_f32_16x16x32_bf16 v[124:127], v[170:173], v[210:213], v[124:127]
	v_mfma_f32_16x16x32_bf16 v[116:119], v[178:181], v[210:213], v[116:119]
	v_mfma_f32_16x16x32_bf16 v[108:111], v[170:173], v[218:221], v[108:111]
	v_mfma_f32_16x16x32_bf16 v[100:103], v[178:181], v[218:221], v[100:103]
	v_mfma_f32_16x16x32_bf16 v[92:95], v[170:173], v[226:229], v[92:95]
	v_mfma_f32_16x16x32_bf16 v[84:87], v[178:181], v[226:229], v[84:87]
	v_mfma_f32_16x16x32_bf16 v[76:79], v[170:173], v[234:237], v[76:79]
	v_mfma_f32_16x16x32_bf16 v[68:71], v[178:181], v[234:237], v[68:71]
	v_mfma_f32_16x16x32_bf16 v[120:123], v[182:185], v[206:209], v[120:123]
	v_mfma_f32_16x16x32_bf16 v[112:115], v[198:201], v[206:209], v[112:115]
	v_mfma_f32_16x16x32_bf16 v[104:107], v[182:185], v[214:217], v[104:107]
	v_mfma_f32_16x16x32_bf16 v[96:99], v[198:201], v[214:217], v[96:99]
	v_mfma_f32_16x16x32_bf16 v[88:91], v[182:185], v[222:225], v[88:91]
	v_mfma_f32_16x16x32_bf16 v[80:83], v[198:201], v[222:225], v[80:83]
	v_mfma_f32_16x16x32_bf16 v[72:75], v[182:185], v[230:233], v[72:75]
	v_mfma_f32_16x16x32_bf16 v[64:67], v[198:201], v[230:233], v[64:67]
	v_mfma_f32_16x16x32_bf16 v[120:123], v[190:193], v[210:213], v[120:123]
	v_mfma_f32_16x16x32_bf16 v[112:115], v[202:205], v[210:213], v[112:115]
	v_mfma_f32_16x16x32_bf16 v[104:107], v[190:193], v[218:221], v[104:107]
	v_mfma_f32_16x16x32_bf16 v[96:99], v[202:205], v[218:221], v[96:99]
	v_mfma_f32_16x16x32_bf16 v[88:91], v[190:193], v[226:229], v[88:91]
	v_mfma_f32_16x16x32_bf16 v[80:83], v[202:205], v[226:229], v[80:83]
	v_mfma_f32_16x16x32_bf16 v[72:75], v[190:193], v[234:237], v[72:75]
	v_mfma_f32_16x16x32_bf16 v[64:67], v[202:205], v[234:237], v[64:67]
	s_barrier
	s_add_i32 s13, s13, s19
	v_lshl_add_u64 v[240:241], v[238:239], 0, v[162:163]
	s_mov_b32 m0, s13
	ds_read_b128 v[206:209], v159 offset:16384
	ds_read_b128 v[210:213], v159 offset:17408
	ds_read_b128 v[214:217], v159 offset:18432
	ds_read_b128 v[218:221], v159 offset:19456
	ds_read_b128 v[222:225], v159 offset:20480
	ds_read_b128 v[226:229], v159 offset:21504
	ds_read_b128 v[230:233], v159 offset:22528
	ds_read_b128 v[234:237], v159 offset:23552
	global_load_lds_dwordx4 v[240:241], off
	v_lshl_add_u64 v[242:243], v[238:239], 0, v[136:137]
	s_add_i32 m0, s13, 0x2000
	v_lshl_add_u64 v[244:245], v[238:239], 0, s[78:79]
	s_add_i32 s13, s14, s19
	global_load_lds_dwordx4 v[242:243], off
	v_lshl_add_u64 v[246:247], v[244:245], 0, v[162:163]
	s_mov_b32 m0, s13
	v_lshl_add_u64 v[244:245], v[244:245], 0, v[136:137]
	global_load_lds_dwordx4 v[246:247], off
	s_add_i32 m0, s13, 0x2000
	v_lshl_add_u64 v[246:247], v[186:187], 0, v[134:135]
	global_load_lds_dwordx4 v[244:245], off
	v_lshl_add_u64 v[244:245], v[186:187], 0, v[132:133]
	s_mov_b32 m0, s20
	s_nop 0
	global_load_lds_dwordx4 v[244:245], off
	s_mov_b32 m0, s21
	s_nop 0
	global_load_lds_dwordx4 v[246:247], off
	s_waitcnt vmcnt(8)
	s_waitcnt lgkmcnt(0)
	s_barrier
	s_waitcnt lgkmcnt(0)
	v_mfma_f32_16x16x32_bf16 v[60:63], v[164:167], v[206:209], v[60:63]
	v_mfma_f32_16x16x32_bf16 v[52:55], v[174:177], v[206:209], v[52:55]
	v_mfma_f32_16x16x32_bf16 v[44:47], v[164:167], v[214:217], v[44:47]
	v_mfma_f32_16x16x32_bf16 v[36:39], v[174:177], v[214:217], v[36:39]
	v_mfma_f32_16x16x32_bf16 v[28:31], v[164:167], v[222:225], v[28:31]
	v_mfma_f32_16x16x32_bf16 v[20:23], v[174:177], v[222:225], v[20:23]
	v_mfma_f32_16x16x32_bf16 v[12:15], v[164:167], v[230:233], v[12:15]
	v_mfma_f32_16x16x32_bf16 v[4:7], v[174:177], v[230:233], v[4:7]
	v_mfma_f32_16x16x32_bf16 v[60:63], v[170:173], v[210:213], v[60:63]
	v_mfma_f32_16x16x32_bf16 v[52:55], v[178:181], v[210:213], v[52:55]
	v_mfma_f32_16x16x32_bf16 v[44:47], v[170:173], v[218:221], v[44:47]
	v_mfma_f32_16x16x32_bf16 v[36:39], v[178:181], v[218:221], v[36:39]
	v_mfma_f32_16x16x32_bf16 v[28:31], v[170:173], v[226:229], v[28:31]
	v_mfma_f32_16x16x32_bf16 v[20:23], v[178:181], v[226:229], v[20:23]
	v_mfma_f32_16x16x32_bf16 v[12:15], v[170:173], v[234:237], v[12:15]
	v_mfma_f32_16x16x32_bf16 v[4:7], v[178:181], v[234:237], v[4:7]
	v_mfma_f32_16x16x32_bf16 v[56:59], v[182:185], v[206:209], v[56:59]
	v_mfma_f32_16x16x32_bf16 v[48:51], v[198:201], v[206:209], v[48:51]
	v_mfma_f32_16x16x32_bf16 v[40:43], v[182:185], v[214:217], v[40:43]
	v_mfma_f32_16x16x32_bf16 v[32:35], v[198:201], v[214:217], v[32:35]
	v_mfma_f32_16x16x32_bf16 v[24:27], v[182:185], v[222:225], v[24:27]
	v_mfma_f32_16x16x32_bf16 v[16:19], v[198:201], v[222:225], v[16:19]
	v_mfma_f32_16x16x32_bf16 v[8:11], v[182:185], v[230:233], v[8:11]
	v_mfma_f32_16x16x32_bf16 v[0:3], v[198:201], v[230:233], v[0:3]
	v_mfma_f32_16x16x32_bf16 v[56:59], v[190:193], v[210:213], v[56:59]
	v_mfma_f32_16x16x32_bf16 v[48:51], v[202:205], v[210:213], v[48:51]
	v_mfma_f32_16x16x32_bf16 v[40:43], v[190:193], v[218:221], v[40:43]
	v_mfma_f32_16x16x32_bf16 v[32:35], v[202:205], v[218:221], v[32:35]
	v_mfma_f32_16x16x32_bf16 v[24:27], v[190:193], v[226:229], v[24:27]
	v_mfma_f32_16x16x32_bf16 v[16:19], v[202:205], v[226:229], v[16:19]
	v_mfma_f32_16x16x32_bf16 v[8:11], v[190:193], v[234:237], v[8:11]
	v_mfma_f32_16x16x32_bf16 v[0:3], v[202:205], v[234:237], v[0:3]
	s_barrier
	s_add_i32 s13, s93, 0x100
	s_add_i32 s14, s82, 0x100
	v_add_u32_e32 v178, s13, v157
	v_add_u32_e32 v202, s14, v157
	ds_read_b128 v[164:167], v178
	ds_read_b128 v[170:173], v178 offset:1024
	ds_read_b128 v[174:177], v178 offset:2048
	ds_read_b128 v[178:181], v178 offset:3072
	ds_read_b128 v[182:185], v202
	ds_read_b128 v[190:193], v202 offset:1024
	ds_read_b128 v[198:201], v202 offset:2048
	ds_read_b128 v[202:205], v202 offset:3072
	v_lshl_add_u64 v[186:187], v[186:187], 0, s[78:79]
	s_mov_b32 m0, s22
	v_lshl_add_u64 v[248:249], v[186:187], 0, v[132:133]
	ds_read_b128 v[206:209], v159 offset:32768
	ds_read_b128 v[210:213], v159 offset:33792
	ds_read_b128 v[214:217], v159 offset:34816
	ds_read_b128 v[218:221], v159 offset:35840
	ds_read_b128 v[222:225], v159 offset:36864
	ds_read_b128 v[226:229], v159 offset:37888
	ds_read_b128 v[230:233], v159 offset:38912
	ds_read_b128 v[234:237], v159 offset:39936
	global_load_lds_dwordx4 v[248:249], off
	v_lshl_add_u64 v[186:187], v[186:187], 0, v[134:135]
	s_mov_b32 m0, s23
	s_nop 0
	global_load_lds_dwordx4 v[186:187], off
	s_waitcnt vmcnt(8)
	s_waitcnt lgkmcnt(0)
	s_barrier
	s_waitcnt lgkmcnt(0)
	v_mfma_f32_16x16x32_bf16 v[124:127], v[164:167], v[206:209], v[124:127]
	v_mfma_f32_16x16x32_bf16 v[116:119], v[174:177], v[206:209], v[116:119]
	v_mfma_f32_16x16x32_bf16 v[108:111], v[164:167], v[214:217], v[108:111]
	v_mfma_f32_16x16x32_bf16 v[100:103], v[174:177], v[214:217], v[100:103]
	v_mfma_f32_16x16x32_bf16 v[92:95], v[164:167], v[222:225], v[92:95]
	v_mfma_f32_16x16x32_bf16 v[84:87], v[174:177], v[222:225], v[84:87]
	v_mfma_f32_16x16x32_bf16 v[76:79], v[164:167], v[230:233], v[76:79]
	v_mfma_f32_16x16x32_bf16 v[68:71], v[174:177], v[230:233], v[68:71]
	v_mfma_f32_16x16x32_bf16 v[124:127], v[170:173], v[210:213], v[124:127]
	v_mfma_f32_16x16x32_bf16 v[116:119], v[178:181], v[210:213], v[116:119]
	v_mfma_f32_16x16x32_bf16 v[108:111], v[170:173], v[218:221], v[108:111]
	v_mfma_f32_16x16x32_bf16 v[100:103], v[178:181], v[218:221], v[100:103]
	v_mfma_f32_16x16x32_bf16 v[92:95], v[170:173], v[226:229], v[92:95]
	v_mfma_f32_16x16x32_bf16 v[84:87], v[178:181], v[226:229], v[84:87]
	v_mfma_f32_16x16x32_bf16 v[76:79], v[170:173], v[234:237], v[76:79]
	v_mfma_f32_16x16x32_bf16 v[68:71], v[178:181], v[234:237], v[68:71]
	v_mfma_f32_16x16x32_bf16 v[120:123], v[182:185], v[206:209], v[120:123]
	v_mfma_f32_16x16x32_bf16 v[112:115], v[198:201], v[206:209], v[112:115]
	v_mfma_f32_16x16x32_bf16 v[104:107], v[182:185], v[214:217], v[104:107]
	v_mfma_f32_16x16x32_bf16 v[96:99], v[198:201], v[214:217], v[96:99]
	v_mfma_f32_16x16x32_bf16 v[88:91], v[182:185], v[222:225], v[88:91]
	v_mfma_f32_16x16x32_bf16 v[80:83], v[198:201], v[222:225], v[80:83]
	v_mfma_f32_16x16x32_bf16 v[72:75], v[182:185], v[230:233], v[72:75]
	v_mfma_f32_16x16x32_bf16 v[64:67], v[198:201], v[230:233], v[64:67]
	v_mfma_f32_16x16x32_bf16 v[120:123], v[190:193], v[210:213], v[120:123]
	v_mfma_f32_16x16x32_bf16 v[112:115], v[202:205], v[210:213], v[112:115]
	v_mfma_f32_16x16x32_bf16 v[104:107], v[190:193], v[218:221], v[104:107]
	v_mfma_f32_16x16x32_bf16 v[96:99], v[202:205], v[218:221], v[96:99]
	v_mfma_f32_16x16x32_bf16 v[88:91], v[190:193], v[226:229], v[88:91]
	v_mfma_f32_16x16x32_bf16 v[80:83], v[202:205], v[226:229], v[80:83]
	v_mfma_f32_16x16x32_bf16 v[72:75], v[190:193], v[234:237], v[72:75]
	v_mfma_f32_16x16x32_bf16 v[64:67], v[202:205], v[234:237], v[64:67]
	s_barrier
	s_add_i32 s13, s13, s19
	v_lshl_add_u64 v[186:187], v[240:241], 0, s[84:85]
	s_mov_b32 m0, s13
	ds_read_b128 v[206:209], v159 offset:49152
	ds_read_b128 v[210:213], v159 offset:50176
	ds_read_b128 v[214:217], v159 offset:51200
	ds_read_b128 v[218:221], v159 offset:52224
	ds_read_b128 v[222:225], v159 offset:53248
	ds_read_b128 v[226:229], v159 offset:54272
	ds_read_b128 v[230:233], v159 offset:55296
	ds_read_b128 v[234:237], v159 offset:56320
	global_load_lds_dwordx4 v[186:187], off
	v_lshl_add_u64 v[186:187], v[242:243], 0, s[84:85]
	s_add_i32 m0, s13, 0x2000
	s_add_i32 s13, s14, s19
	global_load_lds_dwordx4 v[186:187], off
	v_lshl_add_u64 v[186:187], v[238:239], 0, s[86:87]
	v_lshl_add_u64 v[238:239], v[186:187], 0, v[162:163]
	s_mov_b32 m0, s13
	v_lshl_add_u64 v[186:187], v[186:187], 0, v[136:137]
	global_load_lds_dwordx4 v[238:239], off
	s_add_i32 m0, s13, 0x2000
	s_nop 0
	global_load_lds_dwordx4 v[186:187], off
	v_lshl_add_u64 v[186:187], v[244:245], 0, s[84:85]
	s_mov_b32 m0, s24
	s_nop 0
	global_load_lds_dwordx4 v[186:187], off
	v_lshl_add_u64 v[186:187], v[246:247], 0, s[84:85]
	s_mov_b32 m0, s25
	s_nop 0
	global_load_lds_dwordx4 v[186:187], off
	s_waitcnt vmcnt(8)
	s_waitcnt lgkmcnt(0)
	s_barrier
	s_waitcnt lgkmcnt(0)
	v_mfma_f32_16x16x32_bf16 v[60:63], v[164:167], v[206:209], v[60:63]
	v_mfma_f32_16x16x32_bf16 v[52:55], v[174:177], v[206:209], v[52:55]
	v_mfma_f32_16x16x32_bf16 v[44:47], v[164:167], v[214:217], v[44:47]
	v_mfma_f32_16x16x32_bf16 v[36:39], v[174:177], v[214:217], v[36:39]
	v_mfma_f32_16x16x32_bf16 v[28:31], v[164:167], v[222:225], v[28:31]
	v_mfma_f32_16x16x32_bf16 v[20:23], v[174:177], v[222:225], v[20:23]
	v_mfma_f32_16x16x32_bf16 v[12:15], v[164:167], v[230:233], v[12:15]
	v_mfma_f32_16x16x32_bf16 v[4:7], v[174:177], v[230:233], v[4:7]
	v_mfma_f32_16x16x32_bf16 v[60:63], v[170:173], v[210:213], v[60:63]
	v_mfma_f32_16x16x32_bf16 v[52:55], v[178:181], v[210:213], v[52:55]
	v_mfma_f32_16x16x32_bf16 v[44:47], v[170:173], v[218:221], v[44:47]
	v_mfma_f32_16x16x32_bf16 v[36:39], v[178:181], v[218:221], v[36:39]
	v_mfma_f32_16x16x32_bf16 v[28:31], v[170:173], v[226:229], v[28:31]
	v_mfma_f32_16x16x32_bf16 v[20:23], v[178:181], v[226:229], v[20:23]
	v_mfma_f32_16x16x32_bf16 v[12:15], v[170:173], v[234:237], v[12:15]
	v_mfma_f32_16x16x32_bf16 v[4:7], v[178:181], v[234:237], v[4:7]
	v_mfma_f32_16x16x32_bf16 v[56:59], v[182:185], v[206:209], v[56:59]
	v_mfma_f32_16x16x32_bf16 v[48:51], v[198:201], v[206:209], v[48:51]
	v_mfma_f32_16x16x32_bf16 v[40:43], v[182:185], v[214:217], v[40:43]
	v_mfma_f32_16x16x32_bf16 v[32:35], v[198:201], v[214:217], v[32:35]
	v_mfma_f32_16x16x32_bf16 v[24:27], v[182:185], v[222:225], v[24:27]
	v_mfma_f32_16x16x32_bf16 v[16:19], v[198:201], v[222:225], v[16:19]
	v_mfma_f32_16x16x32_bf16 v[8:11], v[182:185], v[230:233], v[8:11]
	v_mfma_f32_16x16x32_bf16 v[0:3], v[198:201], v[230:233], v[0:3]
	v_mfma_f32_16x16x32_bf16 v[56:59], v[190:193], v[210:213], v[56:59]
	v_mfma_f32_16x16x32_bf16 v[48:51], v[202:205], v[210:213], v[48:51]
	v_mfma_f32_16x16x32_bf16 v[40:43], v[190:193], v[218:221], v[40:43]
	v_mfma_f32_16x16x32_bf16 v[32:35], v[202:205], v[218:221], v[32:35]
	v_mfma_f32_16x16x32_bf16 v[24:27], v[190:193], v[226:229], v[24:27]
	v_mfma_f32_16x16x32_bf16 v[16:19], v[202:205], v[226:229], v[16:19]
	v_mfma_f32_16x16x32_bf16 v[8:11], v[190:193], v[234:237], v[8:11]
	v_mfma_f32_16x16x32_bf16 v[0:3], v[202:205], v[234:237], v[0:3]
	s_barrier
	s_add_i32 s11, s11, 2
	v_lshl_add_u64 v[152:153], v[152:153], 0, s[0:1]
	s_cmp_gt_u32 s11, 13
	v_lshl_add_u64 v[154:155], v[154:155], 0, s[0:1]
	s_cbranch_scc0 .LBB0_1778
	s_and_b64 vcc, exec, s[8:9]
	s_cbranch_vccz .LBB0_1781
	s_barrier

.LBB0_1867:
	s_cmp_eq_u32 s2, 40
	s_cselect_b64 vcc, -1, 0
	s_add_i32 s3, s33, 0x100
	v_add_u32_e32 v155, s3, v152
	s_add_i32 s6, s92, 0x100
	ds_read_b128 v[156:159], v155
	ds_read_b128 v[164:167], v155 offset:1024
	ds_read_b128 v[170:173], v155 offset:2048
	ds_read_b128 v[174:177], v155 offset:3072
	v_add_u32_e32 v155, s6, v152
	ds_read_b128 v[178:181], v155
	ds_read_b128 v[182:185], v155 offset:1024
	ds_read_b128 v[190:193], v155 offset:2048
	ds_read_b128 v[198:201], v155 offset:3072
	v_lshl_add_u64 v[148:149], v[146:147], 0, s[0:1]
	v_cndmask_b32_e32 v187, v149, v141, vcc
	v_cndmask_b32_e32 v186, v148, v140, vcc
	v_cndmask_b32_e32 v235, v145, v143, vcc
	v_cndmask_b32_e32 v234, v144, v142, vcc
	v_lshl_add_u64 v[236:237], v[146:147], 0, v[138:139]
	s_add_i32 m0, s18, 0xc000
	ds_read_b128 v[202:205], v154
	ds_read_b128 v[206:209], v154 offset:1024
	ds_read_b128 v[210:213], v154 offset:2048
	ds_read_b128 v[214:217], v154 offset:3072
	ds_read_b128 v[218:221], v154 offset:4096
	ds_read_b128 v[222:225], v154 offset:5120
	ds_read_b128 v[226:229], v154 offset:6144
	ds_read_b128 v[230:233], v154 offset:7168
	global_load_lds_dwordx4 v[236:237], off
	v_lshl_add_u64 v[146:147], v[146:147], 0, v[136:137]
	s_add_i32 m0, s18, 0xe000
	s_nop 0
	global_load_lds_dwordx4 v[146:147], off
	s_waitcnt vmcnt(8)
	s_waitcnt lgkmcnt(0)
	s_barrier
	s_waitcnt lgkmcnt(0)
	v_mfma_f32_16x16x32_bf16 v[124:127], v[156:159], v[202:205], v[124:127]
	v_mfma_f32_16x16x32_bf16 v[120:123], v[170:173], v[202:205], v[120:123]
	v_mfma_f32_16x16x32_bf16 v[108:111], v[156:159], v[210:213], v[108:111]
	v_mfma_f32_16x16x32_bf16 v[104:107], v[170:173], v[210:213], v[104:107]
	v_mfma_f32_16x16x32_bf16 v[92:95], v[156:159], v[218:221], v[92:95]
	v_mfma_f32_16x16x32_bf16 v[88:91], v[170:173], v[218:221], v[88:91]
	v_mfma_f32_16x16x32_bf16 v[76:79], v[156:159], v[226:229], v[76:79]
	v_mfma_f32_16x16x32_bf16 v[72:75], v[170:173], v[226:229], v[72:75]
	v_mfma_f32_16x16x32_bf16 v[124:127], v[164:167], v[206:209], v[124:127]
	v_mfma_f32_16x16x32_bf16 v[120:123], v[174:177], v[206:209], v[120:123]
	v_mfma_f32_16x16x32_bf16 v[108:111], v[164:167], v[214:217], v[108:111]
	v_mfma_f32_16x16x32_bf16 v[104:107], v[174:177], v[214:217], v[104:107]
	v_mfma_f32_16x16x32_bf16 v[92:95], v[164:167], v[222:225], v[92:95]
	v_mfma_f32_16x16x32_bf16 v[88:91], v[174:177], v[222:225], v[88:91]
	v_mfma_f32_16x16x32_bf16 v[76:79], v[164:167], v[230:233], v[76:79]
	v_mfma_f32_16x16x32_bf16 v[72:75], v[174:177], v[230:233], v[72:75]
	v_mfma_f32_16x16x32_bf16 v[116:119], v[178:181], v[202:205], v[116:119]
	v_mfma_f32_16x16x32_bf16 v[112:115], v[190:193], v[202:205], v[112:115]
	v_mfma_f32_16x16x32_bf16 v[100:103], v[178:181], v[210:213], v[100:103]
	v_mfma_f32_16x16x32_bf16 v[96:99], v[190:193], v[210:213], v[96:99]
	v_mfma_f32_16x16x32_bf16 v[84:87], v[178:181], v[218:221], v[84:87]
	v_mfma_f32_16x16x32_bf16 v[80:83], v[190:193], v[218:221], v[80:83]
	v_mfma_f32_16x16x32_bf16 v[68:71], v[178:181], v[226:229], v[68:71]
	v_mfma_f32_16x16x32_bf16 v[64:67], v[190:193], v[226:229], v[64:67]
	v_mfma_f32_16x16x32_bf16 v[116:119], v[182:185], v[206:209], v[116:119]
	v_mfma_f32_16x16x32_bf16 v[112:115], v[198:201], v[206:209], v[112:115]
	v_mfma_f32_16x16x32_bf16 v[100:103], v[182:185], v[214:217], v[100:103]
	v_mfma_f32_16x16x32_bf16 v[96:99], v[198:201], v[214:217], v[96:99]
	v_mfma_f32_16x16x32_bf16 v[84:87], v[182:185], v[222:225], v[84:87]
	v_mfma_f32_16x16x32_bf16 v[80:83], v[198:201], v[222:225], v[80:83]
	v_mfma_f32_16x16x32_bf16 v[68:71], v[182:185], v[230:233], v[68:71]
	v_mfma_f32_16x16x32_bf16 v[64:67], v[198:201], v[230:233], v[64:67]
	s_barrier
	s_add_i32 s3, s3, s17
	v_lshl_add_u64 v[146:147], v[234:235], 0, v[162:163]
	s_mov_b32 m0, s3
	ds_read_b128 v[202:205], v154 offset:16384
	ds_read_b128 v[206:209], v154 offset:17408
	ds_read_b128 v[210:213], v154 offset:18432
	ds_read_b128 v[214:217], v154 offset:19456
	ds_read_b128 v[218:221], v154 offset:20480
	ds_read_b128 v[222:225], v154 offset:21504
	ds_read_b128 v[226:229], v154 offset:22528
	ds_read_b128 v[230:233], v154 offset:23552
	global_load_lds_dwordx4 v[146:147], off
	v_lshl_add_u64 v[236:237], v[234:235], 0, v[134:135]
	s_add_i32 m0, s3, 0x2000
	v_lshl_add_u64 v[238:239], v[234:235], 0, s[44:45]
	s_add_i32 s3, s6, s17
	global_load_lds_dwordx4 v[236:237], off
	v_lshl_add_u64 v[240:241], v[238:239], 0, v[162:163]
	s_mov_b32 m0, s3
	v_lshl_add_u64 v[238:239], v[238:239], 0, v[134:135]
	global_load_lds_dwordx4 v[240:241], off
	s_add_i32 m0, s3, 0x2000
	v_lshl_add_u64 v[240:241], v[186:187], 0, v[134:135]
	global_load_lds_dwordx4 v[238:239], off
	v_lshl_add_u64 v[238:239], v[186:187], 0, v[162:163]
	s_mov_b32 m0, s18
	s_nop 0
	global_load_lds_dwordx4 v[238:239], off
	s_mov_b32 m0, s19
	s_nop 0
	global_load_lds_dwordx4 v[240:241], off
	s_waitcnt vmcnt(8)
	s_waitcnt lgkmcnt(0)
	s_barrier
	s_waitcnt lgkmcnt(0)
	v_mfma_f32_16x16x32_bf16 v[60:63], v[156:159], v[202:205], v[60:63]
	v_mfma_f32_16x16x32_bf16 v[56:59], v[170:173], v[202:205], v[56:59]
	v_mfma_f32_16x16x32_bf16 v[44:47], v[156:159], v[210:213], v[44:47]
	v_mfma_f32_16x16x32_bf16 v[40:43], v[170:173], v[210:213], v[40:43]
	v_mfma_f32_16x16x32_bf16 v[28:31], v[156:159], v[218:221], v[28:31]
	v_mfma_f32_16x16x32_bf16 v[24:27], v[170:173], v[218:221], v[24:27]
	v_mfma_f32_16x16x32_bf16 v[12:15], v[156:159], v[226:229], v[12:15]
	v_mfma_f32_16x16x32_bf16 v[8:11], v[170:173], v[226:229], v[8:11]
	v_mfma_f32_16x16x32_bf16 v[60:63], v[164:167], v[206:209], v[60:63]
	v_mfma_f32_16x16x32_bf16 v[56:59], v[174:177], v[206:209], v[56:59]
	v_mfma_f32_16x16x32_bf16 v[44:47], v[164:167], v[214:217], v[44:47]
	v_mfma_f32_16x16x32_bf16 v[40:43], v[174:177], v[214:217], v[40:43]
	v_mfma_f32_16x16x32_bf16 v[28:31], v[164:167], v[222:225], v[28:31]
	v_mfma_f32_16x16x32_bf16 v[24:27], v[174:177], v[222:225], v[24:27]
	v_mfma_f32_16x16x32_bf16 v[12:15], v[164:167], v[230:233], v[12:15]
	v_mfma_f32_16x16x32_bf16 v[8:11], v[174:177], v[230:233], v[8:11]
	v_mfma_f32_16x16x32_bf16 v[52:55], v[178:181], v[202:205], v[52:55]
	v_mfma_f32_16x16x32_bf16 v[48:51], v[190:193], v[202:205], v[48:51]
	v_mfma_f32_16x16x32_bf16 v[36:39], v[178:181], v[210:213], v[36:39]
	v_mfma_f32_16x16x32_bf16 v[32:35], v[190:193], v[210:213], v[32:35]
	v_mfma_f32_16x16x32_bf16 v[20:23], v[178:181], v[218:221], v[20:23]
	v_mfma_f32_16x16x32_bf16 v[16:19], v[190:193], v[218:221], v[16:19]
	v_mfma_f32_16x16x32_bf16 v[4:7], v[178:181], v[226:229], v[4:7]
	v_mfma_f32_16x16x32_bf16 v[0:3], v[190:193], v[226:229], v[0:3]
	v_mfma_f32_16x16x32_bf16 v[52:55], v[182:185], v[206:209], v[52:55]
	v_mfma_f32_16x16x32_bf16 v[48:51], v[198:201], v[206:209], v[48:51]
	v_mfma_f32_16x16x32_bf16 v[36:39], v[182:185], v[214:217], v[36:39]
	v_mfma_f32_16x16x32_bf16 v[32:35], v[198:201], v[214:217], v[32:35]
	v_mfma_f32_16x16x32_bf16 v[20:23], v[182:185], v[222:225], v[20:23]
	v_mfma_f32_16x16x32_bf16 v[16:19], v[198:201], v[222:225], v[16:19]
	v_mfma_f32_16x16x32_bf16 v[4:7], v[182:185], v[230:233], v[4:7]
	v_mfma_f32_16x16x32_bf16 v[0:3], v[198:201], v[230:233], v[0:3]
	s_barrier
	s_add_i32 s3, s93, 0x100
	v_add_u32_e32 v155, s3, v152
	s_add_i32 s6, s82, 0x100
	ds_read_b128 v[156:159], v155
	ds_read_b128 v[164:167], v155 offset:1024
	ds_read_b128 v[170:173], v155 offset:2048
	ds_read_b128 v[174:177], v155 offset:3072
	v_add_u32_e32 v155, s6, v152
	ds_read_b128 v[178:181], v155
	ds_read_b128 v[182:185], v155 offset:1024
	ds_read_b128 v[190:193], v155 offset:2048
	ds_read_b128 v[198:201], v155 offset:3072
	v_lshl_add_u64 v[186:187], v[186:187], 0, s[44:45]
	s_mov_b32 m0, s20
	v_lshl_add_u64 v[242:243], v[186:187], 0, v[162:163]
	ds_read_b128 v[202:205], v154 offset:32768
	ds_read_b128 v[206:209], v154 offset:33792
	ds_read_b128 v[210:213], v154 offset:34816
	ds_read_b128 v[214:217], v154 offset:35840
	ds_read_b128 v[218:221], v154 offset:36864
	ds_read_b128 v[222:225], v154 offset:37888
	ds_read_b128 v[226:229], v154 offset:38912
	ds_read_b128 v[230:233], v154 offset:39936
	global_load_lds_dwordx4 v[242:243], off
	v_lshl_add_u64 v[186:187], v[186:187], 0, v[134:135]
	s_mov_b32 m0, s21
	s_nop 0
	global_load_lds_dwordx4 v[186:187], off
	s_waitcnt vmcnt(8)
	s_waitcnt lgkmcnt(0)
	s_barrier
	s_waitcnt lgkmcnt(0)
	v_mfma_f32_16x16x32_bf16 v[124:127], v[156:159], v[202:205], v[124:127]
	v_mfma_f32_16x16x32_bf16 v[120:123], v[170:173], v[202:205], v[120:123]
	v_mfma_f32_16x16x32_bf16 v[108:111], v[156:159], v[210:213], v[108:111]
	v_mfma_f32_16x16x32_bf16 v[104:107], v[170:173], v[210:213], v[104:107]
	v_mfma_f32_16x16x32_bf16 v[92:95], v[156:159], v[218:221], v[92:95]
	v_mfma_f32_16x16x32_bf16 v[88:91], v[170:173], v[218:221], v[88:91]
	v_mfma_f32_16x16x32_bf16 v[76:79], v[156:159], v[226:229], v[76:79]
	v_mfma_f32_16x16x32_bf16 v[72:75], v[170:173], v[226:229], v[72:75]
	v_mfma_f32_16x16x32_bf16 v[124:127], v[164:167], v[206:209], v[124:127]
	v_mfma_f32_16x16x32_bf16 v[120:123], v[174:177], v[206:209], v[120:123]
	v_mfma_f32_16x16x32_bf16 v[108:111], v[164:167], v[214:217], v[108:111]
	v_mfma_f32_16x16x32_bf16 v[104:107], v[174:177], v[214:217], v[104:107]
	v_mfma_f32_16x16x32_bf16 v[92:95], v[164:167], v[222:225], v[92:95]
	v_mfma_f32_16x16x32_bf16 v[88:91], v[174:177], v[222:225], v[88:91]
	v_mfma_f32_16x16x32_bf16 v[76:79], v[164:167], v[230:233], v[76:79]
	v_mfma_f32_16x16x32_bf16 v[72:75], v[174:177], v[230:233], v[72:75]
	v_mfma_f32_16x16x32_bf16 v[116:119], v[178:181], v[202:205], v[116:119]
	v_mfma_f32_16x16x32_bf16 v[112:115], v[190:193], v[202:205], v[112:115]
	v_mfma_f32_16x16x32_bf16 v[100:103], v[178:181], v[210:213], v[100:103]
	v_mfma_f32_16x16x32_bf16 v[96:99], v[190:193], v[210:213], v[96:99]
	v_mfma_f32_16x16x32_bf16 v[84:87], v[178:181], v[218:221], v[84:87]
	v_mfma_f32_16x16x32_bf16 v[80:83], v[190:193], v[218:221], v[80:83]
	v_mfma_f32_16x16x32_bf16 v[68:71], v[178:181], v[226:229], v[68:71]
	v_mfma_f32_16x16x32_bf16 v[64:67], v[190:193], v[226:229], v[64:67]
	v_mfma_f32_16x16x32_bf16 v[116:119], v[182:185], v[206:209], v[116:119]
	v_mfma_f32_16x16x32_bf16 v[112:115], v[198:201], v[206:209], v[112:115]
	v_mfma_f32_16x16x32_bf16 v[100:103], v[182:185], v[214:217], v[100:103]
	v_mfma_f32_16x16x32_bf16 v[96:99], v[198:201], v[214:217], v[96:99]
	v_mfma_f32_16x16x32_bf16 v[84:87], v[182:185], v[222:225], v[84:87]
	v_mfma_f32_16x16x32_bf16 v[80:83], v[198:201], v[222:225], v[80:83]
	v_mfma_f32_16x16x32_bf16 v[68:71], v[182:185], v[230:233], v[68:71]
	v_mfma_f32_16x16x32_bf16 v[64:67], v[198:201], v[230:233], v[64:67]
	s_barrier
	s_add_i32 s3, s3, s17
	v_lshl_add_u64 v[146:147], v[146:147], 0, s[84:85]
	s_mov_b32 m0, s3
	ds_read_b128 v[202:205], v154 offset:49152
	ds_read_b128 v[206:209], v154 offset:50176
	ds_read_b128 v[210:213], v154 offset:51200
	ds_read_b128 v[214:217], v154 offset:52224
	ds_read_b128 v[218:221], v154 offset:53248
	ds_read_b128 v[222:225], v154 offset:54272
	ds_read_b128 v[226:229], v154 offset:55296
	ds_read_b128 v[230:233], v154 offset:56320
	global_load_lds_dwordx4 v[146:147], off
	v_lshl_add_u64 v[146:147], v[236:237], 0, s[84:85]
	s_add_i32 m0, s3, 0x2000
	s_add_i32 s3, s6, s17
	global_load_lds_dwordx4 v[146:147], off
	v_lshl_add_u64 v[146:147], v[234:235], 0, s[30:31]
	v_lshl_add_u64 v[186:187], v[146:147], 0, v[162:163]
	s_mov_b32 m0, s3
	v_lshl_add_u64 v[146:147], v[146:147], 0, v[134:135]
	global_load_lds_dwordx4 v[186:187], off
	s_add_i32 m0, s3, 0x2000
	s_nop 0
	global_load_lds_dwordx4 v[146:147], off
	v_lshl_add_u64 v[146:147], v[238:239], 0, s[84:85]
	s_mov_b32 m0, s22
	s_nop 0
	global_load_lds_dwordx4 v[146:147], off
	v_lshl_add_u64 v[146:147], v[240:241], 0, s[84:85]
	s_mov_b32 m0, s23
	s_nop 0
	global_load_lds_dwordx4 v[146:147], off
	s_waitcnt vmcnt(8)
	s_waitcnt lgkmcnt(0)
	s_barrier
	s_waitcnt lgkmcnt(0)
	v_mfma_f32_16x16x32_bf16 v[60:63], v[156:159], v[202:205], v[60:63]
	v_mfma_f32_16x16x32_bf16 v[56:59], v[170:173], v[202:205], v[56:59]
	v_mfma_f32_16x16x32_bf16 v[44:47], v[156:159], v[210:213], v[44:47]
	v_mfma_f32_16x16x32_bf16 v[40:43], v[170:173], v[210:213], v[40:43]
	v_mfma_f32_16x16x32_bf16 v[28:31], v[156:159], v[218:221], v[28:31]
	v_mfma_f32_16x16x32_bf16 v[24:27], v[170:173], v[218:221], v[24:27]
	v_mfma_f32_16x16x32_bf16 v[12:15], v[156:159], v[226:229], v[12:15]
	v_mfma_f32_16x16x32_bf16 v[8:11], v[170:173], v[226:229], v[8:11]
	v_mfma_f32_16x16x32_bf16 v[60:63], v[164:167], v[206:209], v[60:63]
	v_mfma_f32_16x16x32_bf16 v[56:59], v[174:177], v[206:209], v[56:59]
	v_mfma_f32_16x16x32_bf16 v[44:47], v[164:167], v[214:217], v[44:47]
	v_mfma_f32_16x16x32_bf16 v[40:43], v[174:177], v[214:217], v[40:43]
	v_mfma_f32_16x16x32_bf16 v[28:31], v[164:167], v[222:225], v[28:31]
	v_mfma_f32_16x16x32_bf16 v[24:27], v[174:177], v[222:225], v[24:27]
	v_mfma_f32_16x16x32_bf16 v[12:15], v[164:167], v[230:233], v[12:15]
	v_mfma_f32_16x16x32_bf16 v[8:11], v[174:177], v[230:233], v[8:11]
	v_mfma_f32_16x16x32_bf16 v[52:55], v[178:181], v[202:205], v[52:55]
	v_mfma_f32_16x16x32_bf16 v[48:51], v[190:193], v[202:205], v[48:51]
	v_mfma_f32_16x16x32_bf16 v[36:39], v[178:181], v[210:213], v[36:39]
	v_mfma_f32_16x16x32_bf16 v[32:35], v[190:193], v[210:213], v[32:35]
	v_mfma_f32_16x16x32_bf16 v[20:23], v[178:181], v[218:221], v[20:23]
	v_mfma_f32_16x16x32_bf16 v[16:19], v[190:193], v[218:221], v[16:19]
	v_mfma_f32_16x16x32_bf16 v[4:7], v[178:181], v[226:229], v[4:7]
	v_mfma_f32_16x16x32_bf16 v[0:3], v[190:193], v[226:229], v[0:3]
	v_mfma_f32_16x16x32_bf16 v[52:55], v[182:185], v[206:209], v[52:55]
	v_mfma_f32_16x16x32_bf16 v[48:51], v[198:201], v[206:209], v[48:51]
	v_mfma_f32_16x16x32_bf16 v[36:39], v[182:185], v[214:217], v[36:39]
	v_mfma_f32_16x16x32_bf16 v[32:35], v[198:201], v[214:217], v[32:35]
	v_mfma_f32_16x16x32_bf16 v[20:23], v[182:185], v[222:225], v[20:23]
	v_mfma_f32_16x16x32_bf16 v[16:19], v[198:201], v[222:225], v[16:19]
	v_mfma_f32_16x16x32_bf16 v[4:7], v[182:185], v[230:233], v[4:7]
	v_mfma_f32_16x16x32_bf16 v[0:3], v[198:201], v[230:233], v[0:3]
	s_barrier
	s_add_i32 s2, s2, 2
	v_lshl_add_u64 v[144:145], v[144:145], 0, s[0:1]
	s_cmp_gt_u32 s2, 41
	v_mov_b64_e32 v[146:147], v[148:149]
	s_cbranch_scc0 .LBB0_1867
	s_and_b64 vcc, exec, s[10:11]
	s_cbranch_vccz .LBB0_1870
	s_barrier

.LBB0_1882:
	v_bfe_u32 v35, v4, 4, 2
	v_and_b32_e32 v5, 15, v4
	v_lshlrev_b32_e32 v6, 4, v35
	v_lshlrev_b32_e32 v4, 2, v4
	v_lshl_or_b32 v34, s8, 6, v5
	v_lshl_or_b32 v5, v5, 6, v6
	s_lshl_b32 s5, s8, 13
	v_and_b32_e32 v4, 32, v4
	v_bitop3_b32 v36, v5, s5, v4 bitop3:0xde
	s_lshl_b32 s5, s9, 5
	s_and_b32 s5, s5, 0x60
	s_lshl_b32 s8, s5, 7
	s_add_i32 s18, s93, 0x100
	v_bitop3_b32 v37, v5, s8, v4 bitop3:0xde
	s_add_i32 s8, s18, s17
	v_lshl_add_u64 v[6:7], v[12:13], 0, s[84:85]
	s_mov_b32 m0, s8
	s_add_i32 s11, s8, 0x2000
	s_waitcnt vmcnt(2)
	s_barrier
	global_load_lds_dwordx4 v[6:7], off
	v_lshl_add_u64 v[8:9], v[18:19], 0, s[84:85]
	s_mov_b32 m0, s11
	s_add_i32 s9, s10, 0x8000
	global_load_lds_dwordx4 v[8:9], off
	v_lshl_add_u64 v[4:5], v[26:27], 0, s[84:85]
	s_mov_b32 m0, s9
	s_add_i32 s13, s10, 0xa000
	s_add_i32 s19, s82, 0x100
	global_load_lds_dwordx4 v[4:5], off
	v_lshl_add_u64 v[10:11], v[28:29], 0, s[84:85]
	s_mov_b32 m0, s13
	v_lshl_add_u64 v[16:17], v[32:33], 0, s[26:27]
	s_add_i32 s14, s19, s17
	global_load_lds_dwordx4 v[10:11], off
	v_lshl_add_u64 v[14:15], v[16:17], 0, v[162:163]
	s_mov_b32 m0, s14
	s_add_i32 s15, s14, 0x2000
	global_load_lds_dwordx4 v[14:15], off
	v_lshl_add_u64 v[16:17], v[16:17], 0, v[24:25]
	s_mov_b32 m0, s15
	s_add_i32 s20, s33, 0x100
	global_load_lds_dwordx4 v[16:17], off
	v_add_u32_e32 v186, s20, v37
	s_add_i32 s21, s92, 0x100
	s_waitcnt vmcnt(6)
	s_barrier
	v_add_u32_e32 v187, s21, v37
	ds_read_b128 v[38:41], v186
	ds_read_b128 v[42:45], v186 offset:1024
	ds_read_b128 v[46:49], v186 offset:2048
	ds_read_b128 v[50:53], v186 offset:3072
	ds_read_b128 v[54:57], v187
	ds_read_b128 v[58:61], v187 offset:1024
	ds_read_b128 v[62:65], v187 offset:2048
	ds_read_b128 v[66:69], v187 offset:3072
	v_add_u32_e32 v36, 0x100, v36
	v_add_u32_e32 v250, s18, v37
	v_add_u32_e32 v37, s19, v37
	v_lshlrev_b32_e32 v35, 2, v35
	v_lshl_add_u64 v[102:103], v[30:31], 0, s[26:27]
	s_add_i32 s22, s10, 0xc000
	v_lshl_add_u64 v[104:105], v[102:103], 0, v[162:163]
	s_mov_b32 m0, s22
	s_add_i32 s18, s10, 0xe000
	ds_read_b128 v[70:73], v36
	ds_read_b128 v[74:77], v36 offset:1024
	ds_read_b128 v[78:81], v36 offset:2048
	ds_read_b128 v[82:85], v36 offset:3072
	ds_read_b128 v[86:89], v36 offset:4096
	ds_read_b128 v[90:93], v36 offset:5120
	ds_read_b128 v[94:97], v36 offset:6144
	ds_read_b128 v[98:101], v36 offset:7168
	global_load_lds_dwordx4 v[104:105], off
	v_lshl_add_u64 v[102:103], v[102:103], 0, v[24:25]
	s_mov_b32 m0, s18
	s_nop 0
	global_load_lds_dwordx4 v[102:103], off
	s_waitcnt vmcnt(8)
	s_waitcnt lgkmcnt(0)
	s_barrier
	s_waitcnt lgkmcnt(0)
	v_mfma_f32_16x16x32_bf16 v[102:105], v[38:41], v[70:73], 0
	v_mfma_f32_16x16x32_bf16 v[106:109], v[46:49], v[70:73], 0
	v_mfma_f32_16x16x32_bf16 v[110:113], v[38:41], v[78:81], 0
	v_mfma_f32_16x16x32_bf16 v[114:117], v[46:49], v[78:81], 0
	v_mfma_f32_16x16x32_bf16 v[118:121], v[38:41], v[86:89], 0
	v_mfma_f32_16x16x32_bf16 v[122:125], v[46:49], v[86:89], 0
	v_mfma_f32_16x16x32_bf16 v[130:133], v[38:41], v[94:97], 0
	v_mfma_f32_16x16x32_bf16 v[134:137], v[46:49], v[94:97], 0
	v_mfma_f32_16x16x32_bf16 v[102:105], v[42:45], v[74:77], v[102:105]
	v_mfma_f32_16x16x32_bf16 v[106:109], v[50:53], v[74:77], v[106:109]
	v_mfma_f32_16x16x32_bf16 v[110:113], v[42:45], v[82:85], v[110:113]
	v_mfma_f32_16x16x32_bf16 v[114:117], v[50:53], v[82:85], v[114:117]
	v_mfma_f32_16x16x32_bf16 v[118:121], v[42:45], v[90:93], v[118:121]
	v_mfma_f32_16x16x32_bf16 v[122:125], v[50:53], v[90:93], v[122:125]
	v_mfma_f32_16x16x32_bf16 v[130:133], v[42:45], v[98:101], v[130:133]
	v_mfma_f32_16x16x32_bf16 v[134:137], v[50:53], v[98:101], v[134:137]
	v_mfma_f32_16x16x32_bf16 v[138:141], v[54:57], v[70:73], 0
	v_mfma_f32_16x16x32_bf16 v[70:73], v[62:65], v[70:73], 0
	v_mfma_f32_16x16x32_bf16 v[138:141], v[58:61], v[74:77], v[138:141]
	v_mfma_f32_16x16x32_bf16 v[70:73], v[66:69], v[74:77], v[70:73]
	v_mfma_f32_16x16x32_bf16 v[74:77], v[54:57], v[78:81], 0
	v_mfma_f32_16x16x32_bf16 v[78:81], v[62:65], v[78:81], 0
	v_mfma_f32_16x16x32_bf16 v[74:77], v[58:61], v[82:85], v[74:77]
	v_mfma_f32_16x16x32_bf16 v[78:81], v[66:69], v[82:85], v[78:81]
	v_mfma_f32_16x16x32_bf16 v[82:85], v[54:57], v[86:89], 0
	v_mfma_f32_16x16x32_bf16 v[86:89], v[62:65], v[86:89], 0
	v_mfma_f32_16x16x32_bf16 v[82:85], v[58:61], v[90:93], v[82:85]
	v_mfma_f32_16x16x32_bf16 v[86:89], v[66:69], v[90:93], v[86:89]
	v_mfma_f32_16x16x32_bf16 v[90:93], v[54:57], v[94:97], 0
	v_mfma_f32_16x16x32_bf16 v[94:97], v[62:65], v[94:97], 0
	v_mfma_f32_16x16x32_bf16 v[90:93], v[58:61], v[98:101], v[90:93]
	v_mfma_f32_16x16x32_bf16 v[94:97], v[66:69], v[98:101], v[94:97]
	s_barrier
	s_add_i32 s19, s20, s17
	v_lshl_add_u64 v[126:127], v[12:13], 0, s[0:1]
	s_mov_b32 m0, s19
	s_add_i32 s20, s19, 0x2000
	ds_read_b128 v[98:101], v36 offset:16384
	ds_read_b128 v[142:145], v36 offset:17408
	ds_read_b128 v[146:149], v36 offset:18432
	ds_read_b128 v[150:153], v36 offset:19456
	ds_read_b128 v[154:157], v36 offset:20480
	ds_read_b128 v[164:167], v36 offset:21504
	ds_read_b128 v[170:173], v36 offset:22528
	ds_read_b128 v[174:177], v36 offset:23552
	global_load_lds_dwordx4 v[126:127], off
	v_lshl_add_u64 v[126:127], v[18:19], 0, s[0:1]
	s_mov_b32 m0, s20
	s_mov_b64 s[26:27], 0xb0100
	global_load_lds_dwordx4 v[126:127], off
	v_lshl_add_u64 v[126:127], v[32:33], 0, s[26:27]
	s_add_i32 s17, s21, s17
	v_lshl_add_u64 v[158:159], v[126:127], 0, v[162:163]
	s_mov_b32 m0, s17
	s_add_i32 s21, s17, 0x2000
	global_load_lds_dwordx4 v[158:159], off
	v_lshl_add_u64 v[126:127], v[126:127], 0, v[24:25]
	s_mov_b32 m0, s21
	s_nop 0
	global_load_lds_dwordx4 v[126:127], off
	v_lshl_add_u64 v[126:127], v[26:27], 0, s[0:1]
	s_mov_b32 m0, s10
	s_nop 0
	global_load_lds_dwordx4 v[126:127], off
	v_lshl_add_u64 v[126:127], v[28:29], 0, s[0:1]
	s_mov_b32 m0, s16
	s_nop 0
	global_load_lds_dwordx4 v[126:127], off
	s_waitcnt vmcnt(8)
	s_waitcnt lgkmcnt(0)
	s_barrier
	s_waitcnt lgkmcnt(0)
	v_mfma_f32_16x16x32_bf16 v[178:181], v[38:41], v[98:101], 0
	v_mfma_f32_16x16x32_bf16 v[190:193], v[38:41], v[146:149], 0
	v_mfma_f32_16x16x32_bf16 v[202:205], v[38:41], v[154:157], 0
	v_mfma_f32_16x16x32_bf16 v[38:41], v[38:41], v[170:173], 0
	v_mfma_f32_16x16x32_bf16 v[178:181], v[42:45], v[142:145], v[178:181]
	v_mfma_f32_16x16x32_bf16 v[182:185], v[46:49], v[98:101], 0
	v_mfma_f32_16x16x32_bf16 v[190:193], v[42:45], v[150:153], v[190:193]
	v_mfma_f32_16x16x32_bf16 v[198:201], v[46:49], v[146:149], 0
	v_mfma_f32_16x16x32_bf16 v[202:205], v[42:45], v[164:167], v[202:205]
	v_mfma_f32_16x16x32_bf16 v[206:209], v[46:49], v[154:157], 0
	v_mfma_f32_16x16x32_bf16 v[38:41], v[42:45], v[174:177], v[38:41]
	v_mfma_f32_16x16x32_bf16 v[42:45], v[46:49], v[170:173], 0
	v_mfma_f32_16x16x32_bf16 v[182:185], v[50:53], v[142:145], v[182:185]
	v_mfma_f32_16x16x32_bf16 v[198:201], v[50:53], v[150:153], v[198:201]
	v_mfma_f32_16x16x32_bf16 v[206:209], v[50:53], v[164:167], v[206:209]
	v_mfma_f32_16x16x32_bf16 v[42:45], v[50:53], v[174:177], v[42:45]
	v_mfma_f32_16x16x32_bf16 v[46:49], v[54:57], v[98:101], 0
	v_mfma_f32_16x16x32_bf16 v[50:53], v[62:65], v[98:101], 0
	v_mfma_f32_16x16x32_bf16 v[46:49], v[58:61], v[142:145], v[46:49]
	v_mfma_f32_16x16x32_bf16 v[50:53], v[66:69], v[142:145], v[50:53]
	v_mfma_f32_16x16x32_bf16 v[98:101], v[54:57], v[146:149], 0
	v_mfma_f32_16x16x32_bf16 v[142:145], v[62:65], v[146:149], 0
	v_mfma_f32_16x16x32_bf16 v[146:149], v[54:57], v[154:157], 0
	v_mfma_f32_16x16x32_bf16 v[54:57], v[54:57], v[170:173], 0
	v_mfma_f32_16x16x32_bf16 v[98:101], v[58:61], v[150:153], v[98:101]
	v_mfma_f32_16x16x32_bf16 v[142:145], v[66:69], v[150:153], v[142:145]
	v_mfma_f32_16x16x32_bf16 v[146:149], v[58:61], v[164:167], v[146:149]
	v_mfma_f32_16x16x32_bf16 v[150:153], v[62:65], v[154:157], 0
	v_mfma_f32_16x16x32_bf16 v[54:57], v[58:61], v[174:177], v[54:57]
	v_mfma_f32_16x16x32_bf16 v[58:61], v[62:65], v[170:173], 0
	v_mfma_f32_16x16x32_bf16 v[150:153], v[66:69], v[164:167], v[150:153]
	v_mfma_f32_16x16x32_bf16 v[58:61], v[66:69], v[174:177], v[58:61]
	s_barrier
	ds_read_b128 v[62:65], v250
	ds_read_b128 v[66:69], v250 offset:1024
	ds_read_b128 v[154:157], v250 offset:2048
	ds_read_b128 v[164:167], v250 offset:3072
	ds_read_b128 v[170:173], v37
	ds_read_b128 v[174:177], v37 offset:1024
	ds_read_b128 v[210:213], v37 offset:2048
	ds_read_b128 v[214:217], v37 offset:3072
	v_lshl_add_u64 v[126:127], v[30:31], 0, s[26:27]
	s_mov_b32 m0, s6
	v_lshl_add_u64 v[158:159], v[126:127], 0, v[162:163]
	ds_read_b128 v[218:221], v36 offset:32768
	ds_read_b128 v[222:225], v36 offset:33792
	ds_read_b128 v[226:229], v36 offset:34816
	ds_read_b128 v[230:233], v36 offset:35840
	ds_read_b128 v[234:237], v36 offset:36864
	ds_read_b128 v[238:241], v36 offset:37888
	ds_read_b128 v[242:245], v36 offset:38912
	ds_read_b128 v[246:249], v36 offset:39936
	global_load_lds_dwordx4 v[158:159], off
	v_lshl_add_u64 v[126:127], v[126:127], 0, v[24:25]
	s_mov_b32 m0, s7
	s_nop 0
	global_load_lds_dwordx4 v[126:127], off
	s_waitcnt vmcnt(8)
	s_waitcnt lgkmcnt(0)
	s_barrier
	s_waitcnt lgkmcnt(0)
	v_mfma_f32_16x16x32_bf16 v[102:105], v[62:65], v[218:221], v[102:105]
	v_mfma_f32_16x16x32_bf16 v[106:109], v[154:157], v[218:221], v[106:109]
	v_mfma_f32_16x16x32_bf16 v[110:113], v[62:65], v[226:229], v[110:113]
	v_mfma_f32_16x16x32_bf16 v[114:117], v[154:157], v[226:229], v[114:117]
	v_mfma_f32_16x16x32_bf16 v[118:121], v[62:65], v[234:237], v[118:121]
	v_mfma_f32_16x16x32_bf16 v[122:125], v[154:157], v[234:237], v[122:125]
	v_mfma_f32_16x16x32_bf16 v[130:133], v[62:65], v[242:245], v[130:133]
	v_mfma_f32_16x16x32_bf16 v[134:137], v[154:157], v[242:245], v[134:137]
	v_mfma_f32_16x16x32_bf16 v[102:105], v[66:69], v[222:225], v[102:105]
	v_mfma_f32_16x16x32_bf16 v[106:109], v[164:167], v[222:225], v[106:109]
	v_mfma_f32_16x16x32_bf16 v[110:113], v[66:69], v[230:233], v[110:113]
	v_mfma_f32_16x16x32_bf16 v[114:117], v[164:167], v[230:233], v[114:117]
	v_mfma_f32_16x16x32_bf16 v[118:121], v[66:69], v[238:241], v[118:121]
	v_mfma_f32_16x16x32_bf16 v[122:125], v[164:167], v[238:241], v[122:125]
	v_mfma_f32_16x16x32_bf16 v[130:133], v[66:69], v[246:249], v[130:133]
	v_mfma_f32_16x16x32_bf16 v[134:137], v[164:167], v[246:249], v[134:137]
	v_mfma_f32_16x16x32_bf16 v[138:141], v[170:173], v[218:221], v[138:141]
	v_mfma_f32_16x16x32_bf16 v[70:73], v[210:213], v[218:221], v[70:73]
	v_mfma_f32_16x16x32_bf16 v[74:77], v[170:173], v[226:229], v[74:77]
	v_mfma_f32_16x16x32_bf16 v[78:81], v[210:213], v[226:229], v[78:81]
	v_mfma_f32_16x16x32_bf16 v[82:85], v[170:173], v[234:237], v[82:85]
	v_mfma_f32_16x16x32_bf16 v[86:89], v[210:213], v[234:237], v[86:89]
	v_mfma_f32_16x16x32_bf16 v[90:93], v[170:173], v[242:245], v[90:93]
	v_mfma_f32_16x16x32_bf16 v[94:97], v[210:213], v[242:245], v[94:97]
	v_mfma_f32_16x16x32_bf16 v[138:141], v[174:177], v[222:225], v[138:141]
	v_mfma_f32_16x16x32_bf16 v[70:73], v[214:217], v[222:225], v[70:73]
	v_mfma_f32_16x16x32_bf16 v[74:77], v[174:177], v[230:233], v[74:77]
	v_mfma_f32_16x16x32_bf16 v[78:81], v[214:217], v[230:233], v[78:81]
	v_mfma_f32_16x16x32_bf16 v[82:85], v[174:177], v[238:241], v[82:85]
	v_mfma_f32_16x16x32_bf16 v[86:89], v[214:217], v[238:241], v[86:89]
	v_mfma_f32_16x16x32_bf16 v[90:93], v[174:177], v[246:249], v[90:93]
	v_mfma_f32_16x16x32_bf16 v[94:97], v[214:217], v[246:249], v[94:97]
	s_barrier
	s_mov_b64 s[26:27], 0x180
	s_mov_b32 m0, s8
	v_lshl_add_u64 v[126:127], v[12:13], 0, s[26:27]
	s_mov_b64 s[30:31], 0xb0180
	ds_read_b128 v[218:221], v36 offset:49152
	ds_read_b128 v[222:225], v36 offset:50176
	ds_read_b128 v[226:229], v36 offset:51200
	ds_read_b128 v[230:233], v36 offset:52224
	ds_read_b128 v[234:237], v36 offset:53248
	ds_read_b128 v[238:241], v36 offset:54272
	ds_read_b128 v[242:245], v36 offset:55296
	ds_read_b128 v[246:249], v36 offset:56320
	global_load_lds_dwordx4 v[126:127], off
	v_lshl_add_u64 v[126:127], v[18:19], 0, s[26:27]
	s_mov_b32 m0, s11
	v_lshl_add_u64 v[32:33], v[32:33], 0, s[30:31]
	global_load_lds_dwordx4 v[126:127], off
	v_lshl_add_u64 v[126:127], v[32:33], 0, v[162:163]
	s_mov_b32 m0, s14
	v_lshl_add_u64 v[32:33], v[32:33], 0, v[24:25]
	global_load_lds_dwordx4 v[126:127], off
	s_mov_b32 m0, s15
	s_nop 0
	global_load_lds_dwordx4 v[32:33], off
	v_lshl_add_u64 v[32:33], v[26:27], 0, s[26:27]
	s_mov_b32 m0, s9
	s_nop 0
	global_load_lds_dwordx4 v[32:33], off
	v_lshl_add_u64 v[32:33], v[28:29], 0, s[26:27]
	s_mov_b32 m0, s13
	s_nop 0
	global_load_lds_dwordx4 v[32:33], off
	s_waitcnt vmcnt(8)
	s_waitcnt lgkmcnt(0)
	s_barrier
	s_waitcnt lgkmcnt(0)
	v_mfma_f32_16x16x32_bf16 v[178:181], v[62:65], v[218:221], v[178:181]
	v_mfma_f32_16x16x32_bf16 v[182:185], v[154:157], v[218:221], v[182:185]
	v_mfma_f32_16x16x32_bf16 v[190:193], v[62:65], v[226:229], v[190:193]
	v_mfma_f32_16x16x32_bf16 v[198:201], v[154:157], v[226:229], v[198:201]
	v_mfma_f32_16x16x32_bf16 v[202:205], v[62:65], v[234:237], v[202:205]
	v_mfma_f32_16x16x32_bf16 v[206:209], v[154:157], v[234:237], v[206:209]
	v_mfma_f32_16x16x32_bf16 v[38:41], v[62:65], v[242:245], v[38:41]
	v_mfma_f32_16x16x32_bf16 v[42:45], v[154:157], v[242:245], v[42:45]
	v_mfma_f32_16x16x32_bf16 v[178:181], v[66:69], v[222:225], v[178:181]
	v_mfma_f32_16x16x32_bf16 v[182:185], v[164:167], v[222:225], v[182:185]
	v_mfma_f32_16x16x32_bf16 v[190:193], v[66:69], v[230:233], v[190:193]
	v_mfma_f32_16x16x32_bf16 v[198:201], v[164:167], v[230:233], v[198:201]
	v_mfma_f32_16x16x32_bf16 v[202:205], v[66:69], v[238:241], v[202:205]
	v_mfma_f32_16x16x32_bf16 v[206:209], v[164:167], v[238:241], v[206:209]
	v_mfma_f32_16x16x32_bf16 v[38:41], v[66:69], v[246:249], v[38:41]
	v_mfma_f32_16x16x32_bf16 v[42:45], v[164:167], v[246:249], v[42:45]
	v_mfma_f32_16x16x32_bf16 v[46:49], v[170:173], v[218:221], v[46:49]
	v_mfma_f32_16x16x32_bf16 v[50:53], v[210:213], v[218:221], v[50:53]
	v_mfma_f32_16x16x32_bf16 v[62:65], v[170:173], v[226:229], v[98:101]
	v_mfma_f32_16x16x32_bf16 v[66:69], v[210:213], v[226:229], v[142:145]
	v_mfma_f32_16x16x32_bf16 v[98:101], v[170:173], v[234:237], v[146:149]
	v_mfma_f32_16x16x32_bf16 v[142:145], v[210:213], v[234:237], v[150:153]
	v_mfma_f32_16x16x32_bf16 v[54:57], v[170:173], v[242:245], v[54:57]
	v_mfma_f32_16x16x32_bf16 v[58:61], v[210:213], v[242:245], v[58:61]
	v_mfma_f32_16x16x32_bf16 v[46:49], v[174:177], v[222:225], v[46:49]
	v_mfma_f32_16x16x32_bf16 v[50:53], v[214:217], v[222:225], v[50:53]
	v_mfma_f32_16x16x32_bf16 v[62:65], v[174:177], v[230:233], v[62:65]
	v_mfma_f32_16x16x32_bf16 v[66:69], v[214:217], v[230:233], v[66:69]
	v_mfma_f32_16x16x32_bf16 v[98:101], v[174:177], v[238:241], v[98:101]
	v_mfma_f32_16x16x32_bf16 v[142:145], v[214:217], v[238:241], v[142:145]
	v_mfma_f32_16x16x32_bf16 v[54:57], v[174:177], v[246:249], v[54:57]
	v_mfma_f32_16x16x32_bf16 v[58:61], v[214:217], v[246:249], v[58:61]
	s_barrier
	ds_read_b128 v[146:149], v186
	ds_read_b128 v[150:153], v186 offset:1024
	ds_read_b128 v[154:157], v186 offset:2048
	ds_read_b128 v[164:167], v186 offset:3072
	ds_read_b128 v[170:173], v187
	ds_read_b128 v[174:177], v187 offset:1024
	ds_read_b128 v[210:213], v187 offset:2048
	ds_read_b128 v[214:217], v187 offset:3072
	v_lshl_add_u64 v[30:31], v[30:31], 0, s[30:31]
	s_mov_b32 m0, s22
	v_lshl_add_u64 v[32:33], v[30:31], 0, v[162:163]
	ds_read_b128 v[218:221], v36
	ds_read_b128 v[222:225], v36 offset:1024
	ds_read_b128 v[226:229], v36 offset:2048
	ds_read_b128 v[230:233], v36 offset:3072
	ds_read_b128 v[234:237], v36 offset:4096
	ds_read_b128 v[238:241], v36 offset:5120
	ds_read_b128 v[242:245], v36 offset:6144
	ds_read_b128 v[246:249], v36 offset:7168
	global_load_lds_dwordx4 v[32:33], off
	v_lshl_add_u64 v[24:25], v[30:31], 0, v[24:25]
	s_mov_b32 m0, s18
	s_nop 0
	global_load_lds_dwordx4 v[24:25], off
	s_waitcnt vmcnt(8)
	s_waitcnt lgkmcnt(0)
	s_barrier
	s_waitcnt lgkmcnt(0)
	v_mfma_f32_16x16x32_bf16 v[30:33], v[146:149], v[218:221], v[102:105]
	v_mfma_f32_16x16x32_bf16 v[102:105], v[154:157], v[218:221], v[106:109]
	v_mfma_f32_16x16x32_bf16 v[106:109], v[146:149], v[226:229], v[110:113]
	v_mfma_f32_16x16x32_bf16 v[110:113], v[154:157], v[226:229], v[114:117]
	v_mfma_f32_16x16x32_bf16 v[114:117], v[146:149], v[234:237], v[118:121]
	v_mfma_f32_16x16x32_bf16 v[118:121], v[154:157], v[234:237], v[122:125]
	v_mfma_f32_16x16x32_bf16 v[122:125], v[146:149], v[242:245], v[130:133]
	v_mfma_f32_16x16x32_bf16 v[130:133], v[154:157], v[242:245], v[134:137]
	v_mfma_f32_16x16x32_bf16 v[30:33], v[150:153], v[222:225], v[30:33]
	v_mfma_f32_16x16x32_bf16 v[102:105], v[164:167], v[222:225], v[102:105]
	v_mfma_f32_16x16x32_bf16 v[106:109], v[150:153], v[230:233], v[106:109]
	v_mfma_f32_16x16x32_bf16 v[110:113], v[164:167], v[230:233], v[110:113]
	v_mfma_f32_16x16x32_bf16 v[114:117], v[150:153], v[238:241], v[114:117]
	v_mfma_f32_16x16x32_bf16 v[118:121], v[164:167], v[238:241], v[118:121]
	v_mfma_f32_16x16x32_bf16 v[122:125], v[150:153], v[246:249], v[122:125]
	v_mfma_f32_16x16x32_bf16 v[130:133], v[164:167], v[246:249], v[130:133]
	v_mfma_f32_16x16x32_bf16 v[134:137], v[170:173], v[218:221], v[138:141]
	v_mfma_f32_16x16x32_bf16 v[70:73], v[210:213], v[218:221], v[70:73]
	v_mfma_f32_16x16x32_bf16 v[74:77], v[170:173], v[226:229], v[74:77]
	v_mfma_f32_16x16x32_bf16 v[78:81], v[210:213], v[226:229], v[78:81]
	v_mfma_f32_16x16x32_bf16 v[82:85], v[170:173], v[234:237], v[82:85]
	v_mfma_f32_16x16x32_bf16 v[86:89], v[210:213], v[234:237], v[86:89]
	v_mfma_f32_16x16x32_bf16 v[90:93], v[170:173], v[242:245], v[90:93]
	v_mfma_f32_16x16x32_bf16 v[94:97], v[210:213], v[242:245], v[94:97]
	v_mfma_f32_16x16x32_bf16 v[134:137], v[174:177], v[222:225], v[134:137]
	v_mfma_f32_16x16x32_bf16 v[70:73], v[214:217], v[222:225], v[70:73]
	v_mfma_f32_16x16x32_bf16 v[74:77], v[174:177], v[230:233], v[74:77]
	v_mfma_f32_16x16x32_bf16 v[78:81], v[214:217], v[230:233], v[78:81]
	v_mfma_f32_16x16x32_bf16 v[82:85], v[174:177], v[238:241], v[82:85]
	v_mfma_f32_16x16x32_bf16 v[86:89], v[214:217], v[238:241], v[86:89]
	v_mfma_f32_16x16x32_bf16 v[90:93], v[174:177], v[246:249], v[90:93]
	v_mfma_f32_16x16x32_bf16 v[94:97], v[214:217], v[246:249], v[94:97]
	s_barrier
	s_mov_b32 m0, s19
	ds_read_b128 v[138:141], v36 offset:16384
	ds_read_b128 v[218:221], v36 offset:17408
	ds_read_b128 v[222:225], v36 offset:18432
	ds_read_b128 v[226:229], v36 offset:19456
	ds_read_b128 v[230:233], v36 offset:20480
	ds_read_b128 v[234:237], v36 offset:21504
	ds_read_b128 v[238:241], v36 offset:22528
	ds_read_b128 v[242:245], v36 offset:23552
	global_load_lds_dwordx4 v[12:13], off
	s_mov_b32 m0, s20
	s_nop 0
	global_load_lds_dwordx4 v[18:19], off
	s_mov_b32 m0, s17
	s_nop 0
	global_load_lds_dwordx4 v[20:21], off
	s_mov_b32 m0, s21
	s_nop 0
	global_load_lds_dwordx4 v[22:23], off
	s_mov_b32 m0, s10
	s_nop 0
	global_load_lds_dwordx4 v[26:27], off
	s_mov_b32 m0, s16
	s_nop 0
	global_load_lds_dwordx4 v[28:29], off
	s_waitcnt vmcnt(8)
	s_waitcnt lgkmcnt(0)
	s_barrier
	s_waitcnt lgkmcnt(0)
	v_mfma_f32_16x16x32_bf16 v[18:21], v[146:149], v[138:141], v[178:181]
	v_mfma_f32_16x16x32_bf16 v[22:25], v[154:157], v[138:141], v[182:185]
	v_mfma_f32_16x16x32_bf16 v[26:29], v[146:149], v[222:225], v[190:193]
	v_mfma_f32_16x16x32_bf16 v[178:181], v[154:157], v[222:225], v[198:201]
	v_mfma_f32_16x16x32_bf16 v[182:185], v[146:149], v[230:233], v[202:205]
	v_mfma_f32_16x16x32_bf16 v[190:193], v[154:157], v[230:233], v[206:209]
	v_mfma_f32_16x16x32_bf16 v[38:41], v[146:149], v[238:241], v[38:41]
	v_mfma_f32_16x16x32_bf16 v[42:45], v[154:157], v[238:241], v[42:45]
	v_mfma_f32_16x16x32_bf16 v[18:21], v[150:153], v[218:221], v[18:21]
	v_mfma_f32_16x16x32_bf16 v[22:25], v[164:167], v[218:221], v[22:25]
	v_mfma_f32_16x16x32_bf16 v[26:29], v[150:153], v[226:229], v[26:29]
	v_mfma_f32_16x16x32_bf16 v[178:181], v[164:167], v[226:229], v[178:181]
	v_mfma_f32_16x16x32_bf16 v[182:185], v[150:153], v[234:237], v[182:185]
	v_mfma_f32_16x16x32_bf16 v[190:193], v[164:167], v[234:237], v[190:193]
	v_mfma_f32_16x16x32_bf16 v[38:41], v[150:153], v[242:245], v[38:41]
	v_mfma_f32_16x16x32_bf16 v[42:45], v[164:167], v[242:245], v[42:45]
	v_mfma_f32_16x16x32_bf16 v[46:49], v[170:173], v[138:141], v[46:49]
	v_mfma_f32_16x16x32_bf16 v[50:53], v[210:213], v[138:141], v[50:53]
	v_mfma_f32_16x16x32_bf16 v[62:65], v[170:173], v[222:225], v[62:65]
	v_mfma_f32_16x16x32_bf16 v[66:69], v[210:213], v[222:225], v[66:69]
	v_mfma_f32_16x16x32_bf16 v[98:101], v[170:173], v[230:233], v[98:101]
	v_mfma_f32_16x16x32_bf16 v[138:141], v[210:213], v[230:233], v[142:145]
	v_mfma_f32_16x16x32_bf16 v[54:57], v[170:173], v[238:241], v[54:57]
	v_mfma_f32_16x16x32_bf16 v[58:61], v[210:213], v[238:241], v[58:61]
	v_mfma_f32_16x16x32_bf16 v[46:49], v[174:177], v[218:221], v[46:49]
	v_mfma_f32_16x16x32_bf16 v[50:53], v[214:217], v[218:221], v[50:53]
	v_mfma_f32_16x16x32_bf16 v[62:65], v[174:177], v[226:229], v[62:65]
	v_mfma_f32_16x16x32_bf16 v[66:69], v[214:217], v[226:229], v[66:69]
	v_mfma_f32_16x16x32_bf16 v[98:101], v[174:177], v[234:237], v[98:101]
	v_mfma_f32_16x16x32_bf16 v[138:141], v[214:217], v[234:237], v[138:141]
	v_mfma_f32_16x16x32_bf16 v[54:57], v[174:177], v[242:245], v[54:57]
	v_mfma_f32_16x16x32_bf16 v[58:61], v[214:217], v[242:245], v[58:61]
	s_barrier
	ds_read_b128 v[142:145], v250
	ds_read_b128 v[146:149], v250 offset:1024
	ds_read_b128 v[150:153], v250 offset:2048
	ds_read_b128 v[154:157], v250 offset:3072
	ds_read_b128 v[164:167], v37
	ds_read_b128 v[170:173], v37 offset:1024
	ds_read_b128 v[174:177], v37 offset:2048
	ds_read_b128 v[198:201], v37 offset:3072
	s_mov_b32 m0, s6
	ds_read_b128 v[202:205], v36 offset:32768
	ds_read_b128 v[206:209], v36 offset:33792
	ds_read_b128 v[210:213], v36 offset:34816
	ds_read_b128 v[214:217], v36 offset:35840
	ds_read_b128 v[218:221], v36 offset:36864
	ds_read_b128 v[222:225], v36 offset:37888
	ds_read_b128 v[226:229], v36 offset:38912
	ds_read_b128 v[230:233], v36 offset:39936
	global_load_lds_dwordx4 v[0:1], off
	s_mov_b32 m0, s7
	s_nop 0
	global_load_lds_dwordx4 v[2:3], off
	s_waitcnt vmcnt(8)
	s_waitcnt lgkmcnt(0)
	s_barrier
	s_waitcnt lgkmcnt(0)
	v_mfma_f32_16x16x32_bf16 v[0:3], v[142:145], v[202:205], v[30:33]
	v_mfma_f32_16x16x32_bf16 v[234:237], v[146:149], v[206:209], v[0:3]
	v_mfma_f32_16x16x32_bf16 v[0:3], v[150:153], v[202:205], v[102:105]
	v_mfma_f32_16x16x32_bf16 v[102:105], v[154:157], v[206:209], v[0:3]
	v_mfma_f32_16x16x32_bf16 v[0:3], v[142:145], v[210:213], v[106:109]
	v_mfma_f32_16x16x32_bf16 v[106:109], v[146:149], v[214:217], v[0:3]
	v_mfma_f32_16x16x32_bf16 v[0:3], v[150:153], v[210:213], v[110:113]
	v_mfma_f32_16x16x32_bf16 v[110:113], v[154:157], v[214:217], v[0:3]
	v_mfma_f32_16x16x32_bf16 v[0:3], v[142:145], v[218:221], v[114:117]
	v_mfma_f32_16x16x32_bf16 v[114:117], v[146:149], v[222:225], v[0:3]
	v_mfma_f32_16x16x32_bf16 v[0:3], v[150:153], v[218:221], v[118:121]
	v_mfma_f32_16x16x32_bf16 v[118:121], v[154:157], v[222:225], v[0:3]
	v_mfma_f32_16x16x32_bf16 v[0:3], v[142:145], v[226:229], v[122:125]
	v_mfma_f32_16x16x32_bf16 v[122:125], v[146:149], v[230:233], v[0:3]
	v_mfma_f32_16x16x32_bf16 v[0:3], v[150:153], v[226:229], v[130:133]
	v_mfma_f32_16x16x32_bf16 v[130:133], v[154:157], v[230:233], v[0:3]
	v_mfma_f32_16x16x32_bf16 v[0:3], v[164:167], v[202:205], v[134:137]
	v_mfma_f32_16x16x32_bf16 v[134:137], v[170:173], v[206:209], v[0:3]
	v_mfma_f32_16x16x32_bf16 v[0:3], v[174:177], v[202:205], v[70:73]
	v_mfma_f32_16x16x32_bf16 v[70:73], v[198:201], v[206:209], v[0:3]
	v_mfma_f32_16x16x32_bf16 v[0:3], v[164:167], v[210:213], v[74:77]
	v_mfma_f32_16x16x32_bf16 v[74:77], v[170:173], v[214:217], v[0:3]
	v_mfma_f32_16x16x32_bf16 v[0:3], v[174:177], v[210:213], v[78:81]
	v_mfma_f32_16x16x32_bf16 v[78:81], v[198:201], v[214:217], v[0:3]
	v_mfma_f32_16x16x32_bf16 v[0:3], v[164:167], v[218:221], v[82:85]
	v_mfma_f32_16x16x32_bf16 v[82:85], v[170:173], v[222:225], v[0:3]
	v_mfma_f32_16x16x32_bf16 v[0:3], v[174:177], v[218:221], v[86:89]
	v_mfma_f32_16x16x32_bf16 v[86:89], v[198:201], v[222:225], v[0:3]
	v_mfma_f32_16x16x32_bf16 v[0:3], v[164:167], v[226:229], v[90:93]
	v_mfma_f32_16x16x32_bf16 v[90:93], v[170:173], v[230:233], v[0:3]
	v_mfma_f32_16x16x32_bf16 v[0:3], v[174:177], v[226:229], v[94:97]
	v_mfma_f32_16x16x32_bf16 v[94:97], v[198:201], v[230:233], v[0:3]
	s_barrier
	s_mov_b32 m0, s8
	ds_read_b128 v[202:205], v36 offset:49152
	ds_read_b128 v[206:209], v36 offset:50176
	ds_read_b128 v[210:213], v36 offset:51200
	ds_read_b128 v[214:217], v36 offset:52224
	ds_read_b128 v[218:221], v36 offset:53248
	ds_read_b128 v[222:225], v36 offset:54272
	ds_read_b128 v[226:229], v36 offset:55296
	ds_read_b128 v[230:233], v36 offset:56320
	global_load_lds_dwordx4 v[6:7], off
	s_mov_b32 m0, s11
	s_nop 0
	global_load_lds_dwordx4 v[8:9], off
	s_mov_b32 m0, s14
	s_nop 0
	global_load_lds_dwordx4 v[14:15], off
	s_mov_b32 m0, s15
	s_nop 0
	global_load_lds_dwordx4 v[16:17], off
	s_mov_b32 m0, s9
	s_nop 0
	global_load_lds_dwordx4 v[4:5], off
	s_mov_b32 m0, s13
	s_nop 0
	global_load_lds_dwordx4 v[10:11], off
	s_waitcnt vmcnt(8)
	s_waitcnt lgkmcnt(0)
	s_barrier
	s_waitcnt lgkmcnt(0)
	v_mfma_f32_16x16x32_bf16 v[0:3], v[142:145], v[202:205], v[18:21]
	v_mfma_f32_16x16x32_bf16 v[238:241], v[146:149], v[206:209], v[0:3]
	v_mfma_f32_16x16x32_bf16 v[0:3], v[150:153], v[202:205], v[22:25]
	v_mfma_f32_16x16x32_bf16 v[242:245], v[154:157], v[206:209], v[0:3]
	v_mfma_f32_16x16x32_bf16 v[0:3], v[142:145], v[210:213], v[26:29]
	v_mfma_f32_16x16x32_bf16 v[246:249], v[146:149], v[214:217], v[0:3]
	v_mfma_f32_16x16x32_bf16 v[0:3], v[150:153], v[210:213], v[178:181]
	v_mfma_f32_16x16x32_bf16 v[178:181], v[154:157], v[214:217], v[0:3]
	v_mfma_f32_16x16x32_bf16 v[0:3], v[142:145], v[218:221], v[182:185]
	v_mfma_f32_16x16x32_bf16 v[28:31], v[146:149], v[222:225], v[0:3]
	v_mfma_f32_16x16x32_bf16 v[0:3], v[150:153], v[218:221], v[190:193]
	v_mfma_f32_16x16x32_bf16 v[16:19], v[154:157], v[222:225], v[0:3]
	v_mfma_f32_16x16x32_bf16 v[0:3], v[142:145], v[226:229], v[38:41]
	v_mfma_f32_16x16x32_bf16 v[12:15], v[146:149], v[230:233], v[0:3]
	v_mfma_f32_16x16x32_bf16 v[0:3], v[150:153], v[226:229], v[42:45]
	v_mfma_f32_16x16x32_bf16 v[0:3], v[154:157], v[230:233], v[0:3]
	v_mfma_f32_16x16x32_bf16 v[4:7], v[164:167], v[202:205], v[46:49]
	v_mfma_f32_16x16x32_bf16 v[36:39], v[170:173], v[206:209], v[4:7]
	v_mfma_f32_16x16x32_bf16 v[4:7], v[174:177], v[202:205], v[50:53]
	v_mfma_f32_16x16x32_bf16 v[40:43], v[198:201], v[206:209], v[4:7]
	v_mfma_f32_16x16x32_bf16 v[4:7], v[164:167], v[210:213], v[62:65]
	v_mfma_f32_16x16x32_bf16 v[44:47], v[170:173], v[214:217], v[4:7]
	v_mfma_f32_16x16x32_bf16 v[4:7], v[174:177], v[210:213], v[66:69]
	v_mfma_f32_16x16x32_bf16 v[48:51], v[198:201], v[214:217], v[4:7]
	v_mfma_f32_16x16x32_bf16 v[4:7], v[164:167], v[218:221], v[98:101]
	v_mfma_f32_16x16x32_bf16 v[24:27], v[170:173], v[222:225], v[4:7]
	v_mfma_f32_16x16x32_bf16 v[4:7], v[174:177], v[218:221], v[138:141]
	v_mfma_f32_16x16x32_bf16 v[20:23], v[198:201], v[222:225], v[4:7]
	v_mfma_f32_16x16x32_bf16 v[4:7], v[164:167], v[226:229], v[54:57]
	v_mfma_f32_16x16x32_bf16 v[8:11], v[170:173], v[230:233], v[4:7]
	v_mfma_f32_16x16x32_bf16 v[4:7], v[174:177], v[226:229], v[58:61]
	v_mfma_f32_16x16x32_bf16 v[4:7], v[198:201], v[230:233], v[4:7]
	s_barrier
	v_readlane_b32 vcc_lo, v253, 0
	s_mul_i32 vcc_hi, vcc_lo, 0x1746
	s_lshr_b32 vcc_hi, vcc_hi, 16
	s_mul_i32 s100, vcc_hi, 11
	s_sub_u32 vcc_lo, vcc_lo, s100
	s_mul_i32 s100, vcc_hi, 0x300000
	s_lshr_b32 s101, vcc_lo, 2
	s_lshl_b32 s101, s101, 20
	s_add_u32 s100, s100, s101
	s_and_b32 s101, vcc_lo, 3
	s_lshl_b32 s101, s101, 10
	s_add_u32 s100, s100, s101
	s_lshl_b32 s101, s3, 20
	s_sub_u32 s100, s100, s101
	s_lshl_b32 s101, s2, 10
	s_sub_u32 s100, s100, s101
	s_add_u32 s100, s100, 0x70e2000
	s_load_dwordx2 vcc, s[40:41], 0xf0
	s_waitcnt lgkmcnt(0)
	s_add_u32 vcc_lo, vcc_lo, s100
	s_addc_u32 vcc_hi, vcc_hi, 0
	v_mov_b32_e32 v128, vcc_lo
	v_mov_b32_e32 v129, vcc_hi
	v_lshl_add_u32 v34, s3, 8, v34
	v_lshl_or_b32 v32, s2, 8, v35
	v_or_b32_e32 v32, s5, v32
	v_ashrrev_i32_e32 v35, 31, v34
	v_ashrrev_i32_e32 v33, 31, v32
	v_lshlrev_b64 v[52:53], 12, v[34:35]
	v_lshl_add_u64 v[52:53], v[128:129], 0, v[52:53]
	v_lshlrev_b64 v[54:55], 2, v[32:33]
	v_lshl_add_u64 v[32:33], v[52:53], 0, v[54:55]
	v_pk_mul_f32 v[62:63], v[236:237], 0.5 op_sel_hi:[1,0]
	v_pk_mul_f32 v[60:61], v[234:235], 0.5 op_sel_hi:[1,0]
	global_store_dwordx4 v[32:33], v[60:63], off sc0 sc1
	v_pk_mul_f32 v[66:67], v[104:105], 0.5 op_sel_hi:[1,0]
	v_pk_mul_f32 v[64:65], v[102:103], 0.5 op_sel_hi:[1,0]
	global_store_dwordx4 v[32:33], v[64:67], off offset:64 sc0 sc1
	v_pk_mul_f32 v[62:63], v[136:137], 0.5 op_sel_hi:[1,0]
	v_pk_mul_f32 v[60:61], v[134:135], 0.5 op_sel_hi:[1,0]
	global_store_dwordx4 v[32:33], v[60:63], off offset:512 sc0 sc1
	v_pk_mul_f32 v[66:67], v[72:73], 0.5 op_sel_hi:[1,0]
	v_pk_mul_f32 v[64:65], v[70:71], 0.5 op_sel_hi:[1,0]
	global_store_dwordx4 v[32:33], v[64:67], off offset:576 sc0 sc1
	v_or_b32_e32 v52, 16, v34
	v_ashrrev_i32_e32 v53, 31, v52
	v_lshlrev_b64 v[52:53], 12, v[52:53]
	v_lshl_add_u64 v[52:53], v[128:129], 0, v[52:53]
	v_lshl_add_u64 v[52:53], v[52:53], 0, v[54:55]
	v_pk_mul_f32 v[60:61], v[106:107], 0.5 op_sel_hi:[1,0]
	v_pk_mul_f32 v[62:63], v[108:109], 0.5 op_sel_hi:[1,0]
	global_store_dwordx4 v[52:53], v[60:63], off sc0 sc1
	v_pk_mul_f32 v[64:65], v[110:111], 0.5 op_sel_hi:[1,0]
	v_pk_mul_f32 v[66:67], v[112:113], 0.5 op_sel_hi:[1,0]
	global_store_dwordx4 v[52:53], v[64:67], off offset:64 sc0 sc1
	v_pk_mul_f32 v[60:61], v[74:75], 0.5 op_sel_hi:[1,0]
	v_pk_mul_f32 v[62:63], v[76:77], 0.5 op_sel_hi:[1,0]
	global_store_dwordx4 v[52:53], v[60:63], off offset:512 sc0 sc1
	v_pk_mul_f32 v[64:65], v[78:79], 0.5 op_sel_hi:[1,0]
	v_pk_mul_f32 v[66:67], v[80:81], 0.5 op_sel_hi:[1,0]
	global_store_dwordx4 v[52:53], v[64:67], off offset:576 sc0 sc1
	v_or_b32_e32 v52, 32, v34
	v_ashrrev_i32_e32 v53, 31, v52
	v_lshlrev_b64 v[52:53], 12, v[52:53]
	v_lshl_add_u64 v[52:53], v[128:129], 0, v[52:53]
	v_lshl_add_u64 v[52:53], v[52:53], 0, v[54:55]
	v_pk_mul_f32 v[60:61], v[114:115], 0.5 op_sel_hi:[1,0]
	v_or_b32_e32 v34, 48, v34
	v_pk_mul_f32 v[62:63], v[116:117], 0.5 op_sel_hi:[1,0]
	global_store_dwordx4 v[52:53], v[60:63], off sc0 sc1
	v_pk_mul_f32 v[64:65], v[118:119], 0.5 op_sel_hi:[1,0]
	v_ashrrev_i32_e32 v35, 31, v34
	v_pk_mul_f32 v[66:67], v[120:121], 0.5 op_sel_hi:[1,0]
	global_store_dwordx4 v[52:53], v[64:67], off offset:64 sc0 sc1
	v_pk_mul_f32 v[60:61], v[82:83], 0.5 op_sel_hi:[1,0]
	v_lshlrev_b64 v[34:35], 12, v[34:35]
	v_pk_mul_f32 v[62:63], v[84:85], 0.5 op_sel_hi:[1,0]
	global_store_dwordx4 v[52:53], v[60:63], off offset:512 sc0 sc1
	v_pk_mul_f32 v[64:65], v[86:87], 0.5 op_sel_hi:[1,0]
	v_lshl_add_u64 v[34:35], v[128:129], 0, v[34:35]
	v_pk_mul_f32 v[66:67], v[88:89], 0.5 op_sel_hi:[1,0]
	global_store_dwordx4 v[52:53], v[64:67], off offset:576 sc0 sc1
	v_lshl_add_u64 v[34:35], v[34:35], 0, v[54:55]
	v_pk_mul_f32 v[60:61], v[122:123], 0.5 op_sel_hi:[1,0]
	v_pk_mul_f32 v[62:63], v[124:125], 0.5 op_sel_hi:[1,0]
	global_store_dwordx4 v[34:35], v[60:63], off sc0 sc1
	v_pk_mul_f32 v[64:65], v[130:131], 0.5 op_sel_hi:[1,0]
	v_pk_mul_f32 v[66:67], v[132:133], 0.5 op_sel_hi:[1,0]
	global_store_dwordx4 v[34:35], v[64:67], off offset:64 sc0 sc1
	v_pk_mul_f32 v[60:61], v[90:91], 0.5 op_sel_hi:[1,0]
	v_pk_mul_f32 v[62:63], v[92:93], 0.5 op_sel_hi:[1,0]
	global_store_dwordx4 v[34:35], v[60:63], off offset:512 sc0 sc1
	v_pk_mul_f32 v[64:65], v[94:95], 0.5 op_sel_hi:[1,0]
	v_add_co_u32_e32 v56, vcc, s23, v32
	v_pk_mul_f32 v[66:67], v[96:97], 0.5 op_sel_hi:[1,0]
	global_store_dwordx4 v[34:35], v[64:67], off offset:576 sc0 sc1
	s_mov_b64 s[2:3], 0x80000
	v_pk_mul_f32 v[60:61], v[238:239], 0.5 op_sel_hi:[1,0]
	v_addc_co_u32_e32 v57, vcc, 0, v33, vcc
	v_lshl_add_u64 v[34:35], v[32:33], 0, s[2:3]
	v_pk_mul_f32 v[62:63], v[240:241], 0.5 op_sel_hi:[1,0]
	global_store_dwordx4 v[34:35], v[60:63], off sc0 sc1
	v_pk_mul_f32 v[64:65], v[242:243], 0.5 op_sel_hi:[1,0]
	v_pk_mul_f32 v[66:67], v[244:245], 0.5 op_sel_hi:[1,0]
	global_store_dwordx4 v[34:35], v[64:67], off offset:64 sc0 sc1
	v_pk_mul_f32 v[38:39], v[38:39], 0.5 op_sel_hi:[1,0]
	v_pk_mul_f32 v[36:37], v[36:37], 0.5 op_sel_hi:[1,0]
	global_store_dwordx4 v[34:35], v[36:39], off offset:512 sc0 sc1
	v_pk_mul_f32 v[64:65], v[40:41], 0.5 op_sel_hi:[1,0]
	v_add_co_u32_e32 v40, vcc, s24, v32
	v_pk_mul_f32 v[66:67], v[42:43], 0.5 op_sel_hi:[1,0]
	global_store_dwordx4 v[34:35], v[64:67], off offset:576 sc0 sc1
	s_mov_b64 s[2:3], 0x90000
	v_pk_mul_f32 v[60:61], v[246:247], 0.5 op_sel_hi:[1,0]
	v_addc_co_u32_e32 v41, vcc, 0, v33, vcc
	v_lshl_add_u64 v[34:35], v[32:33], 0, s[2:3]
	v_pk_mul_f32 v[62:63], v[248:249], 0.5 op_sel_hi:[1,0]
	global_store_dwordx4 v[34:35], v[60:63], off sc0 sc1
	v_pk_mul_f32 v[64:65], v[178:179], 0.5 op_sel_hi:[1,0]
	v_pk_mul_f32 v[66:67], v[180:181], 0.5 op_sel_hi:[1,0]
	global_store_dwordx4 v[34:35], v[64:67], off offset:64 sc0 sc1
	v_pk_mul_f32 v[60:61], v[44:45], 0.5 op_sel_hi:[1,0]
	v_pk_mul_f32 v[62:63], v[46:47], 0.5 op_sel_hi:[1,0]
	global_store_dwordx4 v[34:35], v[60:63], off offset:512 sc0 sc1
	v_pk_mul_f32 v[64:65], v[48:49], 0.5 op_sel_hi:[1,0]
	s_mov_b64 s[2:3], 0xa0000
	v_pk_mul_f32 v[66:67], v[50:51], 0.5 op_sel_hi:[1,0]
	global_store_dwordx4 v[34:35], v[64:67], off offset:576 sc0 sc1
	v_lshl_add_u64 v[34:35], v[32:33], 0, s[2:3]
	s_mov_b32 s2, 0xa0000
	v_add_co_u32_e32 v36, vcc, s2, v32
	v_pk_mul_f32 v[28:29], v[28:29], 0.5 op_sel_hi:[1,0]
	s_nop 0
	v_addc_co_u32_e32 v37, vcc, 0, v33, vcc
	v_pk_mul_f32 v[30:31], v[30:31], 0.5 op_sel_hi:[1,0]
	global_store_dwordx4 v[34:35], v[28:31], off sc0 sc1
	v_pk_mul_f32 v[18:19], v[18:19], 0.5 op_sel_hi:[1,0]
	v_pk_mul_f32 v[16:17], v[16:17], 0.5 op_sel_hi:[1,0]
	global_store_dwordx4 v[34:35], v[16:19], off offset:64 sc0 sc1
	v_pk_mul_f32 v[60:61], v[24:25], 0.5 op_sel_hi:[1,0]
	v_pk_mul_f32 v[62:63], v[26:27], 0.5 op_sel_hi:[1,0]
	global_store_dwordx4 v[34:35], v[60:63], off offset:512 sc0 sc1
	v_pk_mul_f32 v[64:65], v[20:21], 0.5 op_sel_hi:[1,0]
	s_mov_b32 s2, 0xb0000
	v_pk_mul_f32 v[66:67], v[22:23], 0.5 op_sel_hi:[1,0]
	global_store_dwordx4 v[34:35], v[64:67], off offset:576 sc0 sc1
	v_add_co_u32_e32 v18, vcc, s2, v32
	v_pk_mul_f32 v[12:13], v[12:13], 0.5 op_sel_hi:[1,0]
	s_nop 0
	v_addc_co_u32_e32 v19, vcc, 0, v33, vcc
	v_lshl_add_u64 v[16:17], v[32:33], 0, s[28:29]
	v_pk_mul_f32 v[14:15], v[14:15], 0.5 op_sel_hi:[1,0]
	global_store_dwordx4 v[16:17], v[12:15], off sc0 sc1
	v_pk_mul_f32 v[2:3], v[2:3], 0.5 op_sel_hi:[1,0]
	v_pk_mul_f32 v[0:1], v[0:1], 0.5 op_sel_hi:[1,0]
	global_store_dwordx4 v[16:17], v[0:3], off offset:64 sc0 sc1
	v_pk_mul_f32 v[60:61], v[8:9], 0.5 op_sel_hi:[1,0]
	v_pk_mul_f32 v[62:63], v[10:11], 0.5 op_sel_hi:[1,0]
	global_store_dwordx4 v[16:17], v[60:63], off offset:512 sc0 sc1
	v_pk_mul_f32 v[64:65], v[4:5], 0.5 op_sel_hi:[1,0]
	v_pk_mul_f32 v[66:67], v[6:7], 0.5 op_sel_hi:[1,0]
	global_store_dwordx4 v[16:17], v[64:67], off offset:576 sc0 sc1
	s_waitcnt vmcnt(0)
	s_cmpk_gt_u32 s4, 0xff
	s_cbranch_scc1 .LBB0_1884
	s_barrier
